# inverse priority flips: s_setprio 1 during the K-loop load segments, 0 during the MFMA segments
# baseline (speedup 1.0000x reference)
;     __device__ __forceinline__ Pre prefetch(const Unit& u, int tid) const { return prenorm_load(stats, u.pn * BM, sW + (size_t)(u.pn >> 4) * SW_ROWS + u.pm * BM, tid); }
;     __device__ __forceinline__ Pre prefetch(const Unit& u, int tid) const { return prenorm_load(stats, u.pm * BM, sW + (size_t)(u.pm >> 4) * SW_ROWS + u.pn * BM, tid); }
;     __device__ __forceinline__ Pre prefetch(const Unit& u, int tid) const { return prenorm_load(stats, u.pm * BM, sW + (size_t)(u.pm >> 4) * SW_ROWS + u.pn * BM, tid); }
; #define PG8_STAGE(bufoff, gbase, voff) do { _Pragma("unroll") for (int _i = 0; _i < 2; ++_i) \
;         __builtin_amdgcn_global_load_lds((const unsigned*)((const char*)(gbase) + (voff)[_i]), (LAS unsigned*)(lds + (bufoff) + ldsw + _i * 8192), 16, 0, 0); } while (0)
; #define PG8_LDA(dst, b, h) do { _Pragma("unroll") for (int m = 0; m < 4; ++m) _Pragma("unroll") for (int k = 0; k < 2; ++k) dst[m][k] = *(const LAS bf16x8*)(lds + PG8_SA(b, h) + aoff + m * 2048 + k * 1024); } while (0)
; #define PG8_WAIT_V(n) asm volatile("s_waitcnt vmcnt(" #n ")" ::: "memory")
; #define PG8_BAR __builtin_amdgcn_s_barrier()
; template <class Epi, class Sched>
; __device__ __forceinline__ void gemm_phase(LAS unsigned char* lds, const Gemm g, const Sched& S, const Epi& E, const int tid) {
;     ...
;         const char* nA = has_next ? (const char*)g.A + (size_t)nxt.pm * tstep : cA; const char* nB = has_next ? (const char*)g.Bt + (size_t)nxt.pn * tstep : cB;
;         const typename Epi::Pre pre = E.prefetch(cur, tid);
;         for (int t = 0; t < nt; t += 2) {
;             const bool last = (t == nt - 2);
;             const char* a1 = cA + (size_t)(t + 1) * kstep;
;             const char* a2 = last ? nA : cA + (size_t)(t + 2) * kstep; const char* b2 = last ? nB : cB + (size_t)(t + 2) * kstep;
;             const char* a3 = a2 + kstep; const char* b3 = b2 + kstep;
;             PG8_LDB(B0, 0, 0); PG8_LDB(B1, 0, 1); PG8_SCHED; PG8_LDA(At, 0, 0); PG8_STAGE(PG8_SA(1, 1), a1 + hstep, voffA);
;             PG8_WAIT_V(8); PG8_WAIT_L(0); PG8_BAR; PG8_MMA(0, 0, At, B0); PG8_MMA(0, 1, At, B1); PG8_BAR; PG8_SCHED;
;             PG8_LDA(At, 0, 1); PG8_STAGE(PG8_SB(0, 0), b2, voffB); PG8_STAGE(PG8_SB(0, 1), b2 + hstep, voffB); PG8_STAGE(PG8_SA(0, 0), a2, voffA);
;             PG8_WAIT_V(8); PG8_WAIT_L(0); PG8_BAR; PG8_MMA(1, 0, At, B0); PG8_MMA(1, 1, At, B1); PG8_BAR; PG8_SCHED;
.LBB0_167:
	s_or_b64 exec, exec, s[22:23]
	s_ashr_i32 s55, s54, 31
	s_lshl_b64 s[22:23], s[54:55], 19
	s_add_u32 s22, s46, s22
	s_addc_u32 s23, s47, s23
	s_and_b64 s[38:39], s[6:7], exec
	s_cselect_b32 s55, s23, s65
	s_cselect_b32 s56, s22, s64
	s_ashr_i32 s63, s62, 31
	s_lshl_b64 s[38:39], s[62:63], 19
	s_add_u32 s38, s12, s38
	s_addc_u32 s39, s73, s39
	s_and_b64 s[58:59], s[6:7], exec
	s_cselect_b32 s57, s39, s67
	s_cselect_b32 s58, s38, s66
	s_add_u32 s64, s64, 0x40080
	s_addc_u32 s65, s65, 0
	s_add_u32 s59, s66, 0x100
	s_addc_u32 s60, s67, 0
	s_mov_b32 s61, -2
	s_add_u32 s63, s64, 0xfffc0080
	s_addc_u32 s66, s65, -1
	s_add_i32 s78, 0, 0x10000
	s_cmp_eq_u32 s61, 12
	s_cselect_b32 s71, s55, s66
	s_cselect_b32 s70, s56, s63
	v_add_u32_e32 v145, s78, v166
	s_cselect_b32 s67, s57, s60
	s_cselect_b32 s66, s58, s59
	s_add_i32 s63, 0, 0x14000
	ds_read_b128 v[146:149], v145
	ds_read_b128 v[150:153], v145 offset:1024
	ds_read_b128 v[154:157], v145 offset:2048
	ds_read_b128 v[158:161], v145 offset:3072
	v_add_u32_e32 v145, s63, v166
	ds_read_b128 v[172:175], v145
	ds_read_b128 v[176:179], v145 offset:1024
	ds_read_b128 v[180:183], v145 offset:2048
	ds_read_b128 v[184:187], v145 offset:3072
	v_lshl_add_u64 v[162:163], s[64:65], 0, v[140:141]
	s_add_i32 m0, s75, 0xc000
	ds_read_b128 v[188:191], v171
	ds_read_b128 v[198:201], v171 offset:1024
	ds_read_b128 v[202:205], v171 offset:2048
	ds_read_b128 v[206:209], v171 offset:3072
	ds_read_b128 v[210:213], v171 offset:4096
	ds_read_b128 v[214:217], v171 offset:5120
	ds_read_b128 v[218:221], v171 offset:6144
	ds_read_b128 v[230:233], v171 offset:7168
	global_load_lds_dwordx4 v[162:163], off
	v_lshl_add_u64 v[162:163], s[64:65], 0, v[142:143]
	s_add_i32 m0, s75, 0xe000
	s_nop 0
	global_load_lds_dwordx4 v[162:163], off
	s_waitcnt vmcnt(8)
	s_waitcnt lgkmcnt(0)
	s_setprio 0
	s_barrier
	s_waitcnt lgkmcnt(0)
	v_mfma_f32_16x16x32_bf16 v[128:131], v[146:149], v[188:191], 0
	v_mfma_f32_16x16x32_bf16 v[124:127], v[154:157], v[188:191], 0
	v_mfma_f32_16x16x32_bf16 v[104:107], v[154:157], v[202:205], 0
	v_mfma_f32_16x16x32_bf16 v[108:111], v[146:149], v[202:205], 0
	v_mfma_f32_16x16x32_bf16 v[92:95], v[146:149], v[210:213], 0
	v_mfma_f32_16x16x32_bf16 v[88:91], v[154:157], v[210:213], 0
	v_mfma_f32_16x16x32_bf16 v[72:75], v[154:157], v[218:221], 0
	v_mfma_f32_16x16x32_bf16 v[76:79], v[146:149], v[218:221], 0
	v_mfma_f32_16x16x32_bf16 v[128:131], v[150:153], v[198:201], v[128:131]
	v_mfma_f32_16x16x32_bf16 v[124:127], v[158:161], v[198:201], v[124:127]
	v_mfma_f32_16x16x32_bf16 v[104:107], v[158:161], v[206:209], v[104:107]
	v_mfma_f32_16x16x32_bf16 v[108:111], v[150:153], v[206:209], v[108:111]
	v_mfma_f32_16x16x32_bf16 v[92:95], v[150:153], v[214:217], v[92:95]
	v_mfma_f32_16x16x32_bf16 v[88:91], v[158:161], v[214:217], v[88:91]
	v_mfma_f32_16x16x32_bf16 v[72:75], v[158:161], v[230:233], v[72:75]
	v_mfma_f32_16x16x32_bf16 v[76:79], v[150:153], v[230:233], v[76:79]
	v_mfma_f32_16x16x32_bf16 v[120:123], v[172:175], v[188:191], 0
	v_mfma_f32_16x16x32_bf16 v[116:119], v[180:183], v[188:191], 0
	v_mfma_f32_16x16x32_bf16 v[96:99], v[180:183], v[202:205], 0
	v_mfma_f32_16x16x32_bf16 v[100:103], v[172:175], v[202:205], 0
	v_mfma_f32_16x16x32_bf16 v[84:87], v[172:175], v[210:213], 0
	v_mfma_f32_16x16x32_bf16 v[80:83], v[180:183], v[210:213], 0
	v_mfma_f32_16x16x32_bf16 v[64:67], v[180:183], v[218:221], 0
	v_mfma_f32_16x16x32_bf16 v[68:71], v[172:175], v[218:221], 0
	v_mfma_f32_16x16x32_bf16 v[120:123], v[176:179], v[198:201], v[120:123]
	v_mfma_f32_16x16x32_bf16 v[116:119], v[184:187], v[198:201], v[116:119]
	v_mfma_f32_16x16x32_bf16 v[96:99], v[184:187], v[206:209], v[96:99]
	v_mfma_f32_16x16x32_bf16 v[100:103], v[176:179], v[206:209], v[100:103]
	v_mfma_f32_16x16x32_bf16 v[84:87], v[176:179], v[214:217], v[84:87]
	v_mfma_f32_16x16x32_bf16 v[80:83], v[184:187], v[214:217], v[80:83]
	v_mfma_f32_16x16x32_bf16 v[64:67], v[184:187], v[230:233], v[64:67]
	v_mfma_f32_16x16x32_bf16 v[68:71], v[176:179], v[230:233], v[68:71]
	s_barrier
	s_setprio 1
	s_add_i32 s78, s78, s74
	v_lshl_add_u64 v[162:163], s[66:67], 0, v[192:193]
	s_mov_b32 m0, s78
	ds_read_b128 v[188:191], v171 offset:16384
	ds_read_b128 v[198:201], v171 offset:17408
	ds_read_b128 v[202:205], v171 offset:18432
	ds_read_b128 v[206:209], v171 offset:19456
	ds_read_b128 v[210:213], v171 offset:20480
	ds_read_b128 v[214:217], v171 offset:21504
	ds_read_b128 v[218:221], v171 offset:22528
	ds_read_b128 v[230:233], v171 offset:23552
	global_load_lds_dwordx4 v[162:163], off
	s_add_i32 m0, s78, 0x2000
	s_add_u32 s78, s66, 0x40000
	v_lshl_add_u64 v[234:235], s[66:67], 0, v[134:135]
	s_addc_u32 s79, s67, 0
	s_add_i32 s63, s63, s74
	global_load_lds_dwordx4 v[234:235], off
	v_lshl_add_u64 v[236:237], s[78:79], 0, v[192:193]
	s_mov_b32 m0, s63
	v_lshl_add_u64 v[238:239], s[70:71], 0, v[136:137]
	global_load_lds_dwordx4 v[236:237], off
	v_lshl_add_u64 v[236:237], s[78:79], 0, v[134:135]
	s_add_i32 m0, s63, 0x2000
	s_nop 0
	global_load_lds_dwordx4 v[236:237], off
	v_lshl_add_u64 v[236:237], s[70:71], 0, v[138:139]
	s_mov_b32 m0, s75
	s_nop 0
	global_load_lds_dwordx4 v[236:237], off
	s_mov_b32 m0, s81
	s_nop 0
	global_load_lds_dwordx4 v[238:239], off
	s_waitcnt vmcnt(8)
	s_waitcnt lgkmcnt(0)
	s_setprio 0
	s_barrier
; #define PG8_STAGE(bufoff, gbase, voff) do { _Pragma("unroll") for (int _i = 0; _i < 2; ++_i) \
;         __builtin_amdgcn_global_load_lds((const unsigned*)((const char*)(gbase) + (voff)[_i]), (LAS unsigned*)(lds + (bufoff) + ldsw + _i * 8192), 16, 0, 0); } while (0)
; #define PG8_LDA(dst, b, h) do { _Pragma("unroll") for (int m = 0; m < 4; ++m) _Pragma("unroll") for (int k = 0; k < 2; ++k) dst[m][k] = *(const LAS bf16x8*)(lds + PG8_SA(b, h) + aoff + m * 2048 + k * 1024); } while (0)
; #define PG8_LDB(dst, b, h) do { _Pragma("unroll") for (int n = 0; n < 2; ++n) _Pragma("unroll") for (int k = 0; k < 2; ++k) dst[n][k] = *(const LAS bf16x8*)(lds + PG8_SB(b, h) + boff + n * 2048 + k * 1024); } while (0)
; #define PG8_MMA(ai, bj, At, Bt) do { __builtin_amdgcn_s_setprio(1); _Pragma("unroll") for (int m = 0; m < 4; ++m) _Pragma("unroll") for (int n = 0; n < 2; ++n) _Pragma("unroll") for (int k = 0; k < 2; ++k) \
;         acc[ai][bj][m][n] = __builtin_amdgcn_mfma_f32_16x16x32_bf16(Bt[n][k], At[m][k], acc[ai][bj][m][n], 0, 0, 0); __builtin_amdgcn_s_setprio(0); } while (0)
; #define PG8_WAIT_V(n) asm volatile("s_waitcnt vmcnt(" #n ")" ::: "memory")
; #define PG8_WAIT_L(n) asm volatile("s_waitcnt lgkmcnt(" #n ")" ::: "memory")
; #define PG8_BAR __builtin_amdgcn_s_barrier()
; #define PG8_SCHED __builtin_amdgcn_sched_barrier(0)
; template <class Epi, class Sched>
; __device__ __forceinline__ void gemm_phase(LAS unsigned char* lds, const Gemm g, const Sched& S, const Epi& E, const int tid) {
;     ...
;             PG8_WAIT_V(8); PG8_WAIT_L(0); PG8_BAR; PG8_MMA(1, 0, At, B0); PG8_MMA(1, 1, At, B1); PG8_BAR; PG8_SCHED;
;             PG8_LDB(B0, 1, 0); PG8_LDB(B1, 1, 1); PG8_SCHED; PG8_LDA(At, 1, 0); PG8_STAGE(PG8_SA(0, 1), a2 + hstep, voffA);
;             PG8_WAIT_V(8); PG8_WAIT_L(0); PG8_BAR; PG8_MMA(0, 0, At, B0); PG8_MMA(0, 1, At, B1); PG8_BAR; PG8_SCHED;
	s_waitcnt lgkmcnt(0)
	v_mfma_f32_16x16x32_bf16 v[60:63], v[146:149], v[188:191], 0
	v_mfma_f32_16x16x32_bf16 v[56:59], v[154:157], v[188:191], 0
	v_mfma_f32_16x16x32_bf16 v[40:43], v[154:157], v[202:205], 0
	v_mfma_f32_16x16x32_bf16 v[44:47], v[146:149], v[202:205], 0
	v_mfma_f32_16x16x32_bf16 v[28:31], v[146:149], v[210:213], 0
	v_mfma_f32_16x16x32_bf16 v[24:27], v[154:157], v[210:213], 0
	v_mfma_f32_16x16x32_bf16 v[8:11], v[154:157], v[218:221], 0
	v_mfma_f32_16x16x32_bf16 v[12:15], v[146:149], v[218:221], 0
	v_mfma_f32_16x16x32_bf16 v[60:63], v[150:153], v[198:201], v[60:63]
	v_mfma_f32_16x16x32_bf16 v[56:59], v[158:161], v[198:201], v[56:59]
	v_mfma_f32_16x16x32_bf16 v[40:43], v[158:161], v[206:209], v[40:43]
	v_mfma_f32_16x16x32_bf16 v[44:47], v[150:153], v[206:209], v[44:47]
	v_mfma_f32_16x16x32_bf16 v[28:31], v[150:153], v[214:217], v[28:31]
	v_mfma_f32_16x16x32_bf16 v[24:27], v[158:161], v[214:217], v[24:27]
	v_mfma_f32_16x16x32_bf16 v[8:11], v[158:161], v[230:233], v[8:11]
	v_mfma_f32_16x16x32_bf16 v[12:15], v[150:153], v[230:233], v[12:15]
	v_mfma_f32_16x16x32_bf16 v[52:55], v[172:175], v[188:191], 0
	v_mfma_f32_16x16x32_bf16 v[48:51], v[180:183], v[188:191], 0
	v_mfma_f32_16x16x32_bf16 v[32:35], v[180:183], v[202:205], 0
	v_mfma_f32_16x16x32_bf16 v[36:39], v[172:175], v[202:205], 0
	v_mfma_f32_16x16x32_bf16 v[20:23], v[172:175], v[210:213], 0
	v_mfma_f32_16x16x32_bf16 v[16:19], v[180:183], v[210:213], 0
	v_mfma_f32_16x16x32_bf16 v[0:3], v[180:183], v[218:221], 0
	v_mfma_f32_16x16x32_bf16 v[4:7], v[172:175], v[218:221], 0
	v_mfma_f32_16x16x32_bf16 v[52:55], v[176:179], v[198:201], v[52:55]
	v_mfma_f32_16x16x32_bf16 v[48:51], v[184:187], v[198:201], v[48:51]
	v_mfma_f32_16x16x32_bf16 v[32:35], v[184:187], v[206:209], v[32:35]
	v_mfma_f32_16x16x32_bf16 v[36:39], v[176:179], v[206:209], v[36:39]
	v_mfma_f32_16x16x32_bf16 v[20:23], v[176:179], v[214:217], v[20:23]
	v_mfma_f32_16x16x32_bf16 v[16:19], v[184:187], v[214:217], v[16:19]
	v_mfma_f32_16x16x32_bf16 v[0:3], v[184:187], v[230:233], v[0:3]
	v_mfma_f32_16x16x32_bf16 v[4:7], v[176:179], v[230:233], v[4:7]
	s_barrier
	s_setprio 1
	s_add_i32 s63, 0, 0x18000
	v_add_u32_e32 v145, s63, v166
	s_add_i32 s78, 0, 0x1c000
	ds_read_b128 v[146:149], v145
	ds_read_b128 v[150:153], v145 offset:1024
	ds_read_b128 v[154:157], v145 offset:2048
	ds_read_b128 v[158:161], v145 offset:3072
	v_add_u32_e32 v145, s78, v166
	ds_read_b128 v[172:175], v145
	ds_read_b128 v[176:179], v145 offset:1024
	ds_read_b128 v[180:183], v145 offset:2048
	ds_read_b128 v[184:187], v145 offset:3072
	s_add_u32 s70, s70, 0x40000
	s_addc_u32 s71, s71, 0
	s_mov_b32 m0, s82
	v_lshl_add_u64 v[240:241], s[70:71], 0, v[138:139]
	ds_read_b128 v[188:191], v171 offset:32768
	ds_read_b128 v[198:201], v171 offset:33792
	ds_read_b128 v[202:205], v171 offset:34816
	ds_read_b128 v[206:209], v171 offset:35840
	ds_read_b128 v[210:213], v171 offset:36864
	ds_read_b128 v[214:217], v171 offset:37888
	ds_read_b128 v[218:221], v171 offset:38912
	ds_read_b128 v[230:233], v171 offset:39936
	global_load_lds_dwordx4 v[240:241], off
	v_lshl_add_u64 v[240:241], s[70:71], 0, v[136:137]
	s_mov_b32 m0, s83
	s_nop 0
	global_load_lds_dwordx4 v[240:241], off
	s_waitcnt vmcnt(8)
	s_waitcnt lgkmcnt(0)
	s_setprio 0
	s_barrier
	s_waitcnt lgkmcnt(0)
	v_mfma_f32_16x16x32_bf16 v[128:131], v[146:149], v[188:191], v[128:131]
	v_mfma_f32_16x16x32_bf16 v[124:127], v[154:157], v[188:191], v[124:127]
	v_mfma_f32_16x16x32_bf16 v[104:107], v[154:157], v[202:205], v[104:107]
	v_mfma_f32_16x16x32_bf16 v[108:111], v[146:149], v[202:205], v[108:111]
	v_mfma_f32_16x16x32_bf16 v[92:95], v[146:149], v[210:213], v[92:95]
	v_mfma_f32_16x16x32_bf16 v[88:91], v[154:157], v[210:213], v[88:91]
	v_mfma_f32_16x16x32_bf16 v[72:75], v[154:157], v[218:221], v[72:75]
	v_mfma_f32_16x16x32_bf16 v[76:79], v[146:149], v[218:221], v[76:79]
	v_mfma_f32_16x16x32_bf16 v[128:131], v[150:153], v[198:201], v[128:131]
	v_mfma_f32_16x16x32_bf16 v[124:127], v[158:161], v[198:201], v[124:127]
	v_mfma_f32_16x16x32_bf16 v[104:107], v[158:161], v[206:209], v[104:107]
	v_mfma_f32_16x16x32_bf16 v[108:111], v[150:153], v[206:209], v[108:111]
	v_mfma_f32_16x16x32_bf16 v[92:95], v[150:153], v[214:217], v[92:95]
	v_mfma_f32_16x16x32_bf16 v[88:91], v[158:161], v[214:217], v[88:91]
	v_mfma_f32_16x16x32_bf16 v[72:75], v[158:161], v[230:233], v[72:75]
	v_mfma_f32_16x16x32_bf16 v[76:79], v[150:153], v[230:233], v[76:79]
	v_mfma_f32_16x16x32_bf16 v[120:123], v[172:175], v[188:191], v[120:123]
	v_mfma_f32_16x16x32_bf16 v[116:119], v[180:183], v[188:191], v[116:119]
	v_mfma_f32_16x16x32_bf16 v[96:99], v[180:183], v[202:205], v[96:99]
	v_mfma_f32_16x16x32_bf16 v[100:103], v[172:175], v[202:205], v[100:103]
	v_mfma_f32_16x16x32_bf16 v[84:87], v[172:175], v[210:213], v[84:87]
	v_mfma_f32_16x16x32_bf16 v[80:83], v[180:183], v[210:213], v[80:83]
	v_mfma_f32_16x16x32_bf16 v[64:67], v[180:183], v[218:221], v[64:67]
	v_mfma_f32_16x16x32_bf16 v[68:71], v[172:175], v[218:221], v[68:71]
	v_mfma_f32_16x16x32_bf16 v[120:123], v[176:179], v[198:201], v[120:123]
	v_mfma_f32_16x16x32_bf16 v[116:119], v[184:187], v[198:201], v[116:119]
	v_mfma_f32_16x16x32_bf16 v[96:99], v[184:187], v[206:209], v[96:99]
	v_mfma_f32_16x16x32_bf16 v[100:103], v[176:179], v[206:209], v[100:103]
	v_mfma_f32_16x16x32_bf16 v[84:87], v[176:179], v[214:217], v[84:87]
	v_mfma_f32_16x16x32_bf16 v[80:83], v[184:187], v[214:217], v[80:83]
	v_mfma_f32_16x16x32_bf16 v[64:67], v[184:187], v[230:233], v[64:67]
	v_mfma_f32_16x16x32_bf16 v[68:71], v[176:179], v[230:233], v[68:71]
	s_barrier
; #define PG8_STAGE(bufoff, gbase, voff) do { _Pragma("unroll") for (int _i = 0; _i < 2; ++_i) \
;         __builtin_amdgcn_global_load_lds((const unsigned*)((const char*)(gbase) + (voff)[_i]), (LAS unsigned*)(lds + (bufoff) + ldsw + _i * 8192), 16, 0, 0); } while (0)
; #define PG8_LDA(dst, b, h) do { _Pragma("unroll") for (int m = 0; m < 4; ++m) _Pragma("unroll") for (int k = 0; k < 2; ++k) dst[m][k] = *(const LAS bf16x8*)(lds + PG8_SA(b, h) + aoff + m * 2048 + k * 1024); } while (0)
; #define PG8_LDB(dst, b, h) do { _Pragma("unroll") for (int n = 0; n < 2; ++n) _Pragma("unroll") for (int k = 0; k < 2; ++k) dst[n][k] = *(const LAS bf16x8*)(lds + PG8_SB(b, h) + boff + n * 2048 + k * 1024); } while (0)
; #define PG8_WAIT_V(n) asm volatile("s_waitcnt vmcnt(" #n ")" ::: "memory")
; #define PG8_BAR __builtin_amdgcn_s_barrier()
; template <class Epi, class Sched>
; __device__ __forceinline__ void gemm_phase(LAS unsigned char* lds, const Gemm g, const Sched& S, const Epi& E, const int tid) {
;     ...
;         for (int t = 0; t < nt; t += 2) {
;             const bool last = (t == nt - 2);
;             const char* a1 = cA + (size_t)(t + 1) * kstep;
;             const char* a2 = last ? nA : cA + (size_t)(t + 2) * kstep; const char* b2 = last ? nB : cB + (size_t)(t + 2) * kstep;
;             const char* a3 = a2 + kstep; const char* b3 = b2 + kstep;
;             PG8_LDB(B0, 0, 0); PG8_LDB(B1, 0, 1); PG8_SCHED; PG8_LDA(At, 0, 0); PG8_STAGE(PG8_SA(1, 1), a1 + hstep, voffA);
;             PG8_WAIT_V(8); PG8_WAIT_L(0); PG8_BAR; PG8_MMA(0, 0, At, B0); PG8_MMA(0, 1, At, B1); PG8_BAR; PG8_SCHED;
;             PG8_LDA(At, 0, 1); PG8_STAGE(PG8_SB(0, 0), b2, voffB); PG8_STAGE(PG8_SB(0, 1), b2 + hstep, voffB); PG8_STAGE(PG8_SA(0, 0), a2, voffA);
;             PG8_WAIT_V(8); PG8_WAIT_L(0); PG8_BAR; PG8_MMA(1, 0, At, B0); PG8_MMA(1, 1, At, B1); PG8_BAR; PG8_SCHED;
;             PG8_LDB(B0, 1, 0); PG8_LDB(B1, 1, 1); PG8_SCHED; PG8_LDA(At, 1, 0); PG8_STAGE(PG8_SA(0, 1), a2 + hstep, voffA);
;             PG8_WAIT_V(8); PG8_WAIT_L(0); PG8_BAR; PG8_MMA(0, 0, At, B0); PG8_MMA(0, 1, At, B1); PG8_BAR; PG8_SCHED;
;             PG8_LDA(At, 1, 1); PG8_STAGE(PG8_SB(1, 0), b3, voffB); PG8_STAGE(PG8_SB(1, 1), b3 + hstep, voffB); PG8_STAGE(PG8_SA(1, 0), a3, voffA);
;             PG8_WAIT_V(8); PG8_WAIT_L(0); PG8_BAR; PG8_MMA(1, 0, At, B0); PG8_MMA(1, 1, At, B1); PG8_BAR; PG8_SCHED;
	s_setprio 1
	s_add_i32 s63, s63, s74
	v_lshl_add_u64 v[162:163], v[162:163], 0, s[68:69]
	s_mov_b32 m0, s63
	ds_read_b128 v[188:191], v171 offset:49152
	ds_read_b128 v[198:201], v171 offset:50176
	ds_read_b128 v[202:205], v171 offset:51200
	ds_read_b128 v[206:209], v171 offset:52224
	ds_read_b128 v[210:213], v171 offset:53248
	ds_read_b128 v[214:217], v171 offset:54272
	ds_read_b128 v[218:221], v171 offset:55296
	ds_read_b128 v[230:233], v171 offset:56320
	global_load_lds_dwordx4 v[162:163], off
	s_add_i32 m0, s63, 0x2000
	s_add_u32 s66, s66, 0x40080
	v_lshl_add_u64 v[162:163], v[234:235], 0, s[68:69]
	s_addc_u32 s67, s67, 0
	s_add_i32 s63, s78, s74
	global_load_lds_dwordx4 v[162:163], off
	v_lshl_add_u64 v[162:163], s[66:67], 0, v[192:193]
	s_mov_b32 m0, s63
	s_nop 0
	global_load_lds_dwordx4 v[162:163], off
	v_lshl_add_u64 v[162:163], s[66:67], 0, v[134:135]
	s_add_i32 m0, s63, 0x2000
	s_nop 0
	global_load_lds_dwordx4 v[162:163], off
	v_lshl_add_u64 v[162:163], v[236:237], 0, s[68:69]
	s_mov_b32 m0, s93
	s_nop 0
	global_load_lds_dwordx4 v[162:163], off
	v_lshl_add_u64 v[162:163], v[238:239], 0, s[68:69]
	s_mov_b32 m0, s94
	s_nop 0
	global_load_lds_dwordx4 v[162:163], off
	s_waitcnt vmcnt(8)
	s_waitcnt lgkmcnt(0)
	s_setprio 0
	s_barrier
	s_waitcnt lgkmcnt(0)
	v_mfma_f32_16x16x32_bf16 v[60:63], v[146:149], v[188:191], v[60:63]
	v_mfma_f32_16x16x32_bf16 v[56:59], v[154:157], v[188:191], v[56:59]
	v_mfma_f32_16x16x32_bf16 v[40:43], v[154:157], v[202:205], v[40:43]
	v_mfma_f32_16x16x32_bf16 v[44:47], v[146:149], v[202:205], v[44:47]
	v_mfma_f32_16x16x32_bf16 v[28:31], v[146:149], v[210:213], v[28:31]
	v_mfma_f32_16x16x32_bf16 v[24:27], v[154:157], v[210:213], v[24:27]
	v_mfma_f32_16x16x32_bf16 v[8:11], v[154:157], v[218:221], v[8:11]
	v_mfma_f32_16x16x32_bf16 v[12:15], v[146:149], v[218:221], v[12:15]
	v_mfma_f32_16x16x32_bf16 v[60:63], v[150:153], v[198:201], v[60:63]
	v_mfma_f32_16x16x32_bf16 v[56:59], v[158:161], v[198:201], v[56:59]
	v_mfma_f32_16x16x32_bf16 v[40:43], v[158:161], v[206:209], v[40:43]
	v_mfma_f32_16x16x32_bf16 v[44:47], v[150:153], v[206:209], v[44:47]
	v_mfma_f32_16x16x32_bf16 v[28:31], v[150:153], v[214:217], v[28:31]
	v_mfma_f32_16x16x32_bf16 v[24:27], v[158:161], v[214:217], v[24:27]
	v_mfma_f32_16x16x32_bf16 v[8:11], v[158:161], v[230:233], v[8:11]
	v_mfma_f32_16x16x32_bf16 v[12:15], v[150:153], v[230:233], v[12:15]
	v_mfma_f32_16x16x32_bf16 v[52:55], v[172:175], v[188:191], v[52:55]
	v_mfma_f32_16x16x32_bf16 v[48:51], v[180:183], v[188:191], v[48:51]
	v_mfma_f32_16x16x32_bf16 v[32:35], v[180:183], v[202:205], v[32:35]
	v_mfma_f32_16x16x32_bf16 v[36:39], v[172:175], v[202:205], v[36:39]
	v_mfma_f32_16x16x32_bf16 v[20:23], v[172:175], v[210:213], v[20:23]
	v_mfma_f32_16x16x32_bf16 v[16:19], v[180:183], v[210:213], v[16:19]
	v_mfma_f32_16x16x32_bf16 v[0:3], v[180:183], v[218:221], v[0:3]
	v_mfma_f32_16x16x32_bf16 v[4:7], v[172:175], v[218:221], v[4:7]
	v_mfma_f32_16x16x32_bf16 v[52:55], v[176:179], v[198:201], v[52:55]
	v_mfma_f32_16x16x32_bf16 v[48:51], v[184:187], v[198:201], v[48:51]
	v_mfma_f32_16x16x32_bf16 v[32:35], v[184:187], v[206:209], v[32:35]
	v_mfma_f32_16x16x32_bf16 v[36:39], v[176:179], v[206:209], v[36:39]
	v_mfma_f32_16x16x32_bf16 v[20:23], v[176:179], v[214:217], v[20:23]
	v_mfma_f32_16x16x32_bf16 v[16:19], v[184:187], v[214:217], v[16:19]
	v_mfma_f32_16x16x32_bf16 v[0:3], v[184:187], v[230:233], v[0:3]
	v_mfma_f32_16x16x32_bf16 v[4:7], v[176:179], v[230:233], v[4:7]
	s_barrier
	s_setprio 1
	s_add_i32 s61, s61, 2
	s_add_u32 s64, s64, 0x100
	s_addc_u32 s65, s65, 0
	s_add_u32 s59, s59, 0x100
	s_addc_u32 s60, s60, 0
	s_cmp_gt_u32 s61, 13
.LBB0_168:
	s_add_u32 s63, s64, 0xfffc0080
	s_addc_u32 s66, s65, -1
	s_add_i32 s78, 0, 0x10000
	s_cmp_eq_u32 s61, 12
	s_cselect_b32 s71, s55, s66
	s_cselect_b32 s70, s56, s63
	v_add_u32_e32 v145, s78, v166
	s_cselect_b32 s67, s57, s60
	s_cselect_b32 s66, s58, s59
	s_add_i32 s63, 0, 0x14000
	ds_read_b128 v[146:149], v145
	ds_read_b128 v[150:153], v145 offset:1024
	ds_read_b128 v[154:157], v145 offset:2048
	ds_read_b128 v[158:161], v145 offset:3072
	v_add_u32_e32 v145, s63, v166
	ds_read_b128 v[172:175], v145
	ds_read_b128 v[176:179], v145 offset:1024
	ds_read_b128 v[180:183], v145 offset:2048
	ds_read_b128 v[184:187], v145 offset:3072
	v_lshl_add_u64 v[162:163], s[64:65], 0, v[140:141]
	s_add_i32 m0, s75, 0xc000
	ds_read_b128 v[188:191], v171
	ds_read_b128 v[198:201], v171 offset:1024
	ds_read_b128 v[202:205], v171 offset:2048
	ds_read_b128 v[206:209], v171 offset:3072
	ds_read_b128 v[210:213], v171 offset:4096
	ds_read_b128 v[214:217], v171 offset:5120
	ds_read_b128 v[218:221], v171 offset:6144
	ds_read_b128 v[230:233], v171 offset:7168
	global_load_lds_dwordx4 v[162:163], off
	v_lshl_add_u64 v[162:163], s[64:65], 0, v[142:143]
	s_add_i32 m0, s75, 0xe000
	s_nop 0
	global_load_lds_dwordx4 v[162:163], off
	s_waitcnt vmcnt(8)
	s_waitcnt lgkmcnt(0)
	s_setprio 0
	s_barrier
; #define PG8_STAGE(bufoff, gbase, voff) do { _Pragma("unroll") for (int _i = 0; _i < 2; ++_i) \
;         __builtin_amdgcn_global_load_lds((const unsigned*)((const char*)(gbase) + (voff)[_i]), (LAS unsigned*)(lds + (bufoff) + ldsw + _i * 8192), 16, 0, 0); } while (0)
; #define PG8_LDA(dst, b, h) do { _Pragma("unroll") for (int m = 0; m < 4; ++m) _Pragma("unroll") for (int k = 0; k < 2; ++k) dst[m][k] = *(const LAS bf16x8*)(lds + PG8_SA(b, h) + aoff + m * 2048 + k * 1024); } while (0)
; #define PG8_MMA(ai, bj, At, Bt) do { __builtin_amdgcn_s_setprio(1); _Pragma("unroll") for (int m = 0; m < 4; ++m) _Pragma("unroll") for (int n = 0; n < 2; ++n) _Pragma("unroll") for (int k = 0; k < 2; ++k) \
;         acc[ai][bj][m][n] = __builtin_amdgcn_mfma_f32_16x16x32_bf16(Bt[n][k], At[m][k], acc[ai][bj][m][n], 0, 0, 0); __builtin_amdgcn_s_setprio(0); } while (0)
; #define PG8_WAIT_V(n) asm volatile("s_waitcnt vmcnt(" #n ")" ::: "memory")
; #define PG8_WAIT_L(n) asm volatile("s_waitcnt lgkmcnt(" #n ")" ::: "memory")
; #define PG8_BAR __builtin_amdgcn_s_barrier()
; #define PG8_SCHED __builtin_amdgcn_sched_barrier(0)
; template <class Epi, class Sched>
; __device__ __forceinline__ void gemm_phase(LAS unsigned char* lds, const Gemm g, const Sched& S, const Epi& E, const int tid) {
;     ...
;             PG8_WAIT_V(8); PG8_WAIT_L(0); PG8_BAR; PG8_MMA(0, 0, At, B0); PG8_MMA(0, 1, At, B1); PG8_BAR; PG8_SCHED;
;             PG8_LDA(At, 0, 1); PG8_STAGE(PG8_SB(0, 0), b2, voffB); PG8_STAGE(PG8_SB(0, 1), b2 + hstep, voffB); PG8_STAGE(PG8_SA(0, 0), a2, voffA);
;             PG8_WAIT_V(8); PG8_WAIT_L(0); PG8_BAR; PG8_MMA(1, 0, At, B0); PG8_MMA(1, 1, At, B1); PG8_BAR; PG8_SCHED;
	s_waitcnt lgkmcnt(0)
	v_mfma_f32_16x16x32_bf16 v[128:131], v[146:149], v[188:191], v[128:131]
	v_mfma_f32_16x16x32_bf16 v[124:127], v[154:157], v[188:191], v[124:127]
	v_mfma_f32_16x16x32_bf16 v[104:107], v[154:157], v[202:205], v[104:107]
	v_mfma_f32_16x16x32_bf16 v[108:111], v[146:149], v[202:205], v[108:111]
	v_mfma_f32_16x16x32_bf16 v[92:95], v[146:149], v[210:213], v[92:95]
	v_mfma_f32_16x16x32_bf16 v[88:91], v[154:157], v[210:213], v[88:91]
	v_mfma_f32_16x16x32_bf16 v[72:75], v[154:157], v[218:221], v[72:75]
	v_mfma_f32_16x16x32_bf16 v[76:79], v[146:149], v[218:221], v[76:79]
	v_mfma_f32_16x16x32_bf16 v[128:131], v[150:153], v[198:201], v[128:131]
	v_mfma_f32_16x16x32_bf16 v[124:127], v[158:161], v[198:201], v[124:127]
	v_mfma_f32_16x16x32_bf16 v[104:107], v[158:161], v[206:209], v[104:107]
	v_mfma_f32_16x16x32_bf16 v[108:111], v[150:153], v[206:209], v[108:111]
	v_mfma_f32_16x16x32_bf16 v[92:95], v[150:153], v[214:217], v[92:95]
	v_mfma_f32_16x16x32_bf16 v[88:91], v[158:161], v[214:217], v[88:91]
	v_mfma_f32_16x16x32_bf16 v[72:75], v[158:161], v[230:233], v[72:75]
	v_mfma_f32_16x16x32_bf16 v[76:79], v[150:153], v[230:233], v[76:79]
	v_mfma_f32_16x16x32_bf16 v[120:123], v[172:175], v[188:191], v[120:123]
	v_mfma_f32_16x16x32_bf16 v[116:119], v[180:183], v[188:191], v[116:119]
	v_mfma_f32_16x16x32_bf16 v[96:99], v[180:183], v[202:205], v[96:99]
	v_mfma_f32_16x16x32_bf16 v[100:103], v[172:175], v[202:205], v[100:103]
	v_mfma_f32_16x16x32_bf16 v[84:87], v[172:175], v[210:213], v[84:87]
	v_mfma_f32_16x16x32_bf16 v[80:83], v[180:183], v[210:213], v[80:83]
	v_mfma_f32_16x16x32_bf16 v[64:67], v[180:183], v[218:221], v[64:67]
	v_mfma_f32_16x16x32_bf16 v[68:71], v[172:175], v[218:221], v[68:71]
	v_mfma_f32_16x16x32_bf16 v[120:123], v[176:179], v[198:201], v[120:123]
	v_mfma_f32_16x16x32_bf16 v[116:119], v[184:187], v[198:201], v[116:119]
	v_mfma_f32_16x16x32_bf16 v[96:99], v[184:187], v[206:209], v[96:99]
	v_mfma_f32_16x16x32_bf16 v[100:103], v[176:179], v[206:209], v[100:103]
	v_mfma_f32_16x16x32_bf16 v[84:87], v[176:179], v[214:217], v[84:87]
	v_mfma_f32_16x16x32_bf16 v[80:83], v[184:187], v[214:217], v[80:83]
	v_mfma_f32_16x16x32_bf16 v[64:67], v[184:187], v[230:233], v[64:67]
	v_mfma_f32_16x16x32_bf16 v[68:71], v[176:179], v[230:233], v[68:71]
	s_barrier
	s_setprio 1
	s_add_i32 s78, s78, s74
	v_lshl_add_u64 v[162:163], s[66:67], 0, v[192:193]
	s_mov_b32 m0, s78
	ds_read_b128 v[188:191], v171 offset:16384
	ds_read_b128 v[198:201], v171 offset:17408
	ds_read_b128 v[202:205], v171 offset:18432
	ds_read_b128 v[206:209], v171 offset:19456
	ds_read_b128 v[210:213], v171 offset:20480
	ds_read_b128 v[214:217], v171 offset:21504
	ds_read_b128 v[218:221], v171 offset:22528
	ds_read_b128 v[230:233], v171 offset:23552
	global_load_lds_dwordx4 v[162:163], off
	s_add_i32 m0, s78, 0x2000
	s_add_u32 s78, s66, 0x40000
	v_lshl_add_u64 v[234:235], s[66:67], 0, v[134:135]
	s_addc_u32 s79, s67, 0
	s_add_i32 s63, s63, s74
	global_load_lds_dwordx4 v[234:235], off
	v_lshl_add_u64 v[236:237], s[78:79], 0, v[192:193]
	s_mov_b32 m0, s63
	v_lshl_add_u64 v[238:239], s[70:71], 0, v[136:137]
	global_load_lds_dwordx4 v[236:237], off
	v_lshl_add_u64 v[236:237], s[78:79], 0, v[134:135]
	s_add_i32 m0, s63, 0x2000
	s_nop 0
	global_load_lds_dwordx4 v[236:237], off
	v_lshl_add_u64 v[236:237], s[70:71], 0, v[138:139]
	s_mov_b32 m0, s75
	s_nop 0
	global_load_lds_dwordx4 v[236:237], off
	s_mov_b32 m0, s81
	s_nop 0
	global_load_lds_dwordx4 v[238:239], off
	s_waitcnt vmcnt(8)
	s_waitcnt lgkmcnt(0)
	s_setprio 0
	s_barrier
	s_waitcnt lgkmcnt(0)
	v_mfma_f32_16x16x32_bf16 v[60:63], v[146:149], v[188:191], v[60:63]
	v_mfma_f32_16x16x32_bf16 v[56:59], v[154:157], v[188:191], v[56:59]
	v_mfma_f32_16x16x32_bf16 v[40:43], v[154:157], v[202:205], v[40:43]
	v_mfma_f32_16x16x32_bf16 v[44:47], v[146:149], v[202:205], v[44:47]
	v_mfma_f32_16x16x32_bf16 v[28:31], v[146:149], v[210:213], v[28:31]
	v_mfma_f32_16x16x32_bf16 v[24:27], v[154:157], v[210:213], v[24:27]
	v_mfma_f32_16x16x32_bf16 v[8:11], v[154:157], v[218:221], v[8:11]
	v_mfma_f32_16x16x32_bf16 v[12:15], v[146:149], v[218:221], v[12:15]
	v_mfma_f32_16x16x32_bf16 v[60:63], v[150:153], v[198:201], v[60:63]
	v_mfma_f32_16x16x32_bf16 v[56:59], v[158:161], v[198:201], v[56:59]
	v_mfma_f32_16x16x32_bf16 v[40:43], v[158:161], v[206:209], v[40:43]
	v_mfma_f32_16x16x32_bf16 v[44:47], v[150:153], v[206:209], v[44:47]
	v_mfma_f32_16x16x32_bf16 v[28:31], v[150:153], v[214:217], v[28:31]
	v_mfma_f32_16x16x32_bf16 v[24:27], v[158:161], v[214:217], v[24:27]
	v_mfma_f32_16x16x32_bf16 v[8:11], v[158:161], v[230:233], v[8:11]
	v_mfma_f32_16x16x32_bf16 v[12:15], v[150:153], v[230:233], v[12:15]
	v_mfma_f32_16x16x32_bf16 v[52:55], v[172:175], v[188:191], v[52:55]
	v_mfma_f32_16x16x32_bf16 v[48:51], v[180:183], v[188:191], v[48:51]
	v_mfma_f32_16x16x32_bf16 v[32:35], v[180:183], v[202:205], v[32:35]
	v_mfma_f32_16x16x32_bf16 v[36:39], v[172:175], v[202:205], v[36:39]
	v_mfma_f32_16x16x32_bf16 v[20:23], v[172:175], v[210:213], v[20:23]
	v_mfma_f32_16x16x32_bf16 v[16:19], v[180:183], v[210:213], v[16:19]
	v_mfma_f32_16x16x32_bf16 v[0:3], v[180:183], v[218:221], v[0:3]
	v_mfma_f32_16x16x32_bf16 v[4:7], v[172:175], v[218:221], v[4:7]
	v_mfma_f32_16x16x32_bf16 v[52:55], v[176:179], v[198:201], v[52:55]
	v_mfma_f32_16x16x32_bf16 v[48:51], v[184:187], v[198:201], v[48:51]
	v_mfma_f32_16x16x32_bf16 v[32:35], v[184:187], v[206:209], v[32:35]
	v_mfma_f32_16x16x32_bf16 v[36:39], v[176:179], v[206:209], v[36:39]
	v_mfma_f32_16x16x32_bf16 v[20:23], v[176:179], v[214:217], v[20:23]
	v_mfma_f32_16x16x32_bf16 v[16:19], v[184:187], v[214:217], v[16:19]
	v_mfma_f32_16x16x32_bf16 v[0:3], v[184:187], v[230:233], v[0:3]
	v_mfma_f32_16x16x32_bf16 v[4:7], v[176:179], v[230:233], v[4:7]
	s_barrier
; #define PG8_STAGE(bufoff, gbase, voff) do { _Pragma("unroll") for (int _i = 0; _i < 2; ++_i) \
;         __builtin_amdgcn_global_load_lds((const unsigned*)((const char*)(gbase) + (voff)[_i]), (LAS unsigned*)(lds + (bufoff) + ldsw + _i * 8192), 16, 0, 0); } while (0)
; #define PG8_LDA(dst, b, h) do { _Pragma("unroll") for (int m = 0; m < 4; ++m) _Pragma("unroll") for (int k = 0; k < 2; ++k) dst[m][k] = *(const LAS bf16x8*)(lds + PG8_SA(b, h) + aoff + m * 2048 + k * 1024); } while (0)
; #define PG8_LDB(dst, b, h) do { _Pragma("unroll") for (int n = 0; n < 2; ++n) _Pragma("unroll") for (int k = 0; k < 2; ++k) dst[n][k] = *(const LAS bf16x8*)(lds + PG8_SB(b, h) + boff + n * 2048 + k * 1024); } while (0)
; #define PG8_MMA(ai, bj, At, Bt) do { __builtin_amdgcn_s_setprio(1); _Pragma("unroll") for (int m = 0; m < 4; ++m) _Pragma("unroll") for (int n = 0; n < 2; ++n) _Pragma("unroll") for (int k = 0; k < 2; ++k) \
;         acc[ai][bj][m][n] = __builtin_amdgcn_mfma_f32_16x16x32_bf16(Bt[n][k], At[m][k], acc[ai][bj][m][n], 0, 0, 0); __builtin_amdgcn_s_setprio(0); } while (0)
; #define PG8_WAIT_V(n) asm volatile("s_waitcnt vmcnt(" #n ")" ::: "memory")
; #define PG8_WAIT_L(n) asm volatile("s_waitcnt lgkmcnt(" #n ")" ::: "memory")
; #define PG8_BAR __builtin_amdgcn_s_barrier()
; #define PG8_SCHED __builtin_amdgcn_sched_barrier(0)
; template <class Epi, class Sched>
; __device__ __forceinline__ void gemm_phase(LAS unsigned char* lds, const Gemm g, const Sched& S, const Epi& E, const int tid) {
;     ...
;             PG8_LDB(B0, 1, 0); PG8_LDB(B1, 1, 1); PG8_SCHED; PG8_LDA(At, 1, 0); PG8_STAGE(PG8_SA(0, 1), a2 + hstep, voffA);
;             PG8_WAIT_V(8); PG8_WAIT_L(0); PG8_BAR; PG8_MMA(0, 0, At, B0); PG8_MMA(0, 1, At, B1); PG8_BAR; PG8_SCHED;
	s_setprio 1
	s_add_i32 s63, 0, 0x18000
	v_add_u32_e32 v145, s63, v166
	s_add_i32 s78, 0, 0x1c000
	ds_read_b128 v[146:149], v145
	ds_read_b128 v[150:153], v145 offset:1024
	ds_read_b128 v[154:157], v145 offset:2048
	ds_read_b128 v[158:161], v145 offset:3072
	v_add_u32_e32 v145, s78, v166
	ds_read_b128 v[172:175], v145
	ds_read_b128 v[176:179], v145 offset:1024
	ds_read_b128 v[180:183], v145 offset:2048
	ds_read_b128 v[184:187], v145 offset:3072
	s_add_u32 s70, s70, 0x40000
	s_addc_u32 s71, s71, 0
	s_mov_b32 m0, s82
	v_lshl_add_u64 v[240:241], s[70:71], 0, v[138:139]
	ds_read_b128 v[188:191], v171 offset:32768
	ds_read_b128 v[198:201], v171 offset:33792
	ds_read_b128 v[202:205], v171 offset:34816
	ds_read_b128 v[206:209], v171 offset:35840
	ds_read_b128 v[210:213], v171 offset:36864
	ds_read_b128 v[214:217], v171 offset:37888
	ds_read_b128 v[218:221], v171 offset:38912
	ds_read_b128 v[230:233], v171 offset:39936
	global_load_lds_dwordx4 v[240:241], off
	v_lshl_add_u64 v[240:241], s[70:71], 0, v[136:137]
	s_mov_b32 m0, s83
	s_nop 0
	global_load_lds_dwordx4 v[240:241], off
	s_waitcnt vmcnt(8)
	s_waitcnt lgkmcnt(0)
	s_setprio 0
	s_barrier
	s_waitcnt lgkmcnt(0)
	v_mfma_f32_16x16x32_bf16 v[128:131], v[146:149], v[188:191], v[128:131]
	v_mfma_f32_16x16x32_bf16 v[124:127], v[154:157], v[188:191], v[124:127]
	v_mfma_f32_16x16x32_bf16 v[104:107], v[154:157], v[202:205], v[104:107]
	v_mfma_f32_16x16x32_bf16 v[108:111], v[146:149], v[202:205], v[108:111]
	v_mfma_f32_16x16x32_bf16 v[92:95], v[146:149], v[210:213], v[92:95]
	v_mfma_f32_16x16x32_bf16 v[88:91], v[154:157], v[210:213], v[88:91]
	v_mfma_f32_16x16x32_bf16 v[72:75], v[154:157], v[218:221], v[72:75]
	v_mfma_f32_16x16x32_bf16 v[76:79], v[146:149], v[218:221], v[76:79]
	v_mfma_f32_16x16x32_bf16 v[128:131], v[150:153], v[198:201], v[128:131]
	v_mfma_f32_16x16x32_bf16 v[124:127], v[158:161], v[198:201], v[124:127]
	v_mfma_f32_16x16x32_bf16 v[104:107], v[158:161], v[206:209], v[104:107]
	v_mfma_f32_16x16x32_bf16 v[108:111], v[150:153], v[206:209], v[108:111]
	v_mfma_f32_16x16x32_bf16 v[92:95], v[150:153], v[214:217], v[92:95]
	v_mfma_f32_16x16x32_bf16 v[88:91], v[158:161], v[214:217], v[88:91]
	v_mfma_f32_16x16x32_bf16 v[72:75], v[158:161], v[230:233], v[72:75]
	v_mfma_f32_16x16x32_bf16 v[76:79], v[150:153], v[230:233], v[76:79]
	v_mfma_f32_16x16x32_bf16 v[120:123], v[172:175], v[188:191], v[120:123]
	v_mfma_f32_16x16x32_bf16 v[116:119], v[180:183], v[188:191], v[116:119]
	v_mfma_f32_16x16x32_bf16 v[96:99], v[180:183], v[202:205], v[96:99]
	v_mfma_f32_16x16x32_bf16 v[100:103], v[172:175], v[202:205], v[100:103]
	v_mfma_f32_16x16x32_bf16 v[84:87], v[172:175], v[210:213], v[84:87]
	v_mfma_f32_16x16x32_bf16 v[80:83], v[180:183], v[210:213], v[80:83]
	v_mfma_f32_16x16x32_bf16 v[64:67], v[180:183], v[218:221], v[64:67]
	v_mfma_f32_16x16x32_bf16 v[68:71], v[172:175], v[218:221], v[68:71]
	v_mfma_f32_16x16x32_bf16 v[120:123], v[176:179], v[198:201], v[120:123]
	v_mfma_f32_16x16x32_bf16 v[116:119], v[184:187], v[198:201], v[116:119]
	v_mfma_f32_16x16x32_bf16 v[96:99], v[184:187], v[206:209], v[96:99]
	v_mfma_f32_16x16x32_bf16 v[100:103], v[176:179], v[206:209], v[100:103]
	v_mfma_f32_16x16x32_bf16 v[84:87], v[176:179], v[214:217], v[84:87]
	v_mfma_f32_16x16x32_bf16 v[80:83], v[184:187], v[214:217], v[80:83]
	v_mfma_f32_16x16x32_bf16 v[64:67], v[184:187], v[230:233], v[64:67]
	v_mfma_f32_16x16x32_bf16 v[68:71], v[176:179], v[230:233], v[68:71]
	s_barrier
; #define PG8_STAGE(bufoff, gbase, voff) do { _Pragma("unroll") for (int _i = 0; _i < 2; ++_i) \
;         __builtin_amdgcn_global_load_lds((const unsigned*)((const char*)(gbase) + (voff)[_i]), (LAS unsigned*)(lds + (bufoff) + ldsw + _i * 8192), 16, 0, 0); } while (0)
; #define PG8_LDA(dst, b, h) do { _Pragma("unroll") for (int m = 0; m < 4; ++m) _Pragma("unroll") for (int k = 0; k < 2; ++k) dst[m][k] = *(const LAS bf16x8*)(lds + PG8_SA(b, h) + aoff + m * 2048 + k * 1024); } while (0)
; #define PG8_MMA(ai, bj, At, Bt) do { __builtin_amdgcn_s_setprio(1); _Pragma("unroll") for (int m = 0; m < 4; ++m) _Pragma("unroll") for (int n = 0; n < 2; ++n) _Pragma("unroll") for (int k = 0; k < 2; ++k) \
;         acc[ai][bj][m][n] = __builtin_amdgcn_mfma_f32_16x16x32_bf16(Bt[n][k], At[m][k], acc[ai][bj][m][n], 0, 0, 0); __builtin_amdgcn_s_setprio(0); } while (0)
; #define PG8_WAIT_V(n) asm volatile("s_waitcnt vmcnt(" #n ")" ::: "memory")
; #define PG8_WAIT_L(n) asm volatile("s_waitcnt lgkmcnt(" #n ")" ::: "memory")
; #define PG8_BAR __builtin_amdgcn_s_barrier()
; #define PG8_SCHED __builtin_amdgcn_sched_barrier(0)
; template <class Epi, class Sched>
; __device__ __forceinline__ void gemm_phase(LAS unsigned char* lds, const Gemm g, const Sched& S, const Epi& E, const int tid) {
;     ...
;             PG8_LDA(At, 1, 1); PG8_STAGE(PG8_SB(1, 0), b3, voffB); PG8_STAGE(PG8_SB(1, 1), b3 + hstep, voffB); PG8_STAGE(PG8_SA(1, 0), a3, voffA);
;             PG8_WAIT_V(8); PG8_WAIT_L(0); PG8_BAR; PG8_MMA(1, 0, At, B0); PG8_MMA(1, 1, At, B1); PG8_BAR; PG8_SCHED;
;         }
;         if (wr == 0) PG8_BAR;
	s_setprio 1
	s_add_i32 s63, s63, s74
	v_lshl_add_u64 v[162:163], v[162:163], 0, s[68:69]
	s_mov_b32 m0, s63
	ds_read_b128 v[188:191], v171 offset:49152
	ds_read_b128 v[198:201], v171 offset:50176
	ds_read_b128 v[202:205], v171 offset:51200
	ds_read_b128 v[206:209], v171 offset:52224
	ds_read_b128 v[210:213], v171 offset:53248
	ds_read_b128 v[214:217], v171 offset:54272
	ds_read_b128 v[218:221], v171 offset:55296
	ds_read_b128 v[230:233], v171 offset:56320
	global_load_lds_dwordx4 v[162:163], off
	s_add_i32 m0, s63, 0x2000
	s_add_u32 s66, s66, 0x40080
	v_lshl_add_u64 v[162:163], v[234:235], 0, s[68:69]
	s_addc_u32 s67, s67, 0
	s_add_i32 s63, s78, s74
	global_load_lds_dwordx4 v[162:163], off
	v_lshl_add_u64 v[162:163], s[66:67], 0, v[192:193]
	s_mov_b32 m0, s63
	s_nop 0
	global_load_lds_dwordx4 v[162:163], off
	v_lshl_add_u64 v[162:163], s[66:67], 0, v[134:135]
	s_add_i32 m0, s63, 0x2000
	s_nop 0
	global_load_lds_dwordx4 v[162:163], off
	v_lshl_add_u64 v[162:163], v[236:237], 0, s[68:69]
	s_mov_b32 m0, s93
	s_nop 0
	global_load_lds_dwordx4 v[162:163], off
	v_lshl_add_u64 v[162:163], v[238:239], 0, s[68:69]
	s_mov_b32 m0, s94
	s_nop 0
	global_load_lds_dwordx4 v[162:163], off
	s_waitcnt vmcnt(8)
	s_waitcnt lgkmcnt(0)
	s_setprio 0
	s_barrier
	s_waitcnt lgkmcnt(0)
	v_mfma_f32_16x16x32_bf16 v[60:63], v[146:149], v[188:191], v[60:63]
	v_mfma_f32_16x16x32_bf16 v[56:59], v[154:157], v[188:191], v[56:59]
	v_mfma_f32_16x16x32_bf16 v[40:43], v[154:157], v[202:205], v[40:43]
	v_mfma_f32_16x16x32_bf16 v[44:47], v[146:149], v[202:205], v[44:47]
	v_mfma_f32_16x16x32_bf16 v[28:31], v[146:149], v[210:213], v[28:31]
	v_mfma_f32_16x16x32_bf16 v[24:27], v[154:157], v[210:213], v[24:27]
	v_mfma_f32_16x16x32_bf16 v[8:11], v[154:157], v[218:221], v[8:11]
	v_mfma_f32_16x16x32_bf16 v[12:15], v[146:149], v[218:221], v[12:15]
	v_mfma_f32_16x16x32_bf16 v[60:63], v[150:153], v[198:201], v[60:63]
	v_mfma_f32_16x16x32_bf16 v[56:59], v[158:161], v[198:201], v[56:59]
	v_mfma_f32_16x16x32_bf16 v[40:43], v[158:161], v[206:209], v[40:43]
	v_mfma_f32_16x16x32_bf16 v[44:47], v[150:153], v[206:209], v[44:47]
	v_mfma_f32_16x16x32_bf16 v[28:31], v[150:153], v[214:217], v[28:31]
	v_mfma_f32_16x16x32_bf16 v[24:27], v[158:161], v[214:217], v[24:27]
	v_mfma_f32_16x16x32_bf16 v[8:11], v[158:161], v[230:233], v[8:11]
	v_mfma_f32_16x16x32_bf16 v[12:15], v[150:153], v[230:233], v[12:15]
	v_mfma_f32_16x16x32_bf16 v[52:55], v[172:175], v[188:191], v[52:55]
	v_mfma_f32_16x16x32_bf16 v[48:51], v[180:183], v[188:191], v[48:51]
	v_mfma_f32_16x16x32_bf16 v[32:35], v[180:183], v[202:205], v[32:35]
	v_mfma_f32_16x16x32_bf16 v[36:39], v[172:175], v[202:205], v[36:39]
	v_mfma_f32_16x16x32_bf16 v[20:23], v[172:175], v[210:213], v[20:23]
	v_mfma_f32_16x16x32_bf16 v[16:19], v[180:183], v[210:213], v[16:19]
	v_mfma_f32_16x16x32_bf16 v[0:3], v[180:183], v[218:221], v[0:3]
	v_mfma_f32_16x16x32_bf16 v[4:7], v[172:175], v[218:221], v[4:7]
	v_mfma_f32_16x16x32_bf16 v[52:55], v[176:179], v[198:201], v[52:55]
	v_mfma_f32_16x16x32_bf16 v[48:51], v[184:187], v[198:201], v[48:51]
	v_mfma_f32_16x16x32_bf16 v[32:35], v[184:187], v[206:209], v[32:35]
	v_mfma_f32_16x16x32_bf16 v[36:39], v[176:179], v[206:209], v[36:39]
	v_mfma_f32_16x16x32_bf16 v[20:23], v[176:179], v[214:217], v[20:23]
	v_mfma_f32_16x16x32_bf16 v[16:19], v[184:187], v[214:217], v[16:19]
	v_mfma_f32_16x16x32_bf16 v[0:3], v[184:187], v[230:233], v[0:3]
	v_mfma_f32_16x16x32_bf16 v[4:7], v[176:179], v[230:233], v[4:7]
	s_barrier
	s_setprio 1
	s_add_i32 s61, s61, 2
	s_add_u32 s64, s64, 0x100
	s_addc_u32 s65, s65, 0
	s_add_u32 s59, s59, 0x100
	s_addc_u32 s60, s60, 0
	s_cmp_gt_u32 s61, 13
	s_cbranch_scc0 .LBB0_168
	s_and_b64 vcc, exec, s[50:51]
	s_cbranch_vccz .LBB0_171
	s_barrier

;     __device__ __forceinline__ Pre prefetch(const Unit& u, int tid) const { return prenorm_load(stats, u.pn * BM, sW + (size_t)(u.pn >> 4) * SW_ROWS + u.pm * BM, tid); }
;     __device__ __forceinline__ Pre prefetch(const Unit& u, int tid) const { return prenorm_load(stats, u.pm * BM, sW + (size_t)(u.pm >> 4) * SW_ROWS + u.pn * BM, tid); }
;     __device__ __forceinline__ Pre prefetch(const Unit& u, int tid) const { return prenorm_load(stats, u.pm * BM, sW + (size_t)(u.pm >> 4) * SW_ROWS + u.pn * BM, tid); }
; #define PG8_STAGE(bufoff, gbase, voff) do { _Pragma("unroll") for (int _i = 0; _i < 2; ++_i) \
;         __builtin_amdgcn_global_load_lds((const unsigned*)((const char*)(gbase) + (voff)[_i]), (LAS unsigned*)(lds + (bufoff) + ldsw + _i * 8192), 16, 0, 0); } while (0)
; #define PG8_LDA(dst, b, h) do { _Pragma("unroll") for (int m = 0; m < 4; ++m) _Pragma("unroll") for (int k = 0; k < 2; ++k) dst[m][k] = *(const LAS bf16x8*)(lds + PG8_SA(b, h) + aoff + m * 2048 + k * 1024); } while (0)
; #define PG8_WAIT_V(n) asm volatile("s_waitcnt vmcnt(" #n ")" ::: "memory")
; #define PG8_BAR __builtin_amdgcn_s_barrier()
; template <class Epi, class Sched>
; __device__ __forceinline__ void gemm_phase(LAS unsigned char* lds, const Gemm g, const Sched& S, const Epi& E, const int tid) {
;     ...
;         const char* nA = has_next ? (const char*)g.A + (size_t)nxt.pm * tstep : cA; const char* nB = has_next ? (const char*)g.Bt + (size_t)nxt.pn * tstep : cB;
;         const typename Epi::Pre pre = E.prefetch(cur, tid);
;         for (int t = 0; t < nt; t += 2) {
;             const bool last = (t == nt - 2);
;             const char* a1 = cA + (size_t)(t + 1) * kstep;
;             const char* a2 = last ? nA : cA + (size_t)(t + 2) * kstep; const char* b2 = last ? nB : cB + (size_t)(t + 2) * kstep;
;             const char* a3 = a2 + kstep; const char* b3 = b2 + kstep;
;             PG8_LDB(B0, 0, 0); PG8_LDB(B1, 0, 1); PG8_SCHED; PG8_LDA(At, 0, 0); PG8_STAGE(PG8_SA(1, 1), a1 + hstep, voffA);
;             PG8_WAIT_V(8); PG8_WAIT_L(0); PG8_BAR; PG8_MMA(0, 0, At, B0); PG8_MMA(0, 1, At, B1); PG8_BAR; PG8_SCHED;
;             PG8_LDA(At, 0, 1); PG8_STAGE(PG8_SB(0, 0), b2, voffB); PG8_STAGE(PG8_SB(0, 1), b2 + hstep, voffB); PG8_STAGE(PG8_SA(0, 0), a2, voffA);
;             PG8_WAIT_V(8); PG8_WAIT_L(0); PG8_BAR; PG8_MMA(1, 0, At, B0); PG8_MMA(1, 1, At, B1); PG8_BAR; PG8_SCHED;
.LBB0_265:
	s_or_b64 exec, exec, s[38:39]
	s_ashr_i32 s23, s22, 31
	s_lshl_b64 s[38:39], s[22:23], 19
	s_add_u32 s38, s46, s38
	s_addc_u32 s39, s47, s39
	s_and_b64 s[56:57], s[4:5], exec
	s_cselect_b32 s23, s39, s7
	s_cselect_b32 s56, s38, s6
	s_ashr_i32 s55, s54, 31
	s_lshl_b64 s[58:59], s[54:55], 19
	s_add_u32 s62, s35, s58
	s_addc_u32 s63, s84, s59
	s_and_b64 s[58:59], s[4:5], exec
	s_cselect_b32 s55, s63, s65
	s_cselect_b32 s57, s62, s64
	s_add_u32 s6, s6, 0x40080
	s_addc_u32 s7, s7, 0
	s_add_u32 s58, s64, 0x100
	s_addc_u32 s59, s65, 0
	s_mov_b32 s60, -2
	s_add_u32 s61, s6, 0xfffc0080
	s_addc_u32 s64, s7, -1
	s_add_i32 s70, 0, 0x10000
	s_cmp_eq_u32 s60, 12
	s_cselect_b32 s67, s23, s64
	s_cselect_b32 s66, s56, s61
	v_add_u32_e32 v81, s70, v216
	s_cselect_b32 s65, s55, s59
	s_cselect_b32 s64, s57, s58
	s_add_i32 s61, 0, 0x14000
	ds_read_b128 v[88:91], v81
	ds_read_b128 v[92:95], v81 offset:1024
	ds_read_b128 v[144:147], v81 offset:2048
	ds_read_b128 v[148:151], v81 offset:3072
	v_add_u32_e32 v81, s61, v216
	ds_read_b128 v[152:155], v81
	ds_read_b128 v[156:159], v81 offset:1024
	ds_read_b128 v[178:181], v81 offset:2048
	ds_read_b128 v[182:185], v81 offset:3072
	v_lshl_add_u64 v[82:83], s[6:7], 0, v[174:175]
	s_add_i32 m0, s73, 0xc000
	ds_read_b128 v[186:189], v230
	ds_read_b128 v[198:201], v230 offset:1024
	ds_read_b128 v[202:205], v230 offset:2048
	ds_read_b128 v[206:209], v230 offset:3072
	ds_read_b128 v[234:237], v230 offset:4096
	ds_read_b128 v[238:241], v230 offset:5120
	ds_read_b128 v[242:245], v230 offset:6144
	ds_read_b128 v[246:249], v230 offset:7168
	global_load_lds_dwordx4 v[82:83], off
	v_lshl_add_u64 v[82:83], s[6:7], 0, v[176:177]
	s_add_i32 m0, s73, 0xe000
	s_nop 0
	global_load_lds_dwordx4 v[82:83], off
	s_waitcnt vmcnt(8)
	s_waitcnt lgkmcnt(0)
	s_setprio 0
	s_barrier
	s_waitcnt lgkmcnt(0)
	v_mfma_f32_16x16x32_bf16 v[140:143], v[88:91], v[186:189], 0
	v_mfma_f32_16x16x32_bf16 v[136:139], v[144:147], v[186:189], 0
	v_mfma_f32_16x16x32_bf16 v[120:123], v[144:147], v[202:205], 0
	v_mfma_f32_16x16x32_bf16 v[124:127], v[88:91], v[202:205], 0
	v_mfma_f32_16x16x32_bf16 v[108:111], v[88:91], v[234:237], 0
	v_mfma_f32_16x16x32_bf16 v[104:107], v[144:147], v[234:237], 0
	v_mfma_f32_16x16x32_bf16 v[76:79], v[144:147], v[242:245], 0
	v_mfma_f32_16x16x32_bf16 v[82:85], v[88:91], v[242:245], 0
	v_mfma_f32_16x16x32_bf16 v[140:143], v[92:95], v[198:201], v[140:143]
	v_mfma_f32_16x16x32_bf16 v[136:139], v[148:151], v[198:201], v[136:139]
	v_mfma_f32_16x16x32_bf16 v[120:123], v[148:151], v[206:209], v[120:123]
	v_mfma_f32_16x16x32_bf16 v[124:127], v[92:95], v[206:209], v[124:127]
	v_mfma_f32_16x16x32_bf16 v[108:111], v[92:95], v[238:241], v[108:111]
	v_mfma_f32_16x16x32_bf16 v[104:107], v[148:151], v[238:241], v[104:107]
	v_mfma_f32_16x16x32_bf16 v[76:79], v[148:151], v[246:249], v[76:79]
	v_mfma_f32_16x16x32_bf16 v[82:85], v[92:95], v[246:249], v[82:85]
	v_mfma_f32_16x16x32_bf16 v[132:135], v[152:155], v[186:189], 0
	v_mfma_f32_16x16x32_bf16 v[128:131], v[178:181], v[186:189], 0
	v_mfma_f32_16x16x32_bf16 v[112:115], v[178:181], v[202:205], 0
	v_mfma_f32_16x16x32_bf16 v[116:119], v[152:155], v[202:205], 0
	v_mfma_f32_16x16x32_bf16 v[100:103], v[152:155], v[234:237], 0
	v_mfma_f32_16x16x32_bf16 v[96:99], v[178:181], v[234:237], 0
	v_mfma_f32_16x16x32_bf16 v[64:67], v[178:181], v[242:245], 0
	v_mfma_f32_16x16x32_bf16 v[68:71], v[152:155], v[242:245], 0
	v_mfma_f32_16x16x32_bf16 v[132:135], v[156:159], v[198:201], v[132:135]
	v_mfma_f32_16x16x32_bf16 v[128:131], v[182:185], v[198:201], v[128:131]
	v_mfma_f32_16x16x32_bf16 v[112:115], v[182:185], v[206:209], v[112:115]
	v_mfma_f32_16x16x32_bf16 v[116:119], v[156:159], v[206:209], v[116:119]
	v_mfma_f32_16x16x32_bf16 v[100:103], v[156:159], v[238:241], v[100:103]
	v_mfma_f32_16x16x32_bf16 v[96:99], v[182:185], v[238:241], v[96:99]
	v_mfma_f32_16x16x32_bf16 v[64:67], v[182:185], v[246:249], v[64:67]
	v_mfma_f32_16x16x32_bf16 v[68:71], v[156:159], v[246:249], v[68:71]
	s_barrier
	s_setprio 1
	s_add_i32 s70, s70, s12
	v_lshl_add_u64 v[190:191], s[64:65], 0, v[164:165]
	s_mov_b32 m0, s70
	ds_read_b128 v[186:189], v230 offset:16384
	ds_read_b128 v[198:201], v230 offset:17408
	ds_read_b128 v[202:205], v230 offset:18432
	ds_read_b128 v[206:209], v230 offset:19456
	ds_read_b128 v[234:237], v230 offset:20480
	ds_read_b128 v[238:241], v230 offset:21504
	ds_read_b128 v[242:245], v230 offset:22528
	ds_read_b128 v[246:249], v230 offset:23552
	global_load_lds_dwordx4 v[190:191], off
	s_add_i32 m0, s70, 0x2000
	s_add_u32 s70, s64, 0x40000
	v_lshl_add_u64 v[250:251], s[64:65], 0, v[168:169]
	s_addc_u32 s71, s65, 0
	s_add_i32 s61, s61, s12
	global_load_lds_dwordx4 v[250:251], off
	v_lshl_add_u64 v[86:87], s[70:71], 0, v[164:165]
	s_mov_b32 m0, s61
	v_lshl_add_u64 v[224:225], s[66:67], 0, v[162:163]
	global_load_lds_dwordx4 v[86:87], off
	v_lshl_add_u64 v[86:87], s[70:71], 0, v[168:169]
	s_add_i32 m0, s61, 0x2000
	v_lshl_add_u64 v[226:227], s[66:67], 0, v[166:167]
	global_load_lds_dwordx4 v[86:87], off
	s_mov_b32 m0, s73
	s_nop 0
	global_load_lds_dwordx4 v[224:225], off
	s_mov_b32 m0, s74
	s_nop 0
	global_load_lds_dwordx4 v[226:227], off
	s_waitcnt vmcnt(8)
	s_waitcnt lgkmcnt(0)
	s_setprio 0
	s_barrier
; #define PG8_STAGE(bufoff, gbase, voff) do { _Pragma("unroll") for (int _i = 0; _i < 2; ++_i) \
;         __builtin_amdgcn_global_load_lds((const unsigned*)((const char*)(gbase) + (voff)[_i]), (LAS unsigned*)(lds + (bufoff) + ldsw + _i * 8192), 16, 0, 0); } while (0)
; #define PG8_LDA(dst, b, h) do { _Pragma("unroll") for (int m = 0; m < 4; ++m) _Pragma("unroll") for (int k = 0; k < 2; ++k) dst[m][k] = *(const LAS bf16x8*)(lds + PG8_SA(b, h) + aoff + m * 2048 + k * 1024); } while (0)
; #define PG8_LDB(dst, b, h) do { _Pragma("unroll") for (int n = 0; n < 2; ++n) _Pragma("unroll") for (int k = 0; k < 2; ++k) dst[n][k] = *(const LAS bf16x8*)(lds + PG8_SB(b, h) + boff + n * 2048 + k * 1024); } while (0)
; #define PG8_MMA(ai, bj, At, Bt) do { __builtin_amdgcn_s_setprio(1); _Pragma("unroll") for (int m = 0; m < 4; ++m) _Pragma("unroll") for (int n = 0; n < 2; ++n) _Pragma("unroll") for (int k = 0; k < 2; ++k) \
;         acc[ai][bj][m][n] = __builtin_amdgcn_mfma_f32_16x16x32_bf16(Bt[n][k], At[m][k], acc[ai][bj][m][n], 0, 0, 0); __builtin_amdgcn_s_setprio(0); } while (0)
; #define PG8_WAIT_V(n) asm volatile("s_waitcnt vmcnt(" #n ")" ::: "memory")
; #define PG8_WAIT_L(n) asm volatile("s_waitcnt lgkmcnt(" #n ")" ::: "memory")
; #define PG8_BAR __builtin_amdgcn_s_barrier()
; #define PG8_SCHED __builtin_amdgcn_sched_barrier(0)
; template <class Epi, class Sched>
; __device__ __forceinline__ void gemm_phase(LAS unsigned char* lds, const Gemm g, const Sched& S, const Epi& E, const int tid) {
;     ...
;             PG8_WAIT_V(8); PG8_WAIT_L(0); PG8_BAR; PG8_MMA(1, 0, At, B0); PG8_MMA(1, 1, At, B1); PG8_BAR; PG8_SCHED;
;             PG8_LDB(B0, 1, 0); PG8_LDB(B1, 1, 1); PG8_SCHED; PG8_LDA(At, 1, 0); PG8_STAGE(PG8_SA(0, 1), a2 + hstep, voffA);
;             PG8_WAIT_V(8); PG8_WAIT_L(0); PG8_BAR; PG8_MMA(0, 0, At, B0); PG8_MMA(0, 1, At, B1); PG8_BAR; PG8_SCHED;
	s_waitcnt lgkmcnt(0)
	v_mfma_f32_16x16x32_bf16 v[60:63], v[88:91], v[186:189], 0
	v_mfma_f32_16x16x32_bf16 v[56:59], v[144:147], v[186:189], 0
	v_mfma_f32_16x16x32_bf16 v[40:43], v[144:147], v[202:205], 0
	v_mfma_f32_16x16x32_bf16 v[44:47], v[88:91], v[202:205], 0
	v_mfma_f32_16x16x32_bf16 v[28:31], v[88:91], v[234:237], 0
	v_mfma_f32_16x16x32_bf16 v[24:27], v[144:147], v[234:237], 0
	v_mfma_f32_16x16x32_bf16 v[8:11], v[144:147], v[242:245], 0
	v_mfma_f32_16x16x32_bf16 v[12:15], v[88:91], v[242:245], 0
	v_mfma_f32_16x16x32_bf16 v[60:63], v[92:95], v[198:201], v[60:63]
	v_mfma_f32_16x16x32_bf16 v[56:59], v[148:151], v[198:201], v[56:59]
	v_mfma_f32_16x16x32_bf16 v[40:43], v[148:151], v[206:209], v[40:43]
	v_mfma_f32_16x16x32_bf16 v[44:47], v[92:95], v[206:209], v[44:47]
	v_mfma_f32_16x16x32_bf16 v[28:31], v[92:95], v[238:241], v[28:31]
	v_mfma_f32_16x16x32_bf16 v[24:27], v[148:151], v[238:241], v[24:27]
	v_mfma_f32_16x16x32_bf16 v[8:11], v[148:151], v[246:249], v[8:11]
	v_mfma_f32_16x16x32_bf16 v[12:15], v[92:95], v[246:249], v[12:15]
	v_mfma_f32_16x16x32_bf16 v[52:55], v[152:155], v[186:189], 0
	v_mfma_f32_16x16x32_bf16 v[48:51], v[178:181], v[186:189], 0
	v_mfma_f32_16x16x32_bf16 v[32:35], v[178:181], v[202:205], 0
	v_mfma_f32_16x16x32_bf16 v[36:39], v[152:155], v[202:205], 0
	v_mfma_f32_16x16x32_bf16 v[20:23], v[152:155], v[234:237], 0
	v_mfma_f32_16x16x32_bf16 v[16:19], v[178:181], v[234:237], 0
	v_mfma_f32_16x16x32_bf16 v[0:3], v[178:181], v[242:245], 0
	v_mfma_f32_16x16x32_bf16 v[4:7], v[152:155], v[242:245], 0
	v_mfma_f32_16x16x32_bf16 v[52:55], v[156:159], v[198:201], v[52:55]
	v_mfma_f32_16x16x32_bf16 v[48:51], v[182:185], v[198:201], v[48:51]
	v_mfma_f32_16x16x32_bf16 v[32:35], v[182:185], v[206:209], v[32:35]
	v_mfma_f32_16x16x32_bf16 v[36:39], v[156:159], v[206:209], v[36:39]
	v_mfma_f32_16x16x32_bf16 v[20:23], v[156:159], v[238:241], v[20:23]
	v_mfma_f32_16x16x32_bf16 v[16:19], v[182:185], v[238:241], v[16:19]
	v_mfma_f32_16x16x32_bf16 v[0:3], v[182:185], v[246:249], v[0:3]
	v_mfma_f32_16x16x32_bf16 v[4:7], v[156:159], v[246:249], v[4:7]
	s_barrier
	s_setprio 1
	s_add_i32 s61, 0, 0x18000
	v_add_u32_e32 v81, s61, v216
	s_add_i32 s70, 0, 0x1c000
	ds_read_b128 v[88:91], v81
	ds_read_b128 v[92:95], v81 offset:1024
	ds_read_b128 v[144:147], v81 offset:2048
	ds_read_b128 v[148:151], v81 offset:3072
	v_add_u32_e32 v81, s70, v216
	ds_read_b128 v[152:155], v81
	ds_read_b128 v[156:159], v81 offset:1024
	ds_read_b128 v[178:181], v81 offset:2048
	ds_read_b128 v[182:185], v81 offset:3072
	s_add_u32 s66, s66, 0x40000
	s_addc_u32 s67, s67, 0
	s_mov_b32 m0, s75
	v_lshl_add_u64 v[86:87], s[66:67], 0, v[162:163]
	ds_read_b128 v[186:189], v230 offset:32768
	ds_read_b128 v[198:201], v230 offset:33792
	ds_read_b128 v[202:205], v230 offset:34816
	ds_read_b128 v[206:209], v230 offset:35840
	ds_read_b128 v[234:237], v230 offset:36864
	ds_read_b128 v[238:241], v230 offset:37888
	ds_read_b128 v[242:245], v230 offset:38912
	ds_read_b128 v[246:249], v230 offset:39936
	global_load_lds_dwordx4 v[86:87], off
	v_lshl_add_u64 v[86:87], s[66:67], 0, v[166:167]
	s_mov_b32 m0, s81
	s_nop 0
	global_load_lds_dwordx4 v[86:87], off
	s_waitcnt vmcnt(8)
	s_waitcnt lgkmcnt(0)
	s_setprio 0
	s_barrier
	s_waitcnt lgkmcnt(0)
	v_mfma_f32_16x16x32_bf16 v[140:143], v[88:91], v[186:189], v[140:143]
	v_mfma_f32_16x16x32_bf16 v[136:139], v[144:147], v[186:189], v[136:139]
	v_mfma_f32_16x16x32_bf16 v[120:123], v[144:147], v[202:205], v[120:123]
	v_mfma_f32_16x16x32_bf16 v[124:127], v[88:91], v[202:205], v[124:127]
	v_mfma_f32_16x16x32_bf16 v[108:111], v[88:91], v[234:237], v[108:111]
	v_mfma_f32_16x16x32_bf16 v[104:107], v[144:147], v[234:237], v[104:107]
	v_mfma_f32_16x16x32_bf16 v[76:79], v[144:147], v[242:245], v[76:79]
	v_mfma_f32_16x16x32_bf16 v[82:85], v[88:91], v[242:245], v[82:85]
	v_mfma_f32_16x16x32_bf16 v[140:143], v[92:95], v[198:201], v[140:143]
	v_mfma_f32_16x16x32_bf16 v[136:139], v[148:151], v[198:201], v[136:139]
	v_mfma_f32_16x16x32_bf16 v[120:123], v[148:151], v[206:209], v[120:123]
	v_mfma_f32_16x16x32_bf16 v[124:127], v[92:95], v[206:209], v[124:127]
	v_mfma_f32_16x16x32_bf16 v[108:111], v[92:95], v[238:241], v[108:111]
	v_mfma_f32_16x16x32_bf16 v[104:107], v[148:151], v[238:241], v[104:107]
	v_mfma_f32_16x16x32_bf16 v[76:79], v[148:151], v[246:249], v[76:79]
	v_mfma_f32_16x16x32_bf16 v[84:87], v[92:95], v[246:249], v[82:85]
	v_mfma_f32_16x16x32_bf16 v[132:135], v[152:155], v[186:189], v[132:135]
	v_mfma_f32_16x16x32_bf16 v[128:131], v[178:181], v[186:189], v[128:131]
	v_mfma_f32_16x16x32_bf16 v[112:115], v[178:181], v[202:205], v[112:115]
	v_mfma_f32_16x16x32_bf16 v[116:119], v[152:155], v[202:205], v[116:119]
	v_mfma_f32_16x16x32_bf16 v[100:103], v[152:155], v[234:237], v[100:103]
	v_mfma_f32_16x16x32_bf16 v[96:99], v[178:181], v[234:237], v[96:99]
	v_mfma_f32_16x16x32_bf16 v[64:67], v[178:181], v[242:245], v[64:67]
	v_mfma_f32_16x16x32_bf16 v[68:71], v[152:155], v[242:245], v[68:71]
	v_mfma_f32_16x16x32_bf16 v[132:135], v[156:159], v[198:201], v[132:135]
	v_mfma_f32_16x16x32_bf16 v[128:131], v[182:185], v[198:201], v[128:131]
	v_mfma_f32_16x16x32_bf16 v[112:115], v[182:185], v[206:209], v[112:115]
	v_mfma_f32_16x16x32_bf16 v[116:119], v[156:159], v[206:209], v[116:119]
	v_mfma_f32_16x16x32_bf16 v[100:103], v[156:159], v[238:241], v[100:103]
	v_mfma_f32_16x16x32_bf16 v[96:99], v[182:185], v[238:241], v[96:99]
	v_mfma_f32_16x16x32_bf16 v[64:67], v[182:185], v[246:249], v[64:67]
	v_mfma_f32_16x16x32_bf16 v[68:71], v[156:159], v[246:249], v[68:71]
	s_barrier
; #define PG8_STAGE(bufoff, gbase, voff) do { _Pragma("unroll") for (int _i = 0; _i < 2; ++_i) \
;         __builtin_amdgcn_global_load_lds((const unsigned*)((const char*)(gbase) + (voff)[_i]), (LAS unsigned*)(lds + (bufoff) + ldsw + _i * 8192), 16, 0, 0); } while (0)
; #define PG8_LDA(dst, b, h) do { _Pragma("unroll") for (int m = 0; m < 4; ++m) _Pragma("unroll") for (int k = 0; k < 2; ++k) dst[m][k] = *(const LAS bf16x8*)(lds + PG8_SA(b, h) + aoff + m * 2048 + k * 1024); } while (0)
; #define PG8_LDB(dst, b, h) do { _Pragma("unroll") for (int n = 0; n < 2; ++n) _Pragma("unroll") for (int k = 0; k < 2; ++k) dst[n][k] = *(const LAS bf16x8*)(lds + PG8_SB(b, h) + boff + n * 2048 + k * 1024); } while (0)
; #define PG8_WAIT_V(n) asm volatile("s_waitcnt vmcnt(" #n ")" ::: "memory")
; #define PG8_BAR __builtin_amdgcn_s_barrier()
; template <class Epi, class Sched>
; __device__ __forceinline__ void gemm_phase(LAS unsigned char* lds, const Gemm g, const Sched& S, const Epi& E, const int tid) {
;     ...
;         for (int t = 0; t < nt; t += 2) {
;             const bool last = (t == nt - 2);
;             const char* a1 = cA + (size_t)(t + 1) * kstep;
;             const char* a2 = last ? nA : cA + (size_t)(t + 2) * kstep; const char* b2 = last ? nB : cB + (size_t)(t + 2) * kstep;
;             const char* a3 = a2 + kstep; const char* b3 = b2 + kstep;
;             PG8_LDB(B0, 0, 0); PG8_LDB(B1, 0, 1); PG8_SCHED; PG8_LDA(At, 0, 0); PG8_STAGE(PG8_SA(1, 1), a1 + hstep, voffA);
;             PG8_WAIT_V(8); PG8_WAIT_L(0); PG8_BAR; PG8_MMA(0, 0, At, B0); PG8_MMA(0, 1, At, B1); PG8_BAR; PG8_SCHED;
;             PG8_LDA(At, 0, 1); PG8_STAGE(PG8_SB(0, 0), b2, voffB); PG8_STAGE(PG8_SB(0, 1), b2 + hstep, voffB); PG8_STAGE(PG8_SA(0, 0), a2, voffA);
;             PG8_WAIT_V(8); PG8_WAIT_L(0); PG8_BAR; PG8_MMA(1, 0, At, B0); PG8_MMA(1, 1, At, B1); PG8_BAR; PG8_SCHED;
;             PG8_LDB(B0, 1, 0); PG8_LDB(B1, 1, 1); PG8_SCHED; PG8_LDA(At, 1, 0); PG8_STAGE(PG8_SA(0, 1), a2 + hstep, voffA);
;             PG8_WAIT_V(8); PG8_WAIT_L(0); PG8_BAR; PG8_MMA(0, 0, At, B0); PG8_MMA(0, 1, At, B1); PG8_BAR; PG8_SCHED;
;             PG8_LDA(At, 1, 1); PG8_STAGE(PG8_SB(1, 0), b3, voffB); PG8_STAGE(PG8_SB(1, 1), b3 + hstep, voffB); PG8_STAGE(PG8_SA(1, 0), a3, voffA);
;             PG8_WAIT_V(8); PG8_WAIT_L(0); PG8_BAR; PG8_MMA(1, 0, At, B0); PG8_MMA(1, 1, At, B1); PG8_BAR; PG8_SCHED;
	s_setprio 1
	s_add_i32 s61, s61, s12
	v_lshl_add_u64 v[82:83], v[190:191], 0, s[68:69]
	s_mov_b32 m0, s61
	ds_read_b128 v[186:189], v230 offset:49152
	ds_read_b128 v[198:201], v230 offset:50176
	ds_read_b128 v[202:205], v230 offset:51200
	ds_read_b128 v[206:209], v230 offset:52224
	ds_read_b128 v[234:237], v230 offset:53248
	ds_read_b128 v[238:241], v230 offset:54272
	ds_read_b128 v[242:245], v230 offset:55296
	ds_read_b128 v[246:249], v230 offset:56320
	global_load_lds_dwordx4 v[82:83], off
	s_add_i32 m0, s61, 0x2000
	s_add_u32 s64, s64, 0x40080
	v_lshl_add_u64 v[82:83], v[250:251], 0, s[68:69]
	s_addc_u32 s65, s65, 0
	s_add_i32 s61, s70, s12
	global_load_lds_dwordx4 v[82:83], off
	v_lshl_add_u64 v[82:83], s[64:65], 0, v[164:165]
	s_mov_b32 m0, s61
	s_nop 0
	global_load_lds_dwordx4 v[82:83], off
	v_lshl_add_u64 v[82:83], s[64:65], 0, v[168:169]
	s_add_i32 m0, s61, 0x2000
	s_nop 0
	global_load_lds_dwordx4 v[82:83], off
	v_lshl_add_u64 v[82:83], v[224:225], 0, s[68:69]
	s_mov_b32 m0, s82
	s_nop 0
	global_load_lds_dwordx4 v[82:83], off
	v_lshl_add_u64 v[82:83], v[226:227], 0, s[68:69]
	s_mov_b32 m0, s83
	s_nop 0
	global_load_lds_dwordx4 v[82:83], off
	s_waitcnt vmcnt(8)
	s_waitcnt lgkmcnt(0)
	s_setprio 0
	s_barrier
	s_waitcnt lgkmcnt(0)
	v_mfma_f32_16x16x32_bf16 v[60:63], v[88:91], v[186:189], v[60:63]
	v_mfma_f32_16x16x32_bf16 v[56:59], v[144:147], v[186:189], v[56:59]
	v_mfma_f32_16x16x32_bf16 v[40:43], v[144:147], v[202:205], v[40:43]
	v_mfma_f32_16x16x32_bf16 v[44:47], v[88:91], v[202:205], v[44:47]
	v_mfma_f32_16x16x32_bf16 v[28:31], v[88:91], v[234:237], v[28:31]
	v_mfma_f32_16x16x32_bf16 v[24:27], v[144:147], v[234:237], v[24:27]
	v_mfma_f32_16x16x32_bf16 v[8:11], v[144:147], v[242:245], v[8:11]
	v_mfma_f32_16x16x32_bf16 v[12:15], v[88:91], v[242:245], v[12:15]
	v_mfma_f32_16x16x32_bf16 v[60:63], v[92:95], v[198:201], v[60:63]
	v_mfma_f32_16x16x32_bf16 v[56:59], v[148:151], v[198:201], v[56:59]
	v_mfma_f32_16x16x32_bf16 v[40:43], v[148:151], v[206:209], v[40:43]
	v_mfma_f32_16x16x32_bf16 v[44:47], v[92:95], v[206:209], v[44:47]
	v_mfma_f32_16x16x32_bf16 v[28:31], v[92:95], v[238:241], v[28:31]
	v_mfma_f32_16x16x32_bf16 v[24:27], v[148:151], v[238:241], v[24:27]
	v_mfma_f32_16x16x32_bf16 v[8:11], v[148:151], v[246:249], v[8:11]
	v_mfma_f32_16x16x32_bf16 v[12:15], v[92:95], v[246:249], v[12:15]
	v_mfma_f32_16x16x32_bf16 v[52:55], v[152:155], v[186:189], v[52:55]
	v_mfma_f32_16x16x32_bf16 v[48:51], v[178:181], v[186:189], v[48:51]
	v_mfma_f32_16x16x32_bf16 v[32:35], v[178:181], v[202:205], v[32:35]
	v_mfma_f32_16x16x32_bf16 v[36:39], v[152:155], v[202:205], v[36:39]
	v_mfma_f32_16x16x32_bf16 v[20:23], v[152:155], v[234:237], v[20:23]
	v_mfma_f32_16x16x32_bf16 v[16:19], v[178:181], v[234:237], v[16:19]
	v_mfma_f32_16x16x32_bf16 v[0:3], v[178:181], v[242:245], v[0:3]
	v_mfma_f32_16x16x32_bf16 v[4:7], v[152:155], v[242:245], v[4:7]
	v_mfma_f32_16x16x32_bf16 v[52:55], v[156:159], v[198:201], v[52:55]
	v_mfma_f32_16x16x32_bf16 v[48:51], v[182:185], v[198:201], v[48:51]
	v_mfma_f32_16x16x32_bf16 v[32:35], v[182:185], v[206:209], v[32:35]
	v_mfma_f32_16x16x32_bf16 v[36:39], v[156:159], v[206:209], v[36:39]
	v_mfma_f32_16x16x32_bf16 v[20:23], v[156:159], v[238:241], v[20:23]
	v_mfma_f32_16x16x32_bf16 v[16:19], v[182:185], v[238:241], v[16:19]
	v_mfma_f32_16x16x32_bf16 v[0:3], v[182:185], v[246:249], v[0:3]
	v_mfma_f32_16x16x32_bf16 v[4:7], v[156:159], v[246:249], v[4:7]
	s_barrier
	s_setprio 1
	s_add_i32 s60, s60, 2
	s_add_u32 s6, s6, 0x100
	s_addc_u32 s7, s7, 0
	s_add_u32 s58, s58, 0x100
	s_addc_u32 s59, s59, 0
	s_cmp_gt_u32 s60, 13
.LBB0_266:
	s_add_u32 s61, s6, 0xfffc0080
	s_addc_u32 s64, s7, -1
	s_add_i32 s70, 0, 0x10000
	s_cmp_eq_u32 s60, 12
	s_cselect_b32 s67, s23, s64
	s_cselect_b32 s66, s56, s61
	v_add_u32_e32 v81, s70, v216
	s_cselect_b32 s65, s55, s59
	s_cselect_b32 s64, s57, s58
	s_add_i32 s61, 0, 0x14000
	ds_read_b128 v[88:91], v81
	ds_read_b128 v[92:95], v81 offset:1024
	ds_read_b128 v[144:147], v81 offset:2048
	ds_read_b128 v[148:151], v81 offset:3072
	v_add_u32_e32 v81, s61, v216
	ds_read_b128 v[152:155], v81
	ds_read_b128 v[156:159], v81 offset:1024
	ds_read_b128 v[178:181], v81 offset:2048
	ds_read_b128 v[182:185], v81 offset:3072
	v_lshl_add_u64 v[82:83], s[6:7], 0, v[174:175]
	s_add_i32 m0, s73, 0xc000
	ds_read_b128 v[186:189], v230
	ds_read_b128 v[198:201], v230 offset:1024
	ds_read_b128 v[202:205], v230 offset:2048
	ds_read_b128 v[206:209], v230 offset:3072
	ds_read_b128 v[234:237], v230 offset:4096
	ds_read_b128 v[238:241], v230 offset:5120
	ds_read_b128 v[242:245], v230 offset:6144
	ds_read_b128 v[246:249], v230 offset:7168
	global_load_lds_dwordx4 v[82:83], off
	v_lshl_add_u64 v[82:83], s[6:7], 0, v[176:177]
	s_add_i32 m0, s73, 0xe000
	s_nop 0
	global_load_lds_dwordx4 v[82:83], off
	s_waitcnt vmcnt(8)
	s_waitcnt lgkmcnt(0)
	s_setprio 0
	s_barrier
; #define PG8_STAGE(bufoff, gbase, voff) do { _Pragma("unroll") for (int _i = 0; _i < 2; ++_i) \
;         __builtin_amdgcn_global_load_lds((const unsigned*)((const char*)(gbase) + (voff)[_i]), (LAS unsigned*)(lds + (bufoff) + ldsw + _i * 8192), 16, 0, 0); } while (0)
; #define PG8_LDA(dst, b, h) do { _Pragma("unroll") for (int m = 0; m < 4; ++m) _Pragma("unroll") for (int k = 0; k < 2; ++k) dst[m][k] = *(const LAS bf16x8*)(lds + PG8_SA(b, h) + aoff + m * 2048 + k * 1024); } while (0)
; #define PG8_MMA(ai, bj, At, Bt) do { __builtin_amdgcn_s_setprio(1); _Pragma("unroll") for (int m = 0; m < 4; ++m) _Pragma("unroll") for (int n = 0; n < 2; ++n) _Pragma("unroll") for (int k = 0; k < 2; ++k) \
;         acc[ai][bj][m][n] = __builtin_amdgcn_mfma_f32_16x16x32_bf16(Bt[n][k], At[m][k], acc[ai][bj][m][n], 0, 0, 0); __builtin_amdgcn_s_setprio(0); } while (0)
; #define PG8_WAIT_V(n) asm volatile("s_waitcnt vmcnt(" #n ")" ::: "memory")
; #define PG8_WAIT_L(n) asm volatile("s_waitcnt lgkmcnt(" #n ")" ::: "memory")
; #define PG8_BAR __builtin_amdgcn_s_barrier()
; #define PG8_SCHED __builtin_amdgcn_sched_barrier(0)
; template <class Epi, class Sched>
; __device__ __forceinline__ void gemm_phase(LAS unsigned char* lds, const Gemm g, const Sched& S, const Epi& E, const int tid) {
;     ...
;             PG8_WAIT_V(8); PG8_WAIT_L(0); PG8_BAR; PG8_MMA(0, 0, At, B0); PG8_MMA(0, 1, At, B1); PG8_BAR; PG8_SCHED;
;             PG8_LDA(At, 0, 1); PG8_STAGE(PG8_SB(0, 0), b2, voffB); PG8_STAGE(PG8_SB(0, 1), b2 + hstep, voffB); PG8_STAGE(PG8_SA(0, 0), a2, voffA);
;             PG8_WAIT_V(8); PG8_WAIT_L(0); PG8_BAR; PG8_MMA(1, 0, At, B0); PG8_MMA(1, 1, At, B1); PG8_BAR; PG8_SCHED;
	s_waitcnt lgkmcnt(0)
	v_mfma_f32_16x16x32_bf16 v[140:143], v[88:91], v[186:189], v[140:143]
	v_mfma_f32_16x16x32_bf16 v[136:139], v[144:147], v[186:189], v[136:139]
	v_mfma_f32_16x16x32_bf16 v[120:123], v[144:147], v[202:205], v[120:123]
	v_mfma_f32_16x16x32_bf16 v[124:127], v[88:91], v[202:205], v[124:127]
	v_mfma_f32_16x16x32_bf16 v[108:111], v[88:91], v[234:237], v[108:111]
	v_mfma_f32_16x16x32_bf16 v[104:107], v[144:147], v[234:237], v[104:107]
	v_mfma_f32_16x16x32_bf16 v[76:79], v[144:147], v[242:245], v[76:79]
	v_mfma_f32_16x16x32_bf16 v[82:85], v[88:91], v[242:245], v[84:87]
	v_mfma_f32_16x16x32_bf16 v[140:143], v[92:95], v[198:201], v[140:143]
	v_mfma_f32_16x16x32_bf16 v[136:139], v[148:151], v[198:201], v[136:139]
	v_mfma_f32_16x16x32_bf16 v[120:123], v[148:151], v[206:209], v[120:123]
	v_mfma_f32_16x16x32_bf16 v[124:127], v[92:95], v[206:209], v[124:127]
	v_mfma_f32_16x16x32_bf16 v[108:111], v[92:95], v[238:241], v[108:111]
	v_mfma_f32_16x16x32_bf16 v[104:107], v[148:151], v[238:241], v[104:107]
	v_mfma_f32_16x16x32_bf16 v[76:79], v[148:151], v[246:249], v[76:79]
	v_mfma_f32_16x16x32_bf16 v[82:85], v[92:95], v[246:249], v[82:85]
	v_mfma_f32_16x16x32_bf16 v[132:135], v[152:155], v[186:189], v[132:135]
	v_mfma_f32_16x16x32_bf16 v[128:131], v[178:181], v[186:189], v[128:131]
	v_mfma_f32_16x16x32_bf16 v[112:115], v[178:181], v[202:205], v[112:115]
	v_mfma_f32_16x16x32_bf16 v[116:119], v[152:155], v[202:205], v[116:119]
	v_mfma_f32_16x16x32_bf16 v[100:103], v[152:155], v[234:237], v[100:103]
	v_mfma_f32_16x16x32_bf16 v[96:99], v[178:181], v[234:237], v[96:99]
	v_mfma_f32_16x16x32_bf16 v[64:67], v[178:181], v[242:245], v[64:67]
	v_mfma_f32_16x16x32_bf16 v[68:71], v[152:155], v[242:245], v[68:71]
	v_mfma_f32_16x16x32_bf16 v[132:135], v[156:159], v[198:201], v[132:135]
	v_mfma_f32_16x16x32_bf16 v[128:131], v[182:185], v[198:201], v[128:131]
	v_mfma_f32_16x16x32_bf16 v[112:115], v[182:185], v[206:209], v[112:115]
	v_mfma_f32_16x16x32_bf16 v[116:119], v[156:159], v[206:209], v[116:119]
	v_mfma_f32_16x16x32_bf16 v[100:103], v[156:159], v[238:241], v[100:103]
	v_mfma_f32_16x16x32_bf16 v[96:99], v[182:185], v[238:241], v[96:99]
	v_mfma_f32_16x16x32_bf16 v[64:67], v[182:185], v[246:249], v[64:67]
	v_mfma_f32_16x16x32_bf16 v[68:71], v[156:159], v[246:249], v[68:71]
	s_barrier
	s_setprio 1
	s_add_i32 s70, s70, s12
	v_lshl_add_u64 v[190:191], s[64:65], 0, v[164:165]
	s_mov_b32 m0, s70
	ds_read_b128 v[186:189], v230 offset:16384
	ds_read_b128 v[198:201], v230 offset:17408
	ds_read_b128 v[202:205], v230 offset:18432
	ds_read_b128 v[206:209], v230 offset:19456
	ds_read_b128 v[234:237], v230 offset:20480
	ds_read_b128 v[238:241], v230 offset:21504
	ds_read_b128 v[242:245], v230 offset:22528
	ds_read_b128 v[246:249], v230 offset:23552
	global_load_lds_dwordx4 v[190:191], off
	s_add_i32 m0, s70, 0x2000
	s_add_u32 s70, s64, 0x40000
	v_lshl_add_u64 v[250:251], s[64:65], 0, v[168:169]
	s_addc_u32 s71, s65, 0
	s_add_i32 s61, s61, s12
	global_load_lds_dwordx4 v[250:251], off
	v_lshl_add_u64 v[86:87], s[70:71], 0, v[164:165]
	s_mov_b32 m0, s61
	v_lshl_add_u64 v[224:225], s[66:67], 0, v[162:163]
	global_load_lds_dwordx4 v[86:87], off
	v_lshl_add_u64 v[86:87], s[70:71], 0, v[168:169]
	s_add_i32 m0, s61, 0x2000
	v_lshl_add_u64 v[226:227], s[66:67], 0, v[166:167]
	global_load_lds_dwordx4 v[86:87], off
	s_mov_b32 m0, s73
	s_nop 0
	global_load_lds_dwordx4 v[224:225], off
	s_mov_b32 m0, s74
	s_nop 0
	global_load_lds_dwordx4 v[226:227], off
	s_waitcnt vmcnt(8)
	s_waitcnt lgkmcnt(0)
	s_setprio 0
	s_barrier
	s_waitcnt lgkmcnt(0)
	v_mfma_f32_16x16x32_bf16 v[60:63], v[88:91], v[186:189], v[60:63]
	v_mfma_f32_16x16x32_bf16 v[56:59], v[144:147], v[186:189], v[56:59]
	v_mfma_f32_16x16x32_bf16 v[40:43], v[144:147], v[202:205], v[40:43]
	v_mfma_f32_16x16x32_bf16 v[44:47], v[88:91], v[202:205], v[44:47]
	v_mfma_f32_16x16x32_bf16 v[28:31], v[88:91], v[234:237], v[28:31]
	v_mfma_f32_16x16x32_bf16 v[24:27], v[144:147], v[234:237], v[24:27]
	v_mfma_f32_16x16x32_bf16 v[8:11], v[144:147], v[242:245], v[8:11]
	v_mfma_f32_16x16x32_bf16 v[12:15], v[88:91], v[242:245], v[12:15]
	v_mfma_f32_16x16x32_bf16 v[60:63], v[92:95], v[198:201], v[60:63]
	v_mfma_f32_16x16x32_bf16 v[56:59], v[148:151], v[198:201], v[56:59]
	v_mfma_f32_16x16x32_bf16 v[40:43], v[148:151], v[206:209], v[40:43]
	v_mfma_f32_16x16x32_bf16 v[44:47], v[92:95], v[206:209], v[44:47]
	v_mfma_f32_16x16x32_bf16 v[28:31], v[92:95], v[238:241], v[28:31]
	v_mfma_f32_16x16x32_bf16 v[24:27], v[148:151], v[238:241], v[24:27]
	v_mfma_f32_16x16x32_bf16 v[8:11], v[148:151], v[246:249], v[8:11]
	v_mfma_f32_16x16x32_bf16 v[12:15], v[92:95], v[246:249], v[12:15]
	v_mfma_f32_16x16x32_bf16 v[52:55], v[152:155], v[186:189], v[52:55]
	v_mfma_f32_16x16x32_bf16 v[48:51], v[178:181], v[186:189], v[48:51]
	v_mfma_f32_16x16x32_bf16 v[32:35], v[178:181], v[202:205], v[32:35]
	v_mfma_f32_16x16x32_bf16 v[36:39], v[152:155], v[202:205], v[36:39]
	v_mfma_f32_16x16x32_bf16 v[20:23], v[152:155], v[234:237], v[20:23]
	v_mfma_f32_16x16x32_bf16 v[16:19], v[178:181], v[234:237], v[16:19]
	v_mfma_f32_16x16x32_bf16 v[0:3], v[178:181], v[242:245], v[0:3]
	v_mfma_f32_16x16x32_bf16 v[4:7], v[152:155], v[242:245], v[4:7]
	v_mfma_f32_16x16x32_bf16 v[52:55], v[156:159], v[198:201], v[52:55]
	v_mfma_f32_16x16x32_bf16 v[48:51], v[182:185], v[198:201], v[48:51]
	v_mfma_f32_16x16x32_bf16 v[32:35], v[182:185], v[206:209], v[32:35]
	v_mfma_f32_16x16x32_bf16 v[36:39], v[156:159], v[206:209], v[36:39]
	v_mfma_f32_16x16x32_bf16 v[20:23], v[156:159], v[238:241], v[20:23]
	v_mfma_f32_16x16x32_bf16 v[16:19], v[182:185], v[238:241], v[16:19]
	v_mfma_f32_16x16x32_bf16 v[0:3], v[182:185], v[246:249], v[0:3]
	v_mfma_f32_16x16x32_bf16 v[4:7], v[156:159], v[246:249], v[4:7]
	s_barrier
; #define PG8_STAGE(bufoff, gbase, voff) do { _Pragma("unroll") for (int _i = 0; _i < 2; ++_i) \
;         __builtin_amdgcn_global_load_lds((const unsigned*)((const char*)(gbase) + (voff)[_i]), (LAS unsigned*)(lds + (bufoff) + ldsw + _i * 8192), 16, 0, 0); } while (0)
; #define PG8_LDA(dst, b, h) do { _Pragma("unroll") for (int m = 0; m < 4; ++m) _Pragma("unroll") for (int k = 0; k < 2; ++k) dst[m][k] = *(const LAS bf16x8*)(lds + PG8_SA(b, h) + aoff + m * 2048 + k * 1024); } while (0)
; #define PG8_LDB(dst, b, h) do { _Pragma("unroll") for (int n = 0; n < 2; ++n) _Pragma("unroll") for (int k = 0; k < 2; ++k) dst[n][k] = *(const LAS bf16x8*)(lds + PG8_SB(b, h) + boff + n * 2048 + k * 1024); } while (0)
; #define PG8_MMA(ai, bj, At, Bt) do { __builtin_amdgcn_s_setprio(1); _Pragma("unroll") for (int m = 0; m < 4; ++m) _Pragma("unroll") for (int n = 0; n < 2; ++n) _Pragma("unroll") for (int k = 0; k < 2; ++k) \
;         acc[ai][bj][m][n] = __builtin_amdgcn_mfma_f32_16x16x32_bf16(Bt[n][k], At[m][k], acc[ai][bj][m][n], 0, 0, 0); __builtin_amdgcn_s_setprio(0); } while (0)
; #define PG8_WAIT_V(n) asm volatile("s_waitcnt vmcnt(" #n ")" ::: "memory")
; #define PG8_WAIT_L(n) asm volatile("s_waitcnt lgkmcnt(" #n ")" ::: "memory")
; #define PG8_BAR __builtin_amdgcn_s_barrier()
; #define PG8_SCHED __builtin_amdgcn_sched_barrier(0)
; template <class Epi, class Sched>
; __device__ __forceinline__ void gemm_phase(LAS unsigned char* lds, const Gemm g, const Sched& S, const Epi& E, const int tid) {
;     ...
;             PG8_LDB(B0, 1, 0); PG8_LDB(B1, 1, 1); PG8_SCHED; PG8_LDA(At, 1, 0); PG8_STAGE(PG8_SA(0, 1), a2 + hstep, voffA);
;             PG8_WAIT_V(8); PG8_WAIT_L(0); PG8_BAR; PG8_MMA(0, 0, At, B0); PG8_MMA(0, 1, At, B1); PG8_BAR; PG8_SCHED;
	s_setprio 1
	s_add_i32 s61, 0, 0x18000
	v_add_u32_e32 v81, s61, v216
	s_add_i32 s70, 0, 0x1c000
	ds_read_b128 v[88:91], v81
	ds_read_b128 v[92:95], v81 offset:1024
	ds_read_b128 v[144:147], v81 offset:2048
	ds_read_b128 v[148:151], v81 offset:3072
	v_add_u32_e32 v81, s70, v216
	ds_read_b128 v[152:155], v81
	ds_read_b128 v[156:159], v81 offset:1024
	ds_read_b128 v[178:181], v81 offset:2048
	ds_read_b128 v[182:185], v81 offset:3072
	s_add_u32 s66, s66, 0x40000
	s_addc_u32 s67, s67, 0
	s_mov_b32 m0, s75
	v_lshl_add_u64 v[86:87], s[66:67], 0, v[162:163]
	ds_read_b128 v[186:189], v230 offset:32768
	ds_read_b128 v[198:201], v230 offset:33792
	ds_read_b128 v[202:205], v230 offset:34816
	ds_read_b128 v[206:209], v230 offset:35840
	ds_read_b128 v[234:237], v230 offset:36864
	ds_read_b128 v[238:241], v230 offset:37888
	ds_read_b128 v[242:245], v230 offset:38912
	ds_read_b128 v[246:249], v230 offset:39936
	global_load_lds_dwordx4 v[86:87], off
	v_lshl_add_u64 v[86:87], s[66:67], 0, v[166:167]
	s_mov_b32 m0, s81
	s_nop 0
	global_load_lds_dwordx4 v[86:87], off
	s_waitcnt vmcnt(8)
	s_waitcnt lgkmcnt(0)
	s_setprio 0
	s_barrier
	s_waitcnt lgkmcnt(0)
	v_mfma_f32_16x16x32_bf16 v[140:143], v[88:91], v[186:189], v[140:143]
	v_mfma_f32_16x16x32_bf16 v[136:139], v[144:147], v[186:189], v[136:139]
	v_mfma_f32_16x16x32_bf16 v[120:123], v[144:147], v[202:205], v[120:123]
	v_mfma_f32_16x16x32_bf16 v[124:127], v[88:91], v[202:205], v[124:127]
	v_mfma_f32_16x16x32_bf16 v[108:111], v[88:91], v[234:237], v[108:111]
	v_mfma_f32_16x16x32_bf16 v[104:107], v[144:147], v[234:237], v[104:107]
	v_mfma_f32_16x16x32_bf16 v[76:79], v[144:147], v[242:245], v[76:79]
	v_mfma_f32_16x16x32_bf16 v[82:85], v[88:91], v[242:245], v[82:85]
	v_mfma_f32_16x16x32_bf16 v[140:143], v[92:95], v[198:201], v[140:143]
	v_mfma_f32_16x16x32_bf16 v[136:139], v[148:151], v[198:201], v[136:139]
	v_mfma_f32_16x16x32_bf16 v[120:123], v[148:151], v[206:209], v[120:123]
	v_mfma_f32_16x16x32_bf16 v[124:127], v[92:95], v[206:209], v[124:127]
	v_mfma_f32_16x16x32_bf16 v[108:111], v[92:95], v[238:241], v[108:111]
	v_mfma_f32_16x16x32_bf16 v[104:107], v[148:151], v[238:241], v[104:107]
	v_mfma_f32_16x16x32_bf16 v[76:79], v[148:151], v[246:249], v[76:79]
	v_mfma_f32_16x16x32_bf16 v[84:87], v[92:95], v[246:249], v[82:85]
	v_mfma_f32_16x16x32_bf16 v[132:135], v[152:155], v[186:189], v[132:135]
	v_mfma_f32_16x16x32_bf16 v[128:131], v[178:181], v[186:189], v[128:131]
	v_mfma_f32_16x16x32_bf16 v[112:115], v[178:181], v[202:205], v[112:115]
	v_mfma_f32_16x16x32_bf16 v[116:119], v[152:155], v[202:205], v[116:119]
	v_mfma_f32_16x16x32_bf16 v[100:103], v[152:155], v[234:237], v[100:103]
	v_mfma_f32_16x16x32_bf16 v[96:99], v[178:181], v[234:237], v[96:99]
	v_mfma_f32_16x16x32_bf16 v[64:67], v[178:181], v[242:245], v[64:67]
	v_mfma_f32_16x16x32_bf16 v[68:71], v[152:155], v[242:245], v[68:71]
	v_mfma_f32_16x16x32_bf16 v[132:135], v[156:159], v[198:201], v[132:135]
	v_mfma_f32_16x16x32_bf16 v[128:131], v[182:185], v[198:201], v[128:131]
	v_mfma_f32_16x16x32_bf16 v[112:115], v[182:185], v[206:209], v[112:115]
	v_mfma_f32_16x16x32_bf16 v[116:119], v[156:159], v[206:209], v[116:119]
	v_mfma_f32_16x16x32_bf16 v[100:103], v[156:159], v[238:241], v[100:103]
	v_mfma_f32_16x16x32_bf16 v[96:99], v[182:185], v[238:241], v[96:99]
	v_mfma_f32_16x16x32_bf16 v[64:67], v[182:185], v[246:249], v[64:67]
	v_mfma_f32_16x16x32_bf16 v[68:71], v[156:159], v[246:249], v[68:71]
	s_barrier
; #define PG8_STAGE(bufoff, gbase, voff) do { _Pragma("unroll") for (int _i = 0; _i < 2; ++_i) \
;         __builtin_amdgcn_global_load_lds((const unsigned*)((const char*)(gbase) + (voff)[_i]), (LAS unsigned*)(lds + (bufoff) + ldsw + _i * 8192), 16, 0, 0); } while (0)
; #define PG8_LDA(dst, b, h) do { _Pragma("unroll") for (int m = 0; m < 4; ++m) _Pragma("unroll") for (int k = 0; k < 2; ++k) dst[m][k] = *(const LAS bf16x8*)(lds + PG8_SA(b, h) + aoff + m * 2048 + k * 1024); } while (0)
; #define PG8_MMA(ai, bj, At, Bt) do { __builtin_amdgcn_s_setprio(1); _Pragma("unroll") for (int m = 0; m < 4; ++m) _Pragma("unroll") for (int n = 0; n < 2; ++n) _Pragma("unroll") for (int k = 0; k < 2; ++k) \
;         acc[ai][bj][m][n] = __builtin_amdgcn_mfma_f32_16x16x32_bf16(Bt[n][k], At[m][k], acc[ai][bj][m][n], 0, 0, 0); __builtin_amdgcn_s_setprio(0); } while (0)
; #define PG8_WAIT_V(n) asm volatile("s_waitcnt vmcnt(" #n ")" ::: "memory")
; #define PG8_WAIT_L(n) asm volatile("s_waitcnt lgkmcnt(" #n ")" ::: "memory")
; #define PG8_BAR __builtin_amdgcn_s_barrier()
; #define PG8_SCHED __builtin_amdgcn_sched_barrier(0)
; template <class Epi, class Sched>
; __device__ __forceinline__ void gemm_phase(LAS unsigned char* lds, const Gemm g, const Sched& S, const Epi& E, const int tid) {
;     ...
;             PG8_LDA(At, 1, 1); PG8_STAGE(PG8_SB(1, 0), b3, voffB); PG8_STAGE(PG8_SB(1, 1), b3 + hstep, voffB); PG8_STAGE(PG8_SA(1, 0), a3, voffA);
;             PG8_WAIT_V(8); PG8_WAIT_L(0); PG8_BAR; PG8_MMA(1, 0, At, B0); PG8_MMA(1, 1, At, B1); PG8_BAR; PG8_SCHED;
;         }
;         if (wr == 0) PG8_BAR;
	s_setprio 1
	s_add_i32 s61, s61, s12
	v_lshl_add_u64 v[82:83], v[190:191], 0, s[68:69]
	s_mov_b32 m0, s61
	ds_read_b128 v[186:189], v230 offset:49152
	ds_read_b128 v[198:201], v230 offset:50176
	ds_read_b128 v[202:205], v230 offset:51200
	ds_read_b128 v[206:209], v230 offset:52224
	ds_read_b128 v[234:237], v230 offset:53248
	ds_read_b128 v[238:241], v230 offset:54272
	ds_read_b128 v[242:245], v230 offset:55296
	ds_read_b128 v[246:249], v230 offset:56320
	global_load_lds_dwordx4 v[82:83], off
	s_add_i32 m0, s61, 0x2000
	s_add_u32 s64, s64, 0x40080
	v_lshl_add_u64 v[82:83], v[250:251], 0, s[68:69]
	s_addc_u32 s65, s65, 0
	s_add_i32 s61, s70, s12
	global_load_lds_dwordx4 v[82:83], off
	v_lshl_add_u64 v[82:83], s[64:65], 0, v[164:165]
	s_mov_b32 m0, s61
	s_nop 0
	global_load_lds_dwordx4 v[82:83], off
	v_lshl_add_u64 v[82:83], s[64:65], 0, v[168:169]
	s_add_i32 m0, s61, 0x2000
	s_nop 0
	global_load_lds_dwordx4 v[82:83], off
	v_lshl_add_u64 v[82:83], v[224:225], 0, s[68:69]
	s_mov_b32 m0, s82
	s_nop 0
	global_load_lds_dwordx4 v[82:83], off
	v_lshl_add_u64 v[82:83], v[226:227], 0, s[68:69]
	s_mov_b32 m0, s83
	s_nop 0
	global_load_lds_dwordx4 v[82:83], off
	s_waitcnt vmcnt(8)
	s_waitcnt lgkmcnt(0)
	s_setprio 0
	s_barrier
	s_waitcnt lgkmcnt(0)
	v_mfma_f32_16x16x32_bf16 v[60:63], v[88:91], v[186:189], v[60:63]
	v_mfma_f32_16x16x32_bf16 v[56:59], v[144:147], v[186:189], v[56:59]
	v_mfma_f32_16x16x32_bf16 v[40:43], v[144:147], v[202:205], v[40:43]
	v_mfma_f32_16x16x32_bf16 v[44:47], v[88:91], v[202:205], v[44:47]
	v_mfma_f32_16x16x32_bf16 v[28:31], v[88:91], v[234:237], v[28:31]
	v_mfma_f32_16x16x32_bf16 v[24:27], v[144:147], v[234:237], v[24:27]
	v_mfma_f32_16x16x32_bf16 v[8:11], v[144:147], v[242:245], v[8:11]
	v_mfma_f32_16x16x32_bf16 v[12:15], v[88:91], v[242:245], v[12:15]
	v_mfma_f32_16x16x32_bf16 v[60:63], v[92:95], v[198:201], v[60:63]
	v_mfma_f32_16x16x32_bf16 v[56:59], v[148:151], v[198:201], v[56:59]
	v_mfma_f32_16x16x32_bf16 v[40:43], v[148:151], v[206:209], v[40:43]
	v_mfma_f32_16x16x32_bf16 v[44:47], v[92:95], v[206:209], v[44:47]
	v_mfma_f32_16x16x32_bf16 v[28:31], v[92:95], v[238:241], v[28:31]
	v_mfma_f32_16x16x32_bf16 v[24:27], v[148:151], v[238:241], v[24:27]
	v_mfma_f32_16x16x32_bf16 v[8:11], v[148:151], v[246:249], v[8:11]
	v_mfma_f32_16x16x32_bf16 v[12:15], v[92:95], v[246:249], v[12:15]
	v_mfma_f32_16x16x32_bf16 v[52:55], v[152:155], v[186:189], v[52:55]
	v_mfma_f32_16x16x32_bf16 v[48:51], v[178:181], v[186:189], v[48:51]
	v_mfma_f32_16x16x32_bf16 v[32:35], v[178:181], v[202:205], v[32:35]
	v_mfma_f32_16x16x32_bf16 v[36:39], v[152:155], v[202:205], v[36:39]
	v_mfma_f32_16x16x32_bf16 v[20:23], v[152:155], v[234:237], v[20:23]
	v_mfma_f32_16x16x32_bf16 v[16:19], v[178:181], v[234:237], v[16:19]
	v_mfma_f32_16x16x32_bf16 v[0:3], v[178:181], v[242:245], v[0:3]
	v_mfma_f32_16x16x32_bf16 v[4:7], v[152:155], v[242:245], v[4:7]
	v_mfma_f32_16x16x32_bf16 v[52:55], v[156:159], v[198:201], v[52:55]
	v_mfma_f32_16x16x32_bf16 v[48:51], v[182:185], v[198:201], v[48:51]
	v_mfma_f32_16x16x32_bf16 v[32:35], v[182:185], v[206:209], v[32:35]
	v_mfma_f32_16x16x32_bf16 v[36:39], v[156:159], v[206:209], v[36:39]
	v_mfma_f32_16x16x32_bf16 v[20:23], v[156:159], v[238:241], v[20:23]
	v_mfma_f32_16x16x32_bf16 v[16:19], v[182:185], v[238:241], v[16:19]
	v_mfma_f32_16x16x32_bf16 v[0:3], v[182:185], v[246:249], v[0:3]
	v_mfma_f32_16x16x32_bf16 v[4:7], v[156:159], v[246:249], v[4:7]
	s_barrier
	s_setprio 1
	s_add_i32 s60, s60, 2
	s_add_u32 s6, s6, 0x100
	s_addc_u32 s7, s7, 0
	s_add_u32 s58, s58, 0x100
	s_addc_u32 s59, s59, 0
	s_cmp_gt_u32 s60, 13
	s_cbranch_scc0 .LBB0_266
	s_and_b64 vcc, exec, s[50:51]
	s_cbranch_vccz .LBB0_269
	s_barrier

;     __device__ __forceinline__ Pre prefetch(const Unit& u, int tid) const { return prenorm_load(stats, u.pn * BM, sW + (size_t)(u.pn >> 4) * SW_ROWS + u.pm * BM, tid); }
;     __device__ __forceinline__ Pre prefetch(const Unit& u, int tid) const { return prenorm_load(stats, u.pm * BM, sW + (size_t)(u.pm >> 4) * SW_ROWS + u.pn * BM, tid); }
;     __device__ __forceinline__ Pre prefetch(const Unit& u, int tid) const { return prenorm_load(stats, u.pm * BM, sW + (size_t)(u.pm >> 4) * SW_ROWS + u.pn * BM, tid); }
; #define PG8_STAGE(bufoff, gbase, voff) do { _Pragma("unroll") for (int _i = 0; _i < 2; ++_i) \
;         __builtin_amdgcn_global_load_lds((const unsigned*)((const char*)(gbase) + (voff)[_i]), (LAS unsigned*)(lds + (bufoff) + ldsw + _i * 8192), 16, 0, 0); } while (0)
; #define PG8_LDA(dst, b, h) do { _Pragma("unroll") for (int m = 0; m < 4; ++m) _Pragma("unroll") for (int k = 0; k < 2; ++k) dst[m][k] = *(const LAS bf16x8*)(lds + PG8_SA(b, h) + aoff + m * 2048 + k * 1024); } while (0)
; #define PG8_WAIT_V(n) asm volatile("s_waitcnt vmcnt(" #n ")" ::: "memory")
; #define PG8_BAR __builtin_amdgcn_s_barrier()
; template <class Epi, class Sched>
; __device__ __forceinline__ void gemm_phase(LAS unsigned char* lds, const Gemm g, const Sched& S, const Epi& E, const int tid) {
;     ...
;         const char* nA = has_next ? (const char*)g.A + (size_t)nxt.pm * tstep : cA; const char* nB = has_next ? (const char*)g.Bt + (size_t)nxt.pn * tstep : cB;
;         const typename Epi::Pre pre = E.prefetch(cur, tid);
;         for (int t = 0; t < nt; t += 2) {
;             const bool last = (t == nt - 2);
;             const char* a1 = cA + (size_t)(t + 1) * kstep;
;             const char* a2 = last ? nA : cA + (size_t)(t + 2) * kstep; const char* b2 = last ? nB : cB + (size_t)(t + 2) * kstep;
;             const char* a3 = a2 + kstep; const char* b3 = b2 + kstep;
;             PG8_LDB(B0, 0, 0); PG8_LDB(B1, 0, 1); PG8_SCHED; PG8_LDA(At, 0, 0); PG8_STAGE(PG8_SA(1, 1), a1 + hstep, voffA);
;             PG8_WAIT_V(8); PG8_WAIT_L(0); PG8_BAR; PG8_MMA(0, 0, At, B0); PG8_MMA(0, 1, At, B1); PG8_BAR; PG8_SCHED;
;             PG8_LDA(At, 0, 1); PG8_STAGE(PG8_SB(0, 0), b2, voffB); PG8_STAGE(PG8_SB(0, 1), b2 + hstep, voffB); PG8_STAGE(PG8_SA(0, 0), a2, voffA);
;             PG8_WAIT_V(8); PG8_WAIT_L(0); PG8_BAR; PG8_MMA(1, 0, At, B0); PG8_MMA(1, 1, At, B1); PG8_BAR; PG8_SCHED;
.LBB0_325:
	s_or_b64 exec, exec, s[50:51]
	s_ashr_i32 s39, s38, 31
	s_lshl_b64 s[50:51], s[38:39], 19
	s_add_u32 s50, s85, s50
	s_addc_u32 s51, s86, s51
	s_and_b64 s[54:55], s[4:5], exec
	s_cselect_b32 s39, s51, s63
	s_cselect_b32 s74, s50, s62
	s_ashr_i32 s23, s22, 31
	s_lshl_b64 s[54:55], s[22:23], 19
	s_add_u32 s54, s46, s54
	s_addc_u32 s55, s47, s55
	s_and_b64 s[66:67], s[4:5], exec
	s_cselect_b32 s23, s55, s65
	s_cselect_b32 s75, s54, s64
	s_add_u32 s62, s62, 0x40080
	s_addc_u32 s63, s63, 0
	s_add_u32 s78, s64, 0x100
	s_addc_u32 s79, s65, 0
	s_mov_b32 s81, -2
	s_waitcnt lgkmcnt(0)
	s_add_u32 s64, s62, 0xfffc0080
	s_addc_u32 s65, s63, -1
	s_add_i32 s82, 0, 0x10000
	s_cmp_eq_u32 s81, 12
	s_cselect_b32 s67, s39, s65
	s_cselect_b32 s66, s74, s64
	v_add_u32_e32 v69, s82, v154
	s_cselect_b32 s65, s23, s79
	s_cselect_b32 s64, s75, s78
	s_add_i32 s90, 0, 0x14000
	ds_read_b128 v[70:73], v69
	ds_read_b128 v[74:77], v69 offset:1024
	ds_read_b128 v[172:175], v69 offset:2048
	ds_read_b128 v[176:179], v69 offset:3072
	v_add_u32_e32 v69, s90, v154
	ds_read_b128 v[180:183], v69
	ds_read_b128 v[184:187], v69 offset:1024
	ds_read_b128 v[188:191], v69 offset:2048
	ds_read_b128 v[198:201], v69 offset:3072
	v_lshl_add_u64 v[78:79], s[62:63], 0, v[144:145]
	s_add_i32 m0, s53, 0xc000
	ds_read_b128 v[202:205], v171
	ds_read_b128 v[206:209], v171 offset:1024
	ds_read_b128 v[210:213], v171 offset:2048
	ds_read_b128 v[214:217], v171 offset:3072
	ds_read_b128 v[218:221], v171 offset:4096
	ds_read_b128 v[230:233], v171 offset:5120
	ds_read_b128 v[234:237], v171 offset:6144
	ds_read_b128 v[238:241], v171 offset:7168
	global_load_lds_dwordx4 v[78:79], off
	v_lshl_add_u64 v[78:79], s[62:63], 0, v[146:147]
	s_add_i32 m0, s53, 0xe000
	s_nop 0
	global_load_lds_dwordx4 v[78:79], off
	s_waitcnt vmcnt(8)
	s_waitcnt lgkmcnt(0)
	s_setprio 0
	s_barrier
	s_waitcnt lgkmcnt(0)
	v_mfma_f32_16x16x32_bf16 v[140:143], v[70:73], v[202:205], 0
	v_mfma_f32_16x16x32_bf16 v[136:139], v[172:175], v[202:205], 0
	v_mfma_f32_16x16x32_bf16 v[128:131], v[172:175], v[210:213], 0
	v_mfma_f32_16x16x32_bf16 v[132:135], v[70:73], v[210:213], 0
	v_mfma_f32_16x16x32_bf16 v[116:119], v[70:73], v[218:221], 0
	v_mfma_f32_16x16x32_bf16 v[112:115], v[172:175], v[218:221], 0
	v_mfma_f32_16x16x32_bf16 v[96:99], v[172:175], v[234:237], 0
	v_mfma_f32_16x16x32_bf16 v[100:103], v[70:73], v[234:237], 0
	v_mfma_f32_16x16x32_bf16 v[140:143], v[74:77], v[206:209], v[140:143]
	v_mfma_f32_16x16x32_bf16 v[136:139], v[176:179], v[206:209], v[136:139]
	v_mfma_f32_16x16x32_bf16 v[128:131], v[176:179], v[214:217], v[128:131]
	v_mfma_f32_16x16x32_bf16 v[132:135], v[74:77], v[214:217], v[132:135]
	v_mfma_f32_16x16x32_bf16 v[116:119], v[74:77], v[230:233], v[116:119]
	v_mfma_f32_16x16x32_bf16 v[112:115], v[176:179], v[230:233], v[112:115]
	v_mfma_f32_16x16x32_bf16 v[96:99], v[176:179], v[238:241], v[96:99]
	v_mfma_f32_16x16x32_bf16 v[100:103], v[74:77], v[238:241], v[100:103]
	v_mfma_f32_16x16x32_bf16 v[124:127], v[180:183], v[202:205], 0
	v_mfma_f32_16x16x32_bf16 v[120:123], v[188:191], v[202:205], 0
	v_mfma_f32_16x16x32_bf16 v[104:107], v[188:191], v[210:213], 0
	v_mfma_f32_16x16x32_bf16 v[108:111], v[180:183], v[210:213], 0
	v_mfma_f32_16x16x32_bf16 v[92:95], v[180:183], v[218:221], 0
	v_mfma_f32_16x16x32_bf16 v[88:91], v[188:191], v[218:221], 0
	v_mfma_f32_16x16x32_bf16 v[78:81], v[188:191], v[234:237], 0
	v_mfma_f32_16x16x32_bf16 v[84:87], v[180:183], v[234:237], 0
	v_mfma_f32_16x16x32_bf16 v[124:127], v[184:187], v[206:209], v[124:127]
	v_mfma_f32_16x16x32_bf16 v[120:123], v[198:201], v[206:209], v[120:123]
	v_mfma_f32_16x16x32_bf16 v[104:107], v[198:201], v[214:217], v[104:107]
	v_mfma_f32_16x16x32_bf16 v[108:111], v[184:187], v[214:217], v[108:111]
	v_mfma_f32_16x16x32_bf16 v[92:95], v[184:187], v[230:233], v[92:95]
	v_mfma_f32_16x16x32_bf16 v[88:91], v[198:201], v[230:233], v[88:91]
	v_mfma_f32_16x16x32_bf16 v[78:81], v[198:201], v[238:241], v[78:81]
	v_mfma_f32_16x16x32_bf16 v[84:87], v[184:187], v[238:241], v[84:87]
	s_barrier
	s_setprio 1
	s_add_i32 s82, s82, s52
	v_lshl_add_u64 v[224:225], s[64:65], 0, v[164:165]
	s_mov_b32 m0, s82
	ds_read_b128 v[202:205], v171 offset:16384
	ds_read_b128 v[206:209], v171 offset:17408
	ds_read_b128 v[210:213], v171 offset:18432
	ds_read_b128 v[214:217], v171 offset:19456
	ds_read_b128 v[218:221], v171 offset:20480
	ds_read_b128 v[230:233], v171 offset:21504
	ds_read_b128 v[234:237], v171 offset:22528
	ds_read_b128 v[238:241], v171 offset:23552
	global_load_lds_dwordx4 v[224:225], off
	s_add_i32 m0, s82, 0x2000
	s_add_u32 s82, s64, 0x40000
	v_lshl_add_u64 v[226:227], s[64:65], 0, v[168:169]
	s_addc_u32 s83, s65, 0
	s_add_i32 s90, s90, s52
	global_load_lds_dwordx4 v[226:227], off
	v_lshl_add_u64 v[82:83], s[82:83], 0, v[164:165]
	s_mov_b32 m0, s90
	v_lshl_add_u64 v[242:243], s[66:67], 0, v[162:163]
	global_load_lds_dwordx4 v[82:83], off
	v_lshl_add_u64 v[82:83], s[82:83], 0, v[168:169]
	s_add_i32 m0, s90, 0x2000
	v_lshl_add_u64 v[244:245], s[66:67], 0, v[166:167]
	global_load_lds_dwordx4 v[82:83], off
	s_mov_b32 m0, s53
	s_nop 0
	global_load_lds_dwordx4 v[242:243], off
	s_mov_b32 m0, s56
	s_nop 0
	global_load_lds_dwordx4 v[244:245], off
	s_waitcnt vmcnt(8)
	s_waitcnt lgkmcnt(0)
	s_setprio 0
	s_barrier
; #define PG8_STAGE(bufoff, gbase, voff) do { _Pragma("unroll") for (int _i = 0; _i < 2; ++_i) \
;         __builtin_amdgcn_global_load_lds((const unsigned*)((const char*)(gbase) + (voff)[_i]), (LAS unsigned*)(lds + (bufoff) + ldsw + _i * 8192), 16, 0, 0); } while (0)
; #define PG8_LDA(dst, b, h) do { _Pragma("unroll") for (int m = 0; m < 4; ++m) _Pragma("unroll") for (int k = 0; k < 2; ++k) dst[m][k] = *(const LAS bf16x8*)(lds + PG8_SA(b, h) + aoff + m * 2048 + k * 1024); } while (0)
; #define PG8_LDB(dst, b, h) do { _Pragma("unroll") for (int n = 0; n < 2; ++n) _Pragma("unroll") for (int k = 0; k < 2; ++k) dst[n][k] = *(const LAS bf16x8*)(lds + PG8_SB(b, h) + boff + n * 2048 + k * 1024); } while (0)
; #define PG8_MMA(ai, bj, At, Bt) do { __builtin_amdgcn_s_setprio(1); _Pragma("unroll") for (int m = 0; m < 4; ++m) _Pragma("unroll") for (int n = 0; n < 2; ++n) _Pragma("unroll") for (int k = 0; k < 2; ++k) \
;         acc[ai][bj][m][n] = __builtin_amdgcn_mfma_f32_16x16x32_bf16(Bt[n][k], At[m][k], acc[ai][bj][m][n], 0, 0, 0); __builtin_amdgcn_s_setprio(0); } while (0)
; #define PG8_WAIT_V(n) asm volatile("s_waitcnt vmcnt(" #n ")" ::: "memory")
; #define PG8_WAIT_L(n) asm volatile("s_waitcnt lgkmcnt(" #n ")" ::: "memory")
; #define PG8_BAR __builtin_amdgcn_s_barrier()
; #define PG8_SCHED __builtin_amdgcn_sched_barrier(0)
; template <class Epi, class Sched>
; __device__ __forceinline__ void gemm_phase(LAS unsigned char* lds, const Gemm g, const Sched& S, const Epi& E, const int tid) {
;     ...
;             PG8_WAIT_V(8); PG8_WAIT_L(0); PG8_BAR; PG8_MMA(1, 0, At, B0); PG8_MMA(1, 1, At, B1); PG8_BAR; PG8_SCHED;
;             PG8_LDB(B0, 1, 0); PG8_LDB(B1, 1, 1); PG8_SCHED; PG8_LDA(At, 1, 0); PG8_STAGE(PG8_SA(0, 1), a2 + hstep, voffA);
;             PG8_WAIT_V(8); PG8_WAIT_L(0); PG8_BAR; PG8_MMA(0, 0, At, B0); PG8_MMA(0, 1, At, B1); PG8_BAR; PG8_SCHED;
	s_waitcnt lgkmcnt(0)
	v_mfma_f32_16x16x32_bf16 v[60:63], v[70:73], v[202:205], 0
	v_mfma_f32_16x16x32_bf16 v[56:59], v[172:175], v[202:205], 0
	v_mfma_f32_16x16x32_bf16 v[44:47], v[172:175], v[210:213], 0
	v_mfma_f32_16x16x32_bf16 v[52:55], v[70:73], v[210:213], 0
	v_mfma_f32_16x16x32_bf16 v[28:31], v[70:73], v[218:221], 0
	v_mfma_f32_16x16x32_bf16 v[24:27], v[172:175], v[218:221], 0
	v_mfma_f32_16x16x32_bf16 v[8:11], v[172:175], v[234:237], 0
	v_mfma_f32_16x16x32_bf16 v[16:19], v[70:73], v[234:237], 0
	v_mfma_f32_16x16x32_bf16 v[60:63], v[74:77], v[206:209], v[60:63]
	v_mfma_f32_16x16x32_bf16 v[56:59], v[176:179], v[206:209], v[56:59]
	v_mfma_f32_16x16x32_bf16 v[44:47], v[176:179], v[214:217], v[44:47]
	v_mfma_f32_16x16x32_bf16 v[52:55], v[74:77], v[214:217], v[52:55]
	v_mfma_f32_16x16x32_bf16 v[28:31], v[74:77], v[230:233], v[28:31]
	v_mfma_f32_16x16x32_bf16 v[24:27], v[176:179], v[230:233], v[24:27]
	v_mfma_f32_16x16x32_bf16 v[8:11], v[176:179], v[238:241], v[8:11]
	v_mfma_f32_16x16x32_bf16 v[16:19], v[74:77], v[238:241], v[16:19]
	v_mfma_f32_16x16x32_bf16 v[48:51], v[180:183], v[202:205], 0
	v_mfma_f32_16x16x32_bf16 v[40:43], v[188:191], v[202:205], 0
	v_mfma_f32_16x16x32_bf16 v[32:35], v[188:191], v[210:213], 0
	v_mfma_f32_16x16x32_bf16 v[36:39], v[180:183], v[210:213], 0
	v_mfma_f32_16x16x32_bf16 v[20:23], v[180:183], v[218:221], 0
	v_mfma_f32_16x16x32_bf16 v[12:15], v[188:191], v[218:221], 0
	v_mfma_f32_16x16x32_bf16 v[0:3], v[188:191], v[234:237], 0
	v_mfma_f32_16x16x32_bf16 v[4:7], v[180:183], v[234:237], 0
	v_mfma_f32_16x16x32_bf16 v[48:51], v[184:187], v[206:209], v[48:51]
	v_mfma_f32_16x16x32_bf16 v[40:43], v[198:201], v[206:209], v[40:43]
	v_mfma_f32_16x16x32_bf16 v[32:35], v[198:201], v[214:217], v[32:35]
	v_mfma_f32_16x16x32_bf16 v[36:39], v[184:187], v[214:217], v[36:39]
	v_mfma_f32_16x16x32_bf16 v[20:23], v[184:187], v[230:233], v[20:23]
	v_mfma_f32_16x16x32_bf16 v[12:15], v[198:201], v[230:233], v[12:15]
	v_mfma_f32_16x16x32_bf16 v[0:3], v[198:201], v[238:241], v[0:3]
	v_mfma_f32_16x16x32_bf16 v[4:7], v[184:187], v[238:241], v[4:7]
	s_barrier
	s_setprio 1
	s_add_i32 s82, 0, 0x18000
	v_add_u32_e32 v69, s82, v154
	s_add_i32 s83, 0, 0x1c000
	ds_read_b128 v[70:73], v69
	ds_read_b128 v[74:77], v69 offset:1024
	ds_read_b128 v[172:175], v69 offset:2048
	ds_read_b128 v[176:179], v69 offset:3072
	v_add_u32_e32 v69, s83, v154
	ds_read_b128 v[180:183], v69
	ds_read_b128 v[184:187], v69 offset:1024
	ds_read_b128 v[188:191], v69 offset:2048
	ds_read_b128 v[198:201], v69 offset:3072
	s_add_u32 s66, s66, 0x40000
	s_addc_u32 s67, s67, 0
	s_mov_b32 m0, s57
	v_lshl_add_u64 v[82:83], s[66:67], 0, v[162:163]
	ds_read_b128 v[202:205], v171 offset:32768
	ds_read_b128 v[206:209], v171 offset:33792
	ds_read_b128 v[210:213], v171 offset:34816
	ds_read_b128 v[214:217], v171 offset:35840
	ds_read_b128 v[218:221], v171 offset:36864
	ds_read_b128 v[230:233], v171 offset:37888
	ds_read_b128 v[234:237], v171 offset:38912
	ds_read_b128 v[238:241], v171 offset:39936
	global_load_lds_dwordx4 v[82:83], off
	v_lshl_add_u64 v[82:83], s[66:67], 0, v[166:167]
	s_mov_b32 m0, s58
	s_nop 0
	global_load_lds_dwordx4 v[82:83], off
	s_waitcnt vmcnt(8)
	s_waitcnt lgkmcnt(0)
	s_setprio 0
	s_barrier
	s_waitcnt lgkmcnt(0)
	v_mfma_f32_16x16x32_bf16 v[140:143], v[70:73], v[202:205], v[140:143]
	v_mfma_f32_16x16x32_bf16 v[136:139], v[172:175], v[202:205], v[136:139]
	v_mfma_f32_16x16x32_bf16 v[128:131], v[172:175], v[210:213], v[128:131]
	v_mfma_f32_16x16x32_bf16 v[132:135], v[70:73], v[210:213], v[132:135]
	v_mfma_f32_16x16x32_bf16 v[116:119], v[70:73], v[218:221], v[116:119]
	v_mfma_f32_16x16x32_bf16 v[112:115], v[172:175], v[218:221], v[112:115]
	v_mfma_f32_16x16x32_bf16 v[96:99], v[172:175], v[234:237], v[96:99]
	v_mfma_f32_16x16x32_bf16 v[100:103], v[70:73], v[234:237], v[100:103]
	v_mfma_f32_16x16x32_bf16 v[140:143], v[74:77], v[206:209], v[140:143]
	v_mfma_f32_16x16x32_bf16 v[136:139], v[176:179], v[206:209], v[136:139]
	v_mfma_f32_16x16x32_bf16 v[128:131], v[176:179], v[214:217], v[128:131]
	v_mfma_f32_16x16x32_bf16 v[132:135], v[74:77], v[214:217], v[132:135]
	v_mfma_f32_16x16x32_bf16 v[116:119], v[74:77], v[230:233], v[116:119]
	v_mfma_f32_16x16x32_bf16 v[112:115], v[176:179], v[230:233], v[112:115]
	v_mfma_f32_16x16x32_bf16 v[96:99], v[176:179], v[238:241], v[96:99]
	v_mfma_f32_16x16x32_bf16 v[100:103], v[74:77], v[238:241], v[100:103]
	v_mfma_f32_16x16x32_bf16 v[124:127], v[180:183], v[202:205], v[124:127]
	v_mfma_f32_16x16x32_bf16 v[120:123], v[188:191], v[202:205], v[120:123]
	v_mfma_f32_16x16x32_bf16 v[104:107], v[188:191], v[210:213], v[104:107]
	v_mfma_f32_16x16x32_bf16 v[108:111], v[180:183], v[210:213], v[108:111]
	v_mfma_f32_16x16x32_bf16 v[92:95], v[180:183], v[218:221], v[92:95]
	v_mfma_f32_16x16x32_bf16 v[88:91], v[188:191], v[218:221], v[88:91]
	v_mfma_f32_16x16x32_bf16 v[78:81], v[188:191], v[234:237], v[78:81]
	v_mfma_f32_16x16x32_bf16 v[82:85], v[180:183], v[234:237], v[84:87]
	v_mfma_f32_16x16x32_bf16 v[124:127], v[184:187], v[206:209], v[124:127]
	v_mfma_f32_16x16x32_bf16 v[120:123], v[198:201], v[206:209], v[120:123]
	v_mfma_f32_16x16x32_bf16 v[104:107], v[198:201], v[214:217], v[104:107]
	v_mfma_f32_16x16x32_bf16 v[108:111], v[184:187], v[214:217], v[108:111]
	v_mfma_f32_16x16x32_bf16 v[92:95], v[184:187], v[230:233], v[92:95]
	v_mfma_f32_16x16x32_bf16 v[88:91], v[198:201], v[230:233], v[88:91]
	v_mfma_f32_16x16x32_bf16 v[80:83], v[198:201], v[238:241], v[78:81]
	v_mfma_f32_16x16x32_bf16 v[84:87], v[184:187], v[238:241], v[82:85]
	s_barrier
; #define PG8_STAGE(bufoff, gbase, voff) do { _Pragma("unroll") for (int _i = 0; _i < 2; ++_i) \
;         __builtin_amdgcn_global_load_lds((const unsigned*)((const char*)(gbase) + (voff)[_i]), (LAS unsigned*)(lds + (bufoff) + ldsw + _i * 8192), 16, 0, 0); } while (0)
; #define PG8_LDA(dst, b, h) do { _Pragma("unroll") for (int m = 0; m < 4; ++m) _Pragma("unroll") for (int k = 0; k < 2; ++k) dst[m][k] = *(const LAS bf16x8*)(lds + PG8_SA(b, h) + aoff + m * 2048 + k * 1024); } while (0)
; #define PG8_LDB(dst, b, h) do { _Pragma("unroll") for (int n = 0; n < 2; ++n) _Pragma("unroll") for (int k = 0; k < 2; ++k) dst[n][k] = *(const LAS bf16x8*)(lds + PG8_SB(b, h) + boff + n * 2048 + k * 1024); } while (0)
; #define PG8_WAIT_V(n) asm volatile("s_waitcnt vmcnt(" #n ")" ::: "memory")
; #define PG8_BAR __builtin_amdgcn_s_barrier()
; template <class Epi, class Sched>
; __device__ __forceinline__ void gemm_phase(LAS unsigned char* lds, const Gemm g, const Sched& S, const Epi& E, const int tid) {
;     ...
;         for (int t = 0; t < nt; t += 2) {
;             const bool last = (t == nt - 2);
;             const char* a1 = cA + (size_t)(t + 1) * kstep;
;             const char* a2 = last ? nA : cA + (size_t)(t + 2) * kstep; const char* b2 = last ? nB : cB + (size_t)(t + 2) * kstep;
;             const char* a3 = a2 + kstep; const char* b3 = b2 + kstep;
;             PG8_LDB(B0, 0, 0); PG8_LDB(B1, 0, 1); PG8_SCHED; PG8_LDA(At, 0, 0); PG8_STAGE(PG8_SA(1, 1), a1 + hstep, voffA);
;             PG8_WAIT_V(8); PG8_WAIT_L(0); PG8_BAR; PG8_MMA(0, 0, At, B0); PG8_MMA(0, 1, At, B1); PG8_BAR; PG8_SCHED;
;             PG8_LDA(At, 0, 1); PG8_STAGE(PG8_SB(0, 0), b2, voffB); PG8_STAGE(PG8_SB(0, 1), b2 + hstep, voffB); PG8_STAGE(PG8_SA(0, 0), a2, voffA);
;             PG8_WAIT_V(8); PG8_WAIT_L(0); PG8_BAR; PG8_MMA(1, 0, At, B0); PG8_MMA(1, 1, At, B1); PG8_BAR; PG8_SCHED;
;             PG8_LDB(B0, 1, 0); PG8_LDB(B1, 1, 1); PG8_SCHED; PG8_LDA(At, 1, 0); PG8_STAGE(PG8_SA(0, 1), a2 + hstep, voffA);
;             PG8_WAIT_V(8); PG8_WAIT_L(0); PG8_BAR; PG8_MMA(0, 0, At, B0); PG8_MMA(0, 1, At, B1); PG8_BAR; PG8_SCHED;
;             PG8_LDA(At, 1, 1); PG8_STAGE(PG8_SB(1, 0), b3, voffB); PG8_STAGE(PG8_SB(1, 1), b3 + hstep, voffB); PG8_STAGE(PG8_SA(1, 0), a3, voffA);
;             PG8_WAIT_V(8); PG8_WAIT_L(0); PG8_BAR; PG8_MMA(1, 0, At, B0); PG8_MMA(1, 1, At, B1); PG8_BAR; PG8_SCHED;
	s_setprio 1
	s_add_i32 s66, s82, s52
	v_lshl_add_u64 v[78:79], v[224:225], 0, s[68:69]
	s_mov_b32 m0, s66
	ds_read_b128 v[202:205], v171 offset:49152
	ds_read_b128 v[206:209], v171 offset:50176
	ds_read_b128 v[210:213], v171 offset:51200
	ds_read_b128 v[214:217], v171 offset:52224
	ds_read_b128 v[218:221], v171 offset:53248
	ds_read_b128 v[230:233], v171 offset:54272
	ds_read_b128 v[234:237], v171 offset:55296
	ds_read_b128 v[238:241], v171 offset:56320
	global_load_lds_dwordx4 v[78:79], off
	s_add_i32 m0, s66, 0x2000
	s_add_u32 s64, s64, 0x40080
	v_lshl_add_u64 v[78:79], v[226:227], 0, s[68:69]
	s_addc_u32 s65, s65, 0
	s_add_i32 s66, s83, s52
	global_load_lds_dwordx4 v[78:79], off
	v_lshl_add_u64 v[78:79], s[64:65], 0, v[164:165]
	s_mov_b32 m0, s66
	s_nop 0
	global_load_lds_dwordx4 v[78:79], off
	v_lshl_add_u64 v[78:79], s[64:65], 0, v[168:169]
	s_add_i32 m0, s66, 0x2000
	s_nop 0
	global_load_lds_dwordx4 v[78:79], off
	v_lshl_add_u64 v[78:79], v[242:243], 0, s[68:69]
	s_mov_b32 m0, s61
	s_nop 0
	global_load_lds_dwordx4 v[78:79], off
	v_lshl_add_u64 v[78:79], v[244:245], 0, s[68:69]
	s_mov_b32 m0, s70
	s_nop 0
	global_load_lds_dwordx4 v[78:79], off
	s_waitcnt vmcnt(8)
	s_waitcnt lgkmcnt(0)
	s_setprio 0
	s_barrier
	s_waitcnt lgkmcnt(0)
	v_mfma_f32_16x16x32_bf16 v[60:63], v[70:73], v[202:205], v[60:63]
	v_mfma_f32_16x16x32_bf16 v[56:59], v[172:175], v[202:205], v[56:59]
	v_mfma_f32_16x16x32_bf16 v[44:47], v[172:175], v[210:213], v[44:47]
	v_mfma_f32_16x16x32_bf16 v[52:55], v[70:73], v[210:213], v[52:55]
	v_mfma_f32_16x16x32_bf16 v[28:31], v[70:73], v[218:221], v[28:31]
	v_mfma_f32_16x16x32_bf16 v[24:27], v[172:175], v[218:221], v[24:27]
	v_mfma_f32_16x16x32_bf16 v[8:11], v[172:175], v[234:237], v[8:11]
	v_mfma_f32_16x16x32_bf16 v[16:19], v[70:73], v[234:237], v[16:19]
	v_mfma_f32_16x16x32_bf16 v[60:63], v[74:77], v[206:209], v[60:63]
	v_mfma_f32_16x16x32_bf16 v[56:59], v[176:179], v[206:209], v[56:59]
	v_mfma_f32_16x16x32_bf16 v[44:47], v[176:179], v[214:217], v[44:47]
	v_mfma_f32_16x16x32_bf16 v[52:55], v[74:77], v[214:217], v[52:55]
	v_mfma_f32_16x16x32_bf16 v[28:31], v[74:77], v[230:233], v[28:31]
	v_mfma_f32_16x16x32_bf16 v[24:27], v[176:179], v[230:233], v[24:27]
	v_mfma_f32_16x16x32_bf16 v[8:11], v[176:179], v[238:241], v[8:11]
	v_mfma_f32_16x16x32_bf16 v[16:19], v[74:77], v[238:241], v[16:19]
	v_mfma_f32_16x16x32_bf16 v[48:51], v[180:183], v[202:205], v[48:51]
	v_mfma_f32_16x16x32_bf16 v[40:43], v[188:191], v[202:205], v[40:43]
	v_mfma_f32_16x16x32_bf16 v[32:35], v[188:191], v[210:213], v[32:35]
	v_mfma_f32_16x16x32_bf16 v[36:39], v[180:183], v[210:213], v[36:39]
	v_mfma_f32_16x16x32_bf16 v[20:23], v[180:183], v[218:221], v[20:23]
	v_mfma_f32_16x16x32_bf16 v[12:15], v[188:191], v[218:221], v[12:15]
	v_mfma_f32_16x16x32_bf16 v[0:3], v[188:191], v[234:237], v[0:3]
	v_mfma_f32_16x16x32_bf16 v[4:7], v[180:183], v[234:237], v[4:7]
	v_mfma_f32_16x16x32_bf16 v[48:51], v[184:187], v[206:209], v[48:51]
	v_mfma_f32_16x16x32_bf16 v[40:43], v[198:201], v[206:209], v[40:43]
	v_mfma_f32_16x16x32_bf16 v[32:35], v[198:201], v[214:217], v[32:35]
	v_mfma_f32_16x16x32_bf16 v[36:39], v[184:187], v[214:217], v[36:39]
	v_mfma_f32_16x16x32_bf16 v[20:23], v[184:187], v[230:233], v[20:23]
	v_mfma_f32_16x16x32_bf16 v[12:15], v[198:201], v[230:233], v[12:15]
	v_mfma_f32_16x16x32_bf16 v[0:3], v[198:201], v[238:241], v[0:3]
	v_mfma_f32_16x16x32_bf16 v[4:7], v[184:187], v[238:241], v[4:7]
	s_barrier
	s_setprio 1
	s_add_i32 s81, s81, 2
	s_add_u32 s62, s62, 0x100
	s_addc_u32 s63, s63, 0
	s_add_u32 s78, s78, 0x100
	s_addc_u32 s79, s79, 0
	s_cmp_gt_u32 s81, 13
.LBB0_326:
	s_add_u32 s64, s62, 0xfffc0080
	s_addc_u32 s65, s63, -1
	s_add_i32 s82, 0, 0x10000
	s_cmp_eq_u32 s81, 12
	s_cselect_b32 s67, s39, s65
	s_cselect_b32 s66, s74, s64
	v_add_u32_e32 v69, s82, v154
	s_cselect_b32 s65, s23, s79
	s_cselect_b32 s64, s75, s78
	s_add_i32 s90, 0, 0x14000
	ds_read_b128 v[70:73], v69
	ds_read_b128 v[74:77], v69 offset:1024
	ds_read_b128 v[172:175], v69 offset:2048
	ds_read_b128 v[176:179], v69 offset:3072
	v_add_u32_e32 v69, s90, v154
	ds_read_b128 v[180:183], v69
	ds_read_b128 v[184:187], v69 offset:1024
	ds_read_b128 v[188:191], v69 offset:2048
	ds_read_b128 v[198:201], v69 offset:3072
	v_lshl_add_u64 v[78:79], s[62:63], 0, v[144:145]
	s_add_i32 m0, s53, 0xc000
	ds_read_b128 v[202:205], v171
	ds_read_b128 v[206:209], v171 offset:1024
	ds_read_b128 v[210:213], v171 offset:2048
	ds_read_b128 v[214:217], v171 offset:3072
	ds_read_b128 v[218:221], v171 offset:4096
	ds_read_b128 v[230:233], v171 offset:5120
	ds_read_b128 v[234:237], v171 offset:6144
	ds_read_b128 v[238:241], v171 offset:7168
	global_load_lds_dwordx4 v[78:79], off
	v_lshl_add_u64 v[78:79], s[62:63], 0, v[146:147]
	s_add_i32 m0, s53, 0xe000
	s_nop 0
	global_load_lds_dwordx4 v[78:79], off
	s_waitcnt vmcnt(8)
	s_waitcnt lgkmcnt(0)
	s_setprio 0
	s_barrier
; #define PG8_STAGE(bufoff, gbase, voff) do { _Pragma("unroll") for (int _i = 0; _i < 2; ++_i) \
;         __builtin_amdgcn_global_load_lds((const unsigned*)((const char*)(gbase) + (voff)[_i]), (LAS unsigned*)(lds + (bufoff) + ldsw + _i * 8192), 16, 0, 0); } while (0)
; #define PG8_LDA(dst, b, h) do { _Pragma("unroll") for (int m = 0; m < 4; ++m) _Pragma("unroll") for (int k = 0; k < 2; ++k) dst[m][k] = *(const LAS bf16x8*)(lds + PG8_SA(b, h) + aoff + m * 2048 + k * 1024); } while (0)
; #define PG8_MMA(ai, bj, At, Bt) do { __builtin_amdgcn_s_setprio(1); _Pragma("unroll") for (int m = 0; m < 4; ++m) _Pragma("unroll") for (int n = 0; n < 2; ++n) _Pragma("unroll") for (int k = 0; k < 2; ++k) \
;         acc[ai][bj][m][n] = __builtin_amdgcn_mfma_f32_16x16x32_bf16(Bt[n][k], At[m][k], acc[ai][bj][m][n], 0, 0, 0); __builtin_amdgcn_s_setprio(0); } while (0)
; #define PG8_WAIT_V(n) asm volatile("s_waitcnt vmcnt(" #n ")" ::: "memory")
; #define PG8_WAIT_L(n) asm volatile("s_waitcnt lgkmcnt(" #n ")" ::: "memory")
; #define PG8_BAR __builtin_amdgcn_s_barrier()
; #define PG8_SCHED __builtin_amdgcn_sched_barrier(0)
; template <class Epi, class Sched>
; __device__ __forceinline__ void gemm_phase(LAS unsigned char* lds, const Gemm g, const Sched& S, const Epi& E, const int tid) {
;     ...
;             PG8_WAIT_V(8); PG8_WAIT_L(0); PG8_BAR; PG8_MMA(0, 0, At, B0); PG8_MMA(0, 1, At, B1); PG8_BAR; PG8_SCHED;
;             PG8_LDA(At, 0, 1); PG8_STAGE(PG8_SB(0, 0), b2, voffB); PG8_STAGE(PG8_SB(0, 1), b2 + hstep, voffB); PG8_STAGE(PG8_SA(0, 0), a2, voffA);
;             PG8_WAIT_V(8); PG8_WAIT_L(0); PG8_BAR; PG8_MMA(1, 0, At, B0); PG8_MMA(1, 1, At, B1); PG8_BAR; PG8_SCHED;
	s_waitcnt lgkmcnt(0)
	v_mfma_f32_16x16x32_bf16 v[140:143], v[70:73], v[202:205], v[140:143]
	v_mfma_f32_16x16x32_bf16 v[136:139], v[172:175], v[202:205], v[136:139]
	v_mfma_f32_16x16x32_bf16 v[128:131], v[172:175], v[210:213], v[128:131]
	v_mfma_f32_16x16x32_bf16 v[132:135], v[70:73], v[210:213], v[132:135]
	v_mfma_f32_16x16x32_bf16 v[116:119], v[70:73], v[218:221], v[116:119]
	v_mfma_f32_16x16x32_bf16 v[112:115], v[172:175], v[218:221], v[112:115]
	v_mfma_f32_16x16x32_bf16 v[96:99], v[172:175], v[234:237], v[96:99]
	v_mfma_f32_16x16x32_bf16 v[100:103], v[70:73], v[234:237], v[100:103]
	v_mfma_f32_16x16x32_bf16 v[140:143], v[74:77], v[206:209], v[140:143]
	v_mfma_f32_16x16x32_bf16 v[136:139], v[176:179], v[206:209], v[136:139]
	v_mfma_f32_16x16x32_bf16 v[128:131], v[176:179], v[214:217], v[128:131]
	v_mfma_f32_16x16x32_bf16 v[132:135], v[74:77], v[214:217], v[132:135]
	v_mfma_f32_16x16x32_bf16 v[116:119], v[74:77], v[230:233], v[116:119]
	v_mfma_f32_16x16x32_bf16 v[112:115], v[176:179], v[230:233], v[112:115]
	v_mfma_f32_16x16x32_bf16 v[96:99], v[176:179], v[238:241], v[96:99]
	v_mfma_f32_16x16x32_bf16 v[100:103], v[74:77], v[238:241], v[100:103]
	v_mfma_f32_16x16x32_bf16 v[124:127], v[180:183], v[202:205], v[124:127]
	v_mfma_f32_16x16x32_bf16 v[120:123], v[188:191], v[202:205], v[120:123]
	v_mfma_f32_16x16x32_bf16 v[104:107], v[188:191], v[210:213], v[104:107]
	v_mfma_f32_16x16x32_bf16 v[108:111], v[180:183], v[210:213], v[108:111]
	v_mfma_f32_16x16x32_bf16 v[92:95], v[180:183], v[218:221], v[92:95]
	v_mfma_f32_16x16x32_bf16 v[88:91], v[188:191], v[218:221], v[88:91]
	v_mfma_f32_16x16x32_bf16 v[78:81], v[188:191], v[234:237], v[80:83]
	v_mfma_f32_16x16x32_bf16 v[84:87], v[180:183], v[234:237], v[84:87]
	v_mfma_f32_16x16x32_bf16 v[124:127], v[184:187], v[206:209], v[124:127]
	v_mfma_f32_16x16x32_bf16 v[120:123], v[198:201], v[206:209], v[120:123]
	v_mfma_f32_16x16x32_bf16 v[104:107], v[198:201], v[214:217], v[104:107]
	v_mfma_f32_16x16x32_bf16 v[108:111], v[184:187], v[214:217], v[108:111]
	v_mfma_f32_16x16x32_bf16 v[92:95], v[184:187], v[230:233], v[92:95]
	v_mfma_f32_16x16x32_bf16 v[88:91], v[198:201], v[230:233], v[88:91]
	v_mfma_f32_16x16x32_bf16 v[78:81], v[198:201], v[238:241], v[78:81]
	v_mfma_f32_16x16x32_bf16 v[84:87], v[184:187], v[238:241], v[84:87]
	s_barrier
	s_setprio 1
	s_add_i32 s82, s82, s52
	v_lshl_add_u64 v[224:225], s[64:65], 0, v[164:165]
	s_mov_b32 m0, s82
	ds_read_b128 v[202:205], v171 offset:16384
	ds_read_b128 v[206:209], v171 offset:17408
	ds_read_b128 v[210:213], v171 offset:18432
	ds_read_b128 v[214:217], v171 offset:19456
	ds_read_b128 v[218:221], v171 offset:20480
	ds_read_b128 v[230:233], v171 offset:21504
	ds_read_b128 v[234:237], v171 offset:22528
	ds_read_b128 v[238:241], v171 offset:23552
	global_load_lds_dwordx4 v[224:225], off
	s_add_i32 m0, s82, 0x2000
	s_add_u32 s82, s64, 0x40000
	v_lshl_add_u64 v[226:227], s[64:65], 0, v[168:169]
	s_addc_u32 s83, s65, 0
	s_add_i32 s90, s90, s52
	global_load_lds_dwordx4 v[226:227], off
	v_lshl_add_u64 v[82:83], s[82:83], 0, v[164:165]
	s_mov_b32 m0, s90
	v_lshl_add_u64 v[242:243], s[66:67], 0, v[162:163]
	global_load_lds_dwordx4 v[82:83], off
	v_lshl_add_u64 v[82:83], s[82:83], 0, v[168:169]
	s_add_i32 m0, s90, 0x2000
	v_lshl_add_u64 v[244:245], s[66:67], 0, v[166:167]
	global_load_lds_dwordx4 v[82:83], off
	s_mov_b32 m0, s53
	s_nop 0
	global_load_lds_dwordx4 v[242:243], off
	s_mov_b32 m0, s56
	s_nop 0
	global_load_lds_dwordx4 v[244:245], off
	s_waitcnt vmcnt(8)
	s_waitcnt lgkmcnt(0)
	s_setprio 0
	s_barrier
	s_waitcnt lgkmcnt(0)
	v_mfma_f32_16x16x32_bf16 v[60:63], v[70:73], v[202:205], v[60:63]
	v_mfma_f32_16x16x32_bf16 v[56:59], v[172:175], v[202:205], v[56:59]
	v_mfma_f32_16x16x32_bf16 v[44:47], v[172:175], v[210:213], v[44:47]
	v_mfma_f32_16x16x32_bf16 v[52:55], v[70:73], v[210:213], v[52:55]
	v_mfma_f32_16x16x32_bf16 v[28:31], v[70:73], v[218:221], v[28:31]
	v_mfma_f32_16x16x32_bf16 v[24:27], v[172:175], v[218:221], v[24:27]
	v_mfma_f32_16x16x32_bf16 v[8:11], v[172:175], v[234:237], v[8:11]
	v_mfma_f32_16x16x32_bf16 v[16:19], v[70:73], v[234:237], v[16:19]
	v_mfma_f32_16x16x32_bf16 v[60:63], v[74:77], v[206:209], v[60:63]
	v_mfma_f32_16x16x32_bf16 v[56:59], v[176:179], v[206:209], v[56:59]
	v_mfma_f32_16x16x32_bf16 v[44:47], v[176:179], v[214:217], v[44:47]
	v_mfma_f32_16x16x32_bf16 v[52:55], v[74:77], v[214:217], v[52:55]
	v_mfma_f32_16x16x32_bf16 v[28:31], v[74:77], v[230:233], v[28:31]
	v_mfma_f32_16x16x32_bf16 v[24:27], v[176:179], v[230:233], v[24:27]
	v_mfma_f32_16x16x32_bf16 v[8:11], v[176:179], v[238:241], v[8:11]
	v_mfma_f32_16x16x32_bf16 v[16:19], v[74:77], v[238:241], v[16:19]
	v_mfma_f32_16x16x32_bf16 v[48:51], v[180:183], v[202:205], v[48:51]
	v_mfma_f32_16x16x32_bf16 v[40:43], v[188:191], v[202:205], v[40:43]
	v_mfma_f32_16x16x32_bf16 v[32:35], v[188:191], v[210:213], v[32:35]
	v_mfma_f32_16x16x32_bf16 v[36:39], v[180:183], v[210:213], v[36:39]
	v_mfma_f32_16x16x32_bf16 v[20:23], v[180:183], v[218:221], v[20:23]
	v_mfma_f32_16x16x32_bf16 v[12:15], v[188:191], v[218:221], v[12:15]
	v_mfma_f32_16x16x32_bf16 v[0:3], v[188:191], v[234:237], v[0:3]
	v_mfma_f32_16x16x32_bf16 v[4:7], v[180:183], v[234:237], v[4:7]
	v_mfma_f32_16x16x32_bf16 v[48:51], v[184:187], v[206:209], v[48:51]
	v_mfma_f32_16x16x32_bf16 v[40:43], v[198:201], v[206:209], v[40:43]
	v_mfma_f32_16x16x32_bf16 v[32:35], v[198:201], v[214:217], v[32:35]
	v_mfma_f32_16x16x32_bf16 v[36:39], v[184:187], v[214:217], v[36:39]
	v_mfma_f32_16x16x32_bf16 v[20:23], v[184:187], v[230:233], v[20:23]
	v_mfma_f32_16x16x32_bf16 v[12:15], v[198:201], v[230:233], v[12:15]
	v_mfma_f32_16x16x32_bf16 v[0:3], v[198:201], v[238:241], v[0:3]
	v_mfma_f32_16x16x32_bf16 v[4:7], v[184:187], v[238:241], v[4:7]
	s_barrier
; #define PG8_STAGE(bufoff, gbase, voff) do { _Pragma("unroll") for (int _i = 0; _i < 2; ++_i) \
;         __builtin_amdgcn_global_load_lds((const unsigned*)((const char*)(gbase) + (voff)[_i]), (LAS unsigned*)(lds + (bufoff) + ldsw + _i * 8192), 16, 0, 0); } while (0)
; #define PG8_LDA(dst, b, h) do { _Pragma("unroll") for (int m = 0; m < 4; ++m) _Pragma("unroll") for (int k = 0; k < 2; ++k) dst[m][k] = *(const LAS bf16x8*)(lds + PG8_SA(b, h) + aoff + m * 2048 + k * 1024); } while (0)
; #define PG8_LDB(dst, b, h) do { _Pragma("unroll") for (int n = 0; n < 2; ++n) _Pragma("unroll") for (int k = 0; k < 2; ++k) dst[n][k] = *(const LAS bf16x8*)(lds + PG8_SB(b, h) + boff + n * 2048 + k * 1024); } while (0)
; #define PG8_MMA(ai, bj, At, Bt) do { __builtin_amdgcn_s_setprio(1); _Pragma("unroll") for (int m = 0; m < 4; ++m) _Pragma("unroll") for (int n = 0; n < 2; ++n) _Pragma("unroll") for (int k = 0; k < 2; ++k) \
;         acc[ai][bj][m][n] = __builtin_amdgcn_mfma_f32_16x16x32_bf16(Bt[n][k], At[m][k], acc[ai][bj][m][n], 0, 0, 0); __builtin_amdgcn_s_setprio(0); } while (0)
; #define PG8_WAIT_V(n) asm volatile("s_waitcnt vmcnt(" #n ")" ::: "memory")
; #define PG8_WAIT_L(n) asm volatile("s_waitcnt lgkmcnt(" #n ")" ::: "memory")
; #define PG8_BAR __builtin_amdgcn_s_barrier()
; #define PG8_SCHED __builtin_amdgcn_sched_barrier(0)
; template <class Epi, class Sched>
; __device__ __forceinline__ void gemm_phase(LAS unsigned char* lds, const Gemm g, const Sched& S, const Epi& E, const int tid) {
;     ...
;             PG8_LDB(B0, 1, 0); PG8_LDB(B1, 1, 1); PG8_SCHED; PG8_LDA(At, 1, 0); PG8_STAGE(PG8_SA(0, 1), a2 + hstep, voffA);
;             PG8_WAIT_V(8); PG8_WAIT_L(0); PG8_BAR; PG8_MMA(0, 0, At, B0); PG8_MMA(0, 1, At, B1); PG8_BAR; PG8_SCHED;
	s_setprio 1
	s_add_i32 s82, 0, 0x18000
	v_add_u32_e32 v69, s82, v154
	s_add_i32 s83, 0, 0x1c000
	ds_read_b128 v[70:73], v69
	ds_read_b128 v[74:77], v69 offset:1024
	ds_read_b128 v[172:175], v69 offset:2048
	ds_read_b128 v[176:179], v69 offset:3072
	v_add_u32_e32 v69, s83, v154
	ds_read_b128 v[180:183], v69
	ds_read_b128 v[184:187], v69 offset:1024
	ds_read_b128 v[188:191], v69 offset:2048
	ds_read_b128 v[198:201], v69 offset:3072
	s_add_u32 s66, s66, 0x40000
	s_addc_u32 s67, s67, 0
	s_mov_b32 m0, s57
	v_lshl_add_u64 v[82:83], s[66:67], 0, v[162:163]
	ds_read_b128 v[202:205], v171 offset:32768
	ds_read_b128 v[206:209], v171 offset:33792
	ds_read_b128 v[210:213], v171 offset:34816
	ds_read_b128 v[214:217], v171 offset:35840
	ds_read_b128 v[218:221], v171 offset:36864
	ds_read_b128 v[230:233], v171 offset:37888
	ds_read_b128 v[234:237], v171 offset:38912
	ds_read_b128 v[238:241], v171 offset:39936
	global_load_lds_dwordx4 v[82:83], off
	v_lshl_add_u64 v[82:83], s[66:67], 0, v[166:167]
	s_mov_b32 m0, s58
	s_nop 0
	global_load_lds_dwordx4 v[82:83], off
	s_waitcnt vmcnt(8)
	s_waitcnt lgkmcnt(0)
	s_setprio 0
	s_barrier
	s_waitcnt lgkmcnt(0)
	v_mfma_f32_16x16x32_bf16 v[140:143], v[70:73], v[202:205], v[140:143]
	v_mfma_f32_16x16x32_bf16 v[136:139], v[172:175], v[202:205], v[136:139]
	v_mfma_f32_16x16x32_bf16 v[128:131], v[172:175], v[210:213], v[128:131]
	v_mfma_f32_16x16x32_bf16 v[132:135], v[70:73], v[210:213], v[132:135]
	v_mfma_f32_16x16x32_bf16 v[116:119], v[70:73], v[218:221], v[116:119]
	v_mfma_f32_16x16x32_bf16 v[112:115], v[172:175], v[218:221], v[112:115]
	v_mfma_f32_16x16x32_bf16 v[96:99], v[172:175], v[234:237], v[96:99]
	v_mfma_f32_16x16x32_bf16 v[100:103], v[70:73], v[234:237], v[100:103]
	v_mfma_f32_16x16x32_bf16 v[140:143], v[74:77], v[206:209], v[140:143]
	v_mfma_f32_16x16x32_bf16 v[136:139], v[176:179], v[206:209], v[136:139]
	v_mfma_f32_16x16x32_bf16 v[128:131], v[176:179], v[214:217], v[128:131]
	v_mfma_f32_16x16x32_bf16 v[132:135], v[74:77], v[214:217], v[132:135]
	v_mfma_f32_16x16x32_bf16 v[116:119], v[74:77], v[230:233], v[116:119]
	v_mfma_f32_16x16x32_bf16 v[112:115], v[176:179], v[230:233], v[112:115]
	v_mfma_f32_16x16x32_bf16 v[96:99], v[176:179], v[238:241], v[96:99]
	v_mfma_f32_16x16x32_bf16 v[100:103], v[74:77], v[238:241], v[100:103]
	v_mfma_f32_16x16x32_bf16 v[124:127], v[180:183], v[202:205], v[124:127]
	v_mfma_f32_16x16x32_bf16 v[120:123], v[188:191], v[202:205], v[120:123]
	v_mfma_f32_16x16x32_bf16 v[104:107], v[188:191], v[210:213], v[104:107]
	v_mfma_f32_16x16x32_bf16 v[108:111], v[180:183], v[210:213], v[108:111]
	v_mfma_f32_16x16x32_bf16 v[92:95], v[180:183], v[218:221], v[92:95]
	v_mfma_f32_16x16x32_bf16 v[88:91], v[188:191], v[218:221], v[88:91]
	v_mfma_f32_16x16x32_bf16 v[78:81], v[188:191], v[234:237], v[78:81]
	v_mfma_f32_16x16x32_bf16 v[82:85], v[180:183], v[234:237], v[84:87]
	v_mfma_f32_16x16x32_bf16 v[124:127], v[184:187], v[206:209], v[124:127]
	v_mfma_f32_16x16x32_bf16 v[120:123], v[198:201], v[206:209], v[120:123]
	v_mfma_f32_16x16x32_bf16 v[104:107], v[198:201], v[214:217], v[104:107]
	v_mfma_f32_16x16x32_bf16 v[108:111], v[184:187], v[214:217], v[108:111]
	v_mfma_f32_16x16x32_bf16 v[92:95], v[184:187], v[230:233], v[92:95]
	v_mfma_f32_16x16x32_bf16 v[88:91], v[198:201], v[230:233], v[88:91]
	v_mfma_f32_16x16x32_bf16 v[80:83], v[198:201], v[238:241], v[78:81]
	v_mfma_f32_16x16x32_bf16 v[84:87], v[184:187], v[238:241], v[82:85]
	s_barrier
; #define PG8_STAGE(bufoff, gbase, voff) do { _Pragma("unroll") for (int _i = 0; _i < 2; ++_i) \
;         __builtin_amdgcn_global_load_lds((const unsigned*)((const char*)(gbase) + (voff)[_i]), (LAS unsigned*)(lds + (bufoff) + ldsw + _i * 8192), 16, 0, 0); } while (0)
; #define PG8_LDA(dst, b, h) do { _Pragma("unroll") for (int m = 0; m < 4; ++m) _Pragma("unroll") for (int k = 0; k < 2; ++k) dst[m][k] = *(const LAS bf16x8*)(lds + PG8_SA(b, h) + aoff + m * 2048 + k * 1024); } while (0)
; #define PG8_MMA(ai, bj, At, Bt) do { __builtin_amdgcn_s_setprio(1); _Pragma("unroll") for (int m = 0; m < 4; ++m) _Pragma("unroll") for (int n = 0; n < 2; ++n) _Pragma("unroll") for (int k = 0; k < 2; ++k) \
;         acc[ai][bj][m][n] = __builtin_amdgcn_mfma_f32_16x16x32_bf16(Bt[n][k], At[m][k], acc[ai][bj][m][n], 0, 0, 0); __builtin_amdgcn_s_setprio(0); } while (0)
; #define PG8_WAIT_V(n) asm volatile("s_waitcnt vmcnt(" #n ")" ::: "memory")
; #define PG8_WAIT_L(n) asm volatile("s_waitcnt lgkmcnt(" #n ")" ::: "memory")
; #define PG8_BAR __builtin_amdgcn_s_barrier()
; #define PG8_SCHED __builtin_amdgcn_sched_barrier(0)
; template <class Epi, class Sched>
; __device__ __forceinline__ void gemm_phase(LAS unsigned char* lds, const Gemm g, const Sched& S, const Epi& E, const int tid) {
;     ...
;             PG8_LDA(At, 1, 1); PG8_STAGE(PG8_SB(1, 0), b3, voffB); PG8_STAGE(PG8_SB(1, 1), b3 + hstep, voffB); PG8_STAGE(PG8_SA(1, 0), a3, voffA);
;             PG8_WAIT_V(8); PG8_WAIT_L(0); PG8_BAR; PG8_MMA(1, 0, At, B0); PG8_MMA(1, 1, At, B1); PG8_BAR; PG8_SCHED;
;         }
;         if (wr == 0) PG8_BAR;
	s_setprio 1
	s_add_i32 s66, s82, s52
	v_lshl_add_u64 v[78:79], v[224:225], 0, s[68:69]
	s_mov_b32 m0, s66
	ds_read_b128 v[202:205], v171 offset:49152
	ds_read_b128 v[206:209], v171 offset:50176
	ds_read_b128 v[210:213], v171 offset:51200
	ds_read_b128 v[214:217], v171 offset:52224
	ds_read_b128 v[218:221], v171 offset:53248
	ds_read_b128 v[230:233], v171 offset:54272
	ds_read_b128 v[234:237], v171 offset:55296
	ds_read_b128 v[238:241], v171 offset:56320
	global_load_lds_dwordx4 v[78:79], off
	s_add_i32 m0, s66, 0x2000
	s_add_u32 s64, s64, 0x40080
	v_lshl_add_u64 v[78:79], v[226:227], 0, s[68:69]
	s_addc_u32 s65, s65, 0
	s_add_i32 s66, s83, s52
	global_load_lds_dwordx4 v[78:79], off
	v_lshl_add_u64 v[78:79], s[64:65], 0, v[164:165]
	s_mov_b32 m0, s66
	s_nop 0
	global_load_lds_dwordx4 v[78:79], off
	v_lshl_add_u64 v[78:79], s[64:65], 0, v[168:169]
	s_add_i32 m0, s66, 0x2000
	s_nop 0
	global_load_lds_dwordx4 v[78:79], off
	v_lshl_add_u64 v[78:79], v[242:243], 0, s[68:69]
	s_mov_b32 m0, s61
	s_nop 0
	global_load_lds_dwordx4 v[78:79], off
	v_lshl_add_u64 v[78:79], v[244:245], 0, s[68:69]
	s_mov_b32 m0, s70
	s_nop 0
	global_load_lds_dwordx4 v[78:79], off
	s_waitcnt vmcnt(8)
	s_waitcnt lgkmcnt(0)
	s_setprio 0
	s_barrier
	s_waitcnt lgkmcnt(0)
	v_mfma_f32_16x16x32_bf16 v[60:63], v[70:73], v[202:205], v[60:63]
	v_mfma_f32_16x16x32_bf16 v[56:59], v[172:175], v[202:205], v[56:59]
	v_mfma_f32_16x16x32_bf16 v[44:47], v[172:175], v[210:213], v[44:47]
	v_mfma_f32_16x16x32_bf16 v[52:55], v[70:73], v[210:213], v[52:55]
	v_mfma_f32_16x16x32_bf16 v[28:31], v[70:73], v[218:221], v[28:31]
	v_mfma_f32_16x16x32_bf16 v[24:27], v[172:175], v[218:221], v[24:27]
	v_mfma_f32_16x16x32_bf16 v[8:11], v[172:175], v[234:237], v[8:11]
	v_mfma_f32_16x16x32_bf16 v[16:19], v[70:73], v[234:237], v[16:19]
	v_mfma_f32_16x16x32_bf16 v[60:63], v[74:77], v[206:209], v[60:63]
	v_mfma_f32_16x16x32_bf16 v[56:59], v[176:179], v[206:209], v[56:59]
	v_mfma_f32_16x16x32_bf16 v[44:47], v[176:179], v[214:217], v[44:47]
	v_mfma_f32_16x16x32_bf16 v[52:55], v[74:77], v[214:217], v[52:55]
	v_mfma_f32_16x16x32_bf16 v[28:31], v[74:77], v[230:233], v[28:31]
	v_mfma_f32_16x16x32_bf16 v[24:27], v[176:179], v[230:233], v[24:27]
	v_mfma_f32_16x16x32_bf16 v[8:11], v[176:179], v[238:241], v[8:11]
	v_mfma_f32_16x16x32_bf16 v[16:19], v[74:77], v[238:241], v[16:19]
	v_mfma_f32_16x16x32_bf16 v[48:51], v[180:183], v[202:205], v[48:51]
	v_mfma_f32_16x16x32_bf16 v[40:43], v[188:191], v[202:205], v[40:43]
	v_mfma_f32_16x16x32_bf16 v[32:35], v[188:191], v[210:213], v[32:35]
	v_mfma_f32_16x16x32_bf16 v[36:39], v[180:183], v[210:213], v[36:39]
	v_mfma_f32_16x16x32_bf16 v[20:23], v[180:183], v[218:221], v[20:23]
	v_mfma_f32_16x16x32_bf16 v[12:15], v[188:191], v[218:221], v[12:15]
	v_mfma_f32_16x16x32_bf16 v[0:3], v[188:191], v[234:237], v[0:3]
	v_mfma_f32_16x16x32_bf16 v[4:7], v[180:183], v[234:237], v[4:7]
	v_mfma_f32_16x16x32_bf16 v[48:51], v[184:187], v[206:209], v[48:51]
	v_mfma_f32_16x16x32_bf16 v[40:43], v[198:201], v[206:209], v[40:43]
	v_mfma_f32_16x16x32_bf16 v[32:35], v[198:201], v[214:217], v[32:35]
	v_mfma_f32_16x16x32_bf16 v[36:39], v[184:187], v[214:217], v[36:39]
	v_mfma_f32_16x16x32_bf16 v[20:23], v[184:187], v[230:233], v[20:23]
	v_mfma_f32_16x16x32_bf16 v[12:15], v[198:201], v[230:233], v[12:15]
	v_mfma_f32_16x16x32_bf16 v[0:3], v[198:201], v[238:241], v[0:3]
	v_mfma_f32_16x16x32_bf16 v[4:7], v[184:187], v[238:241], v[4:7]
	s_barrier
	s_setprio 1
	s_add_i32 s81, s81, 2
	s_add_u32 s62, s62, 0x100
	s_addc_u32 s63, s63, 0
	s_add_u32 s78, s78, 0x100
	s_addc_u32 s79, s79, 0
	s_cmp_gt_u32 s81, 13
	s_cbranch_scc0 .LBB0_326
	s_and_b64 vcc, exec, s[8:9]
	s_cbranch_vccz .LBB0_329
	s_barrier

;     __device__ __forceinline__ Pre prefetch(const Unit& u, int tid) const { return prenorm_load(stats, u.pn * BM, sW + (size_t)(u.pn >> 4) * SW_ROWS + u.pm * BM, tid); }
;     __device__ __forceinline__ Pre prefetch(const Unit& u, int tid) const { return prenorm_load(stats, u.pm * BM, sW + (size_t)(u.pm >> 4) * SW_ROWS + u.pn * BM, tid); }
;     __device__ __forceinline__ Pre prefetch(const Unit& u, int tid) const { return prenorm_load(stats, u.pm * BM, sW + (size_t)(u.pm >> 4) * SW_ROWS + u.pn * BM, tid); }
; #define PG8_STAGE(bufoff, gbase, voff) do { _Pragma("unroll") for (int _i = 0; _i < 2; ++_i) \
;         __builtin_amdgcn_global_load_lds((const unsigned*)((const char*)(gbase) + (voff)[_i]), (LAS unsigned*)(lds + (bufoff) + ldsw + _i * 8192), 16, 0, 0); } while (0)
; #define PG8_LDA(dst, b, h) do { _Pragma("unroll") for (int m = 0; m < 4; ++m) _Pragma("unroll") for (int k = 0; k < 2; ++k) dst[m][k] = *(const LAS bf16x8*)(lds + PG8_SA(b, h) + aoff + m * 2048 + k * 1024); } while (0)
; #define PG8_WAIT_V(n) asm volatile("s_waitcnt vmcnt(" #n ")" ::: "memory")
; #define PG8_BAR __builtin_amdgcn_s_barrier()
; template <class Epi, class Sched>
; __device__ __forceinline__ void gemm_phase(LAS unsigned char* lds, const Gemm g, const Sched& S, const Epi& E, const int tid) {
;     ...
;         const char* nA = has_next ? (const char*)g.A + (size_t)nxt.pm * tstep : cA; const char* nB = has_next ? (const char*)g.Bt + (size_t)nxt.pn * tstep : cB;
;         const typename Epi::Pre pre = E.prefetch(cur, tid);
;         for (int t = 0; t < nt; t += 2) {
;             const bool last = (t == nt - 2);
;             const char* a1 = cA + (size_t)(t + 1) * kstep;
;             const char* a2 = last ? nA : cA + (size_t)(t + 2) * kstep; const char* b2 = last ? nB : cB + (size_t)(t + 2) * kstep;
;             const char* a3 = a2 + kstep; const char* b3 = b2 + kstep;
;             PG8_LDB(B0, 0, 0); PG8_LDB(B1, 0, 1); PG8_SCHED; PG8_LDA(At, 0, 0); PG8_STAGE(PG8_SA(1, 1), a1 + hstep, voffA);
;             PG8_WAIT_V(8); PG8_WAIT_L(0); PG8_BAR; PG8_MMA(0, 0, At, B0); PG8_MMA(0, 1, At, B1); PG8_BAR; PG8_SCHED;
;             PG8_LDA(At, 0, 1); PG8_STAGE(PG8_SB(0, 0), b2, voffB); PG8_STAGE(PG8_SB(0, 1), b2 + hstep, voffB); PG8_STAGE(PG8_SA(0, 0), a2, voffA);
;             PG8_WAIT_V(8); PG8_WAIT_L(0); PG8_BAR; PG8_MMA(1, 0, At, B0); PG8_MMA(1, 1, At, B1); PG8_BAR; PG8_SCHED;
.LBB0_565:
.LBB0_566:
	s_or_b64 exec, exec, s[82:83]
	s_add_u32 vcc_lo, s80, 0x80
	s_addc_u32 vcc_hi, s81, 0
	s_add_u32 s61, s74, 0x100
	s_addc_u32 s67, s75, 0
	s_mov_b32 s74, 0
	s_add_i32 s80, s74, 2
	s_add_u32 s81, vcc_lo, 0x80
	s_addc_u32 s75, vcc_hi, 0
	s_add_i32 s3, 0, 0x10000
	s_cmp_eq_u32 s57, s74
	s_cselect_b32 s75, s71, s75
	s_cselect_b32 s74, s70, s81
	v_add_u32_e32 v70, s3, v232
	s_cselect_b32 s83, s73, s67
	s_cselect_b32 s82, s72, s61
	s_add_i32 s81, 0, 0x14000
	ds_read_b128 v[58:61], v70
	ds_read_b128 v[62:65], v70 offset:1024
	ds_read_b128 v[66:69], v70 offset:2048
	ds_read_b128 v[80:83], v70 offset:3072
	v_add_u32_e32 v70, s81, v232
	ds_read_b128 v[84:87], v70
	ds_read_b128 v[88:91], v70 offset:1024
	ds_read_b128 v[92:95], v70 offset:2048
	ds_read_b128 v[152:155], v70 offset:3072
	v_lshl_add_u64 v[70:71], vcc, 0, v[204:205]
	s_add_i32 m0, s97, 0xc000
	ds_read_b128 v[164:167], v240
	ds_read_b128 v[168:171], v240 offset:1024
	ds_read_b128 v[172:175], v240 offset:2048
	ds_read_b128 v[176:179], v240 offset:3072
	ds_read_b128 v[180:183], v240 offset:4096
	ds_read_b128 v[184:187], v240 offset:5120
	ds_read_b128 v[188:191], v240 offset:6144
	ds_read_b128 v[208:211], v240 offset:7168
	global_load_lds_dwordx4 v[70:71], off
	v_lshl_add_u64 v[70:71], vcc, 0, v[206:207]
	s_add_i32 m0, s97, 0xe000
	s_nop 0
	global_load_lds_dwordx4 v[70:71], off
	s_waitcnt vmcnt(8)
	s_waitcnt lgkmcnt(0)
	s_setprio 0
	s_barrier
	s_waitcnt lgkmcnt(0)
	v_mfma_f32_16x16x32_bf16 v[160:163], v[58:61], v[164:167], 0
	v_mfma_f32_16x16x32_bf16 v[156:159], v[66:69], v[164:167], 0
	v_mfma_f32_16x16x32_bf16 v[136:139], v[66:69], v[172:175], 0
	v_mfma_f32_16x16x32_bf16 v[140:143], v[58:61], v[172:175], 0
	v_mfma_f32_16x16x32_bf16 v[124:127], v[58:61], v[180:183], 0
	v_mfma_f32_16x16x32_bf16 v[120:123], v[66:69], v[180:183], 0
	v_mfma_f32_16x16x32_bf16 v[104:107], v[66:69], v[188:191], 0
	v_mfma_f32_16x16x32_bf16 v[108:111], v[58:61], v[188:191], 0
	v_mfma_f32_16x16x32_bf16 v[160:163], v[62:65], v[168:171], v[160:163]
	v_mfma_f32_16x16x32_bf16 v[156:159], v[80:83], v[168:171], v[156:159]
	v_mfma_f32_16x16x32_bf16 v[136:139], v[80:83], v[176:179], v[136:139]
	v_mfma_f32_16x16x32_bf16 v[140:143], v[62:65], v[176:179], v[140:143]
	v_mfma_f32_16x16x32_bf16 v[124:127], v[62:65], v[184:187], v[124:127]
	v_mfma_f32_16x16x32_bf16 v[120:123], v[80:83], v[184:187], v[120:123]
	v_mfma_f32_16x16x32_bf16 v[104:107], v[80:83], v[208:211], v[104:107]
	v_mfma_f32_16x16x32_bf16 v[108:111], v[62:65], v[208:211], v[108:111]
	v_mfma_f32_16x16x32_bf16 v[148:151], v[84:87], v[164:167], 0
	v_mfma_f32_16x16x32_bf16 v[144:147], v[92:95], v[164:167], 0
	v_mfma_f32_16x16x32_bf16 v[128:131], v[92:95], v[172:175], 0
	v_mfma_f32_16x16x32_bf16 v[132:135], v[84:87], v[172:175], 0
	v_mfma_f32_16x16x32_bf16 v[116:119], v[84:87], v[180:183], 0
	v_mfma_f32_16x16x32_bf16 v[112:115], v[92:95], v[180:183], 0
	v_mfma_f32_16x16x32_bf16 v[96:99], v[92:95], v[188:191], 0
	v_mfma_f32_16x16x32_bf16 v[100:103], v[84:87], v[188:191], 0
	v_mfma_f32_16x16x32_bf16 v[148:151], v[88:91], v[168:171], v[148:151]
	v_mfma_f32_16x16x32_bf16 v[144:147], v[152:155], v[168:171], v[144:147]
	v_mfma_f32_16x16x32_bf16 v[128:131], v[152:155], v[176:179], v[128:131]
	v_mfma_f32_16x16x32_bf16 v[132:135], v[88:91], v[176:179], v[132:135]
	v_mfma_f32_16x16x32_bf16 v[116:119], v[88:91], v[184:187], v[116:119]
	v_mfma_f32_16x16x32_bf16 v[112:115], v[152:155], v[184:187], v[112:115]
	v_mfma_f32_16x16x32_bf16 v[96:99], v[152:155], v[208:211], v[96:99]
	v_mfma_f32_16x16x32_bf16 v[100:103], v[88:91], v[208:211], v[100:103]
	s_barrier
	s_setprio 1
	s_add_i32 s3, s3, s94
	v_lshl_add_u64 v[212:213], s[82:83], 0, v[192:193]
	s_mov_b32 m0, s3
	ds_read_b128 v[164:167], v240 offset:16384
	ds_read_b128 v[168:171], v240 offset:17408
	ds_read_b128 v[172:175], v240 offset:18432
	ds_read_b128 v[176:179], v240 offset:19456
	ds_read_b128 v[180:183], v240 offset:20480
	ds_read_b128 v[184:187], v240 offset:21504
	ds_read_b128 v[188:191], v240 offset:22528
	ds_read_b128 v[208:211], v240 offset:23552
	global_load_lds_dwordx4 v[212:213], off
	s_add_i32 m0, s3, 0x2000
	v_lshl_add_u64 v[214:215], s[82:83], 0, v[198:199]
	s_add_u32 s82, s82, s12
	s_addc_u32 s83, s83, 0
	s_add_i32 s3, s81, s94
	global_load_lds_dwordx4 v[214:215], off
	v_lshl_add_u64 v[216:217], s[82:83], 0, v[192:193]
	s_mov_b32 m0, s3
	v_lshl_add_u64 v[218:219], s[82:83], 0, v[198:199]
	global_load_lds_dwordx4 v[216:217], off
	s_add_i32 m0, s3, 0x2000
	v_lshl_add_u64 v[220:221], s[74:75], 0, v[202:203]
	global_load_lds_dwordx4 v[218:219], off
	s_mov_b32 m0, s97
	v_lshl_add_u64 v[224:225], s[74:75], 0, v[200:201]
	global_load_lds_dwordx4 v[220:221], off
	s_mov_b32 m0, s98
	s_nop 0
	global_load_lds_dwordx4 v[224:225], off
	s_waitcnt vmcnt(8)
	s_waitcnt lgkmcnt(0)
	s_setprio 0
	s_barrier
; #define PG8_STAGE(bufoff, gbase, voff) do { _Pragma("unroll") for (int _i = 0; _i < 2; ++_i) \
;         __builtin_amdgcn_global_load_lds((const unsigned*)((const char*)(gbase) + (voff)[_i]), (LAS unsigned*)(lds + (bufoff) + ldsw + _i * 8192), 16, 0, 0); } while (0)
; #define PG8_LDA(dst, b, h) do { _Pragma("unroll") for (int m = 0; m < 4; ++m) _Pragma("unroll") for (int k = 0; k < 2; ++k) dst[m][k] = *(const LAS bf16x8*)(lds + PG8_SA(b, h) + aoff + m * 2048 + k * 1024); } while (0)
; #define PG8_LDB(dst, b, h) do { _Pragma("unroll") for (int n = 0; n < 2; ++n) _Pragma("unroll") for (int k = 0; k < 2; ++k) dst[n][k] = *(const LAS bf16x8*)(lds + PG8_SB(b, h) + boff + n * 2048 + k * 1024); } while (0)
; #define PG8_MMA(ai, bj, At, Bt) do { __builtin_amdgcn_s_setprio(1); _Pragma("unroll") for (int m = 0; m < 4; ++m) _Pragma("unroll") for (int n = 0; n < 2; ++n) _Pragma("unroll") for (int k = 0; k < 2; ++k) \
;         acc[ai][bj][m][n] = __builtin_amdgcn_mfma_f32_16x16x32_bf16(Bt[n][k], At[m][k], acc[ai][bj][m][n], 0, 0, 0); __builtin_amdgcn_s_setprio(0); } while (0)
; #define PG8_WAIT_V(n) asm volatile("s_waitcnt vmcnt(" #n ")" ::: "memory")
; #define PG8_WAIT_L(n) asm volatile("s_waitcnt lgkmcnt(" #n ")" ::: "memory")
; #define PG8_BAR __builtin_amdgcn_s_barrier()
; #define PG8_SCHED __builtin_amdgcn_sched_barrier(0)
; template <class Epi, class Sched>
; __device__ __forceinline__ void gemm_phase(LAS unsigned char* lds, const Gemm g, const Sched& S, const Epi& E, const int tid) {
;     ...
;             PG8_WAIT_V(8); PG8_WAIT_L(0); PG8_BAR; PG8_MMA(1, 0, At, B0); PG8_MMA(1, 1, At, B1); PG8_BAR; PG8_SCHED;
;             PG8_LDB(B0, 1, 0); PG8_LDB(B1, 1, 1); PG8_SCHED; PG8_LDA(At, 1, 0); PG8_STAGE(PG8_SA(0, 1), a2 + hstep, voffA);
;             PG8_WAIT_V(8); PG8_WAIT_L(0); PG8_BAR; PG8_MMA(0, 0, At, B0); PG8_MMA(0, 1, At, B1); PG8_BAR; PG8_SCHED;
	s_waitcnt lgkmcnt(0)
	v_mfma_f32_16x16x32_bf16 v[76:79], v[58:61], v[164:167], 0
	v_mfma_f32_16x16x32_bf16 v[70:73], v[66:69], v[164:167], 0
	v_mfma_f32_16x16x32_bf16 v[40:43], v[66:69], v[172:175], 0
	v_mfma_f32_16x16x32_bf16 v[44:47], v[58:61], v[172:175], 0
	v_mfma_f32_16x16x32_bf16 v[28:31], v[58:61], v[180:183], 0
	v_mfma_f32_16x16x32_bf16 v[24:27], v[66:69], v[180:183], 0
	v_mfma_f32_16x16x32_bf16 v[8:11], v[66:69], v[188:191], 0
	v_mfma_f32_16x16x32_bf16 v[12:15], v[58:61], v[188:191], 0
	v_mfma_f32_16x16x32_bf16 v[76:79], v[62:65], v[168:171], v[76:79]
	v_mfma_f32_16x16x32_bf16 v[70:73], v[80:83], v[168:171], v[70:73]
	v_mfma_f32_16x16x32_bf16 v[40:43], v[80:83], v[176:179], v[40:43]
	v_mfma_f32_16x16x32_bf16 v[44:47], v[62:65], v[176:179], v[44:47]
	v_mfma_f32_16x16x32_bf16 v[28:31], v[62:65], v[184:187], v[28:31]
	v_mfma_f32_16x16x32_bf16 v[24:27], v[80:83], v[184:187], v[24:27]
	v_mfma_f32_16x16x32_bf16 v[8:11], v[80:83], v[208:211], v[8:11]
	v_mfma_f32_16x16x32_bf16 v[12:15], v[62:65], v[208:211], v[12:15]
	v_mfma_f32_16x16x32_bf16 v[52:55], v[84:87], v[164:167], 0
	v_mfma_f32_16x16x32_bf16 v[48:51], v[92:95], v[164:167], 0
	v_mfma_f32_16x16x32_bf16 v[32:35], v[92:95], v[172:175], 0
	v_mfma_f32_16x16x32_bf16 v[36:39], v[84:87], v[172:175], 0
	v_mfma_f32_16x16x32_bf16 v[20:23], v[84:87], v[180:183], 0
	v_mfma_f32_16x16x32_bf16 v[16:19], v[92:95], v[180:183], 0
	v_mfma_f32_16x16x32_bf16 v[0:3], v[92:95], v[188:191], 0
	v_mfma_f32_16x16x32_bf16 v[4:7], v[84:87], v[188:191], 0
	v_mfma_f32_16x16x32_bf16 v[52:55], v[88:91], v[168:171], v[52:55]
	v_mfma_f32_16x16x32_bf16 v[48:51], v[152:155], v[168:171], v[48:51]
	v_mfma_f32_16x16x32_bf16 v[32:35], v[152:155], v[176:179], v[32:35]
	v_mfma_f32_16x16x32_bf16 v[36:39], v[88:91], v[176:179], v[36:39]
	v_mfma_f32_16x16x32_bf16 v[20:23], v[88:91], v[184:187], v[20:23]
	v_mfma_f32_16x16x32_bf16 v[16:19], v[152:155], v[184:187], v[16:19]
	v_mfma_f32_16x16x32_bf16 v[0:3], v[152:155], v[208:211], v[0:3]
	v_mfma_f32_16x16x32_bf16 v[4:7], v[88:91], v[208:211], v[4:7]
	s_barrier
	s_setprio 1
	s_add_i32 s3, 0, 0x18000
	v_add_u32_e32 v74, s3, v232
	s_add_i32 s81, 0, 0x1c000
	ds_read_b128 v[58:61], v74
	ds_read_b128 v[62:65], v74 offset:1024
	ds_read_b128 v[66:69], v74 offset:2048
	ds_read_b128 v[80:83], v74 offset:3072
	v_add_u32_e32 v74, s81, v232
	ds_read_b128 v[84:87], v74
	ds_read_b128 v[88:91], v74 offset:1024
	ds_read_b128 v[92:95], v74 offset:2048
	ds_read_b128 v[152:155], v74 offset:3072
	s_add_u32 s74, s74, s12
	s_addc_u32 s75, s75, 0
	s_mov_b32 m0, s99
	v_lshl_add_u64 v[74:75], s[74:75], 0, v[202:203]
	ds_read_b128 v[164:167], v240 offset:32768
	ds_read_b128 v[168:171], v240 offset:33792
	ds_read_b128 v[172:175], v240 offset:34816
	ds_read_b128 v[176:179], v240 offset:35840
	ds_read_b128 v[180:183], v240 offset:36864
	ds_read_b128 v[184:187], v240 offset:37888
	ds_read_b128 v[188:191], v240 offset:38912
	ds_read_b128 v[208:211], v240 offset:39936
	global_load_lds_dwordx4 v[74:75], off
	v_lshl_add_u64 v[74:75], s[74:75], 0, v[200:201]
	s_mov_b32 m0, s78
	s_nop 0
	global_load_lds_dwordx4 v[74:75], off
	s_waitcnt vmcnt(8)
	s_waitcnt lgkmcnt(0)
	s_setprio 0
	s_barrier
	s_waitcnt lgkmcnt(0)
	v_mfma_f32_16x16x32_bf16 v[160:163], v[58:61], v[164:167], v[160:163]
	v_mfma_f32_16x16x32_bf16 v[156:159], v[66:69], v[164:167], v[156:159]
	v_mfma_f32_16x16x32_bf16 v[136:139], v[66:69], v[172:175], v[136:139]
	v_mfma_f32_16x16x32_bf16 v[140:143], v[58:61], v[172:175], v[140:143]
	v_mfma_f32_16x16x32_bf16 v[124:127], v[58:61], v[180:183], v[124:127]
	v_mfma_f32_16x16x32_bf16 v[120:123], v[66:69], v[180:183], v[120:123]
	v_mfma_f32_16x16x32_bf16 v[104:107], v[66:69], v[188:191], v[104:107]
	v_mfma_f32_16x16x32_bf16 v[108:111], v[58:61], v[188:191], v[108:111]
	v_mfma_f32_16x16x32_bf16 v[160:163], v[62:65], v[168:171], v[160:163]
	v_mfma_f32_16x16x32_bf16 v[156:159], v[80:83], v[168:171], v[156:159]
	v_mfma_f32_16x16x32_bf16 v[136:139], v[80:83], v[176:179], v[136:139]
	v_mfma_f32_16x16x32_bf16 v[140:143], v[62:65], v[176:179], v[140:143]
	v_mfma_f32_16x16x32_bf16 v[124:127], v[62:65], v[184:187], v[124:127]
	v_mfma_f32_16x16x32_bf16 v[120:123], v[80:83], v[184:187], v[120:123]
	v_mfma_f32_16x16x32_bf16 v[104:107], v[80:83], v[208:211], v[104:107]
	v_mfma_f32_16x16x32_bf16 v[108:111], v[62:65], v[208:211], v[108:111]
	v_mfma_f32_16x16x32_bf16 v[148:151], v[84:87], v[164:167], v[148:151]
	v_mfma_f32_16x16x32_bf16 v[144:147], v[92:95], v[164:167], v[144:147]
	v_mfma_f32_16x16x32_bf16 v[128:131], v[92:95], v[172:175], v[128:131]
	v_mfma_f32_16x16x32_bf16 v[132:135], v[84:87], v[172:175], v[132:135]
	v_mfma_f32_16x16x32_bf16 v[116:119], v[84:87], v[180:183], v[116:119]
	v_mfma_f32_16x16x32_bf16 v[112:115], v[92:95], v[180:183], v[112:115]
	v_mfma_f32_16x16x32_bf16 v[96:99], v[92:95], v[188:191], v[96:99]
	v_mfma_f32_16x16x32_bf16 v[100:103], v[84:87], v[188:191], v[100:103]
	v_mfma_f32_16x16x32_bf16 v[148:151], v[88:91], v[168:171], v[148:151]
	v_mfma_f32_16x16x32_bf16 v[144:147], v[152:155], v[168:171], v[144:147]
	v_mfma_f32_16x16x32_bf16 v[128:131], v[152:155], v[176:179], v[128:131]
	v_mfma_f32_16x16x32_bf16 v[132:135], v[88:91], v[176:179], v[132:135]
	v_mfma_f32_16x16x32_bf16 v[116:119], v[88:91], v[184:187], v[116:119]
	v_mfma_f32_16x16x32_bf16 v[112:115], v[152:155], v[184:187], v[112:115]
	v_mfma_f32_16x16x32_bf16 v[96:99], v[152:155], v[208:211], v[96:99]
	v_mfma_f32_16x16x32_bf16 v[100:103], v[88:91], v[208:211], v[100:103]
	s_barrier
; #define PG8_STAGE(bufoff, gbase, voff) do { _Pragma("unroll") for (int _i = 0; _i < 2; ++_i) \
;         __builtin_amdgcn_global_load_lds((const unsigned*)((const char*)(gbase) + (voff)[_i]), (LAS unsigned*)(lds + (bufoff) + ldsw + _i * 8192), 16, 0, 0); } while (0)
; #define PG8_LDA(dst, b, h) do { _Pragma("unroll") for (int m = 0; m < 4; ++m) _Pragma("unroll") for (int k = 0; k < 2; ++k) dst[m][k] = *(const LAS bf16x8*)(lds + PG8_SA(b, h) + aoff + m * 2048 + k * 1024); } while (0)
; #define PG8_LDB(dst, b, h) do { _Pragma("unroll") for (int n = 0; n < 2; ++n) _Pragma("unroll") for (int k = 0; k < 2; ++k) dst[n][k] = *(const LAS bf16x8*)(lds + PG8_SB(b, h) + boff + n * 2048 + k * 1024); } while (0)
; #define PG8_WAIT_V(n) asm volatile("s_waitcnt vmcnt(" #n ")" ::: "memory")
; #define PG8_BAR __builtin_amdgcn_s_barrier()
; template <class Epi, class Sched>
; __device__ __forceinline__ void gemm_phase(LAS unsigned char* lds, const Gemm g, const Sched& S, const Epi& E, const int tid) {
;     ...
;         for (int t = 0; t < nt; t += 2) {
;             const bool last = (t == nt - 2);
;             const char* a1 = cA + (size_t)(t + 1) * kstep;
;             const char* a2 = last ? nA : cA + (size_t)(t + 2) * kstep; const char* b2 = last ? nB : cB + (size_t)(t + 2) * kstep;
;             const char* a3 = a2 + kstep; const char* b3 = b2 + kstep;
;             PG8_LDB(B0, 0, 0); PG8_LDB(B1, 0, 1); PG8_SCHED; PG8_LDA(At, 0, 0); PG8_STAGE(PG8_SA(1, 1), a1 + hstep, voffA);
;             PG8_WAIT_V(8); PG8_WAIT_L(0); PG8_BAR; PG8_MMA(0, 0, At, B0); PG8_MMA(0, 1, At, B1); PG8_BAR; PG8_SCHED;
;             PG8_LDA(At, 0, 1); PG8_STAGE(PG8_SB(0, 0), b2, voffB); PG8_STAGE(PG8_SB(0, 1), b2 + hstep, voffB); PG8_STAGE(PG8_SA(0, 0), a2, voffA);
;             PG8_WAIT_V(8); PG8_WAIT_L(0); PG8_BAR; PG8_MMA(1, 0, At, B0); PG8_MMA(1, 1, At, B1); PG8_BAR; PG8_SCHED;
;             PG8_LDB(B0, 1, 0); PG8_LDB(B1, 1, 1); PG8_SCHED; PG8_LDA(At, 1, 0); PG8_STAGE(PG8_SA(0, 1), a2 + hstep, voffA);
;             PG8_WAIT_V(8); PG8_WAIT_L(0); PG8_BAR; PG8_MMA(0, 0, At, B0); PG8_MMA(0, 1, At, B1); PG8_BAR; PG8_SCHED;
;             PG8_LDA(At, 1, 1); PG8_STAGE(PG8_SB(1, 0), b3, voffB); PG8_STAGE(PG8_SB(1, 1), b3 + hstep, voffB); PG8_STAGE(PG8_SA(1, 0), a3, voffA);
;             PG8_WAIT_V(8); PG8_WAIT_L(0); PG8_BAR; PG8_MMA(1, 0, At, B0); PG8_MMA(1, 1, At, B1); PG8_BAR; PG8_SCHED;
	s_setprio 1
	s_add_i32 s3, s3, s94
	v_lshl_add_u64 v[74:75], v[212:213], 0, s[68:69]
	s_mov_b32 m0, s3
	ds_read_b128 v[164:167], v240 offset:49152
	ds_read_b128 v[168:171], v240 offset:50176
	ds_read_b128 v[172:175], v240 offset:51200
	ds_read_b128 v[176:179], v240 offset:52224
	ds_read_b128 v[180:183], v240 offset:53248
	ds_read_b128 v[184:187], v240 offset:54272
	ds_read_b128 v[188:191], v240 offset:55296
	ds_read_b128 v[208:211], v240 offset:56320
	global_load_lds_dwordx4 v[74:75], off
	v_lshl_add_u64 v[74:75], v[214:215], 0, s[68:69]
	s_add_i32 m0, s3, 0x2000
	s_add_i32 s3, s81, s94
	global_load_lds_dwordx4 v[74:75], off
	v_lshl_add_u64 v[74:75], v[216:217], 0, s[68:69]
	s_mov_b32 m0, s3
	s_nop 0
	global_load_lds_dwordx4 v[74:75], off
	v_lshl_add_u64 v[74:75], v[218:219], 0, s[68:69]
	s_add_i32 m0, s3, 0x2000
	s_nop 0
	global_load_lds_dwordx4 v[74:75], off
	v_lshl_add_u64 v[74:75], v[220:221], 0, s[68:69]
	s_mov_b32 m0, s53
	s_nop 0
	global_load_lds_dwordx4 v[74:75], off
	v_lshl_add_u64 v[74:75], v[224:225], 0, s[68:69]
	s_mov_b32 m0, s56
	s_nop 0
	global_load_lds_dwordx4 v[74:75], off
	s_waitcnt vmcnt(8)
	s_waitcnt lgkmcnt(0)
	s_setprio 0
	s_barrier
	s_waitcnt lgkmcnt(0)
	v_mfma_f32_16x16x32_bf16 v[74:77], v[58:61], v[164:167], v[76:79]
	v_mfma_f32_16x16x32_bf16 v[70:73], v[66:69], v[164:167], v[70:73]
	v_mfma_f32_16x16x32_bf16 v[40:43], v[66:69], v[172:175], v[40:43]
	v_mfma_f32_16x16x32_bf16 v[44:47], v[58:61], v[172:175], v[44:47]
	v_mfma_f32_16x16x32_bf16 v[28:31], v[58:61], v[180:183], v[28:31]
	v_mfma_f32_16x16x32_bf16 v[24:27], v[66:69], v[180:183], v[24:27]
	v_mfma_f32_16x16x32_bf16 v[8:11], v[66:69], v[188:191], v[8:11]
	v_mfma_f32_16x16x32_bf16 v[12:15], v[58:61], v[188:191], v[12:15]
	v_mfma_f32_16x16x32_bf16 v[76:79], v[62:65], v[168:171], v[74:77]
	v_mfma_f32_16x16x32_bf16 v[72:75], v[80:83], v[168:171], v[70:73]
	v_mfma_f32_16x16x32_bf16 v[40:43], v[80:83], v[176:179], v[40:43]
	v_mfma_f32_16x16x32_bf16 v[44:47], v[62:65], v[176:179], v[44:47]
	v_mfma_f32_16x16x32_bf16 v[28:31], v[62:65], v[184:187], v[28:31]
	v_mfma_f32_16x16x32_bf16 v[24:27], v[80:83], v[184:187], v[24:27]
	v_mfma_f32_16x16x32_bf16 v[8:11], v[80:83], v[208:211], v[8:11]
	v_mfma_f32_16x16x32_bf16 v[12:15], v[62:65], v[208:211], v[12:15]
	v_mfma_f32_16x16x32_bf16 v[52:55], v[84:87], v[164:167], v[52:55]
	v_mfma_f32_16x16x32_bf16 v[48:51], v[92:95], v[164:167], v[48:51]
	v_mfma_f32_16x16x32_bf16 v[32:35], v[92:95], v[172:175], v[32:35]
	v_mfma_f32_16x16x32_bf16 v[36:39], v[84:87], v[172:175], v[36:39]
	v_mfma_f32_16x16x32_bf16 v[20:23], v[84:87], v[180:183], v[20:23]
	v_mfma_f32_16x16x32_bf16 v[16:19], v[92:95], v[180:183], v[16:19]
	v_mfma_f32_16x16x32_bf16 v[0:3], v[92:95], v[188:191], v[0:3]
	v_mfma_f32_16x16x32_bf16 v[4:7], v[84:87], v[188:191], v[4:7]
	v_mfma_f32_16x16x32_bf16 v[52:55], v[88:91], v[168:171], v[52:55]
	v_mfma_f32_16x16x32_bf16 v[48:51], v[152:155], v[168:171], v[48:51]
	v_mfma_f32_16x16x32_bf16 v[32:35], v[152:155], v[176:179], v[32:35]
	v_mfma_f32_16x16x32_bf16 v[36:39], v[88:91], v[176:179], v[36:39]
	v_mfma_f32_16x16x32_bf16 v[20:23], v[88:91], v[184:187], v[20:23]
	v_mfma_f32_16x16x32_bf16 v[16:19], v[152:155], v[184:187], v[16:19]
	v_mfma_f32_16x16x32_bf16 v[0:3], v[152:155], v[208:211], v[0:3]
	v_mfma_f32_16x16x32_bf16 v[4:7], v[88:91], v[208:211], v[4:7]
	s_barrier
	s_setprio 1
	s_add_u32 vcc_lo, vcc_lo, 0x100
	s_addc_u32 vcc_hi, vcc_hi, 0
	s_add_u32 s61, s61, 0x100
	s_addc_u32 s67, s67, 0
	s_cmp_ge_u32 s80, s52
	s_mov_b32 s74, s80
.LBB0_567:
	s_add_i32 s80, s74, 2
	s_add_u32 s81, vcc_lo, 0x80
	s_addc_u32 s75, vcc_hi, 0
	s_add_i32 s3, 0, 0x10000
	s_cmp_eq_u32 s57, s74
	s_cselect_b32 s75, s71, s75
	s_cselect_b32 s74, s70, s81
	v_add_u32_e32 v70, s3, v232
	s_cselect_b32 s83, s73, s67
	s_cselect_b32 s82, s72, s61
	s_add_i32 s81, 0, 0x14000
	ds_read_b128 v[58:61], v70
	ds_read_b128 v[62:65], v70 offset:1024
	ds_read_b128 v[66:69], v70 offset:2048
	ds_read_b128 v[80:83], v70 offset:3072
	v_add_u32_e32 v70, s81, v232
	ds_read_b128 v[84:87], v70
	ds_read_b128 v[88:91], v70 offset:1024
	ds_read_b128 v[92:95], v70 offset:2048
	ds_read_b128 v[152:155], v70 offset:3072
	v_lshl_add_u64 v[70:71], vcc, 0, v[204:205]
	s_add_i32 m0, s97, 0xc000
	ds_read_b128 v[164:167], v240
	ds_read_b128 v[168:171], v240 offset:1024
	ds_read_b128 v[172:175], v240 offset:2048
	ds_read_b128 v[176:179], v240 offset:3072
	ds_read_b128 v[180:183], v240 offset:4096
	ds_read_b128 v[184:187], v240 offset:5120
	ds_read_b128 v[188:191], v240 offset:6144
	ds_read_b128 v[208:211], v240 offset:7168
	global_load_lds_dwordx4 v[70:71], off
	v_lshl_add_u64 v[70:71], vcc, 0, v[206:207]
	s_add_i32 m0, s97, 0xe000
	s_nop 0
	global_load_lds_dwordx4 v[70:71], off
	s_waitcnt vmcnt(8)
	s_waitcnt lgkmcnt(0)
	s_setprio 0
	s_barrier
; #define PG8_STAGE(bufoff, gbase, voff) do { _Pragma("unroll") for (int _i = 0; _i < 2; ++_i) \
;         __builtin_amdgcn_global_load_lds((const unsigned*)((const char*)(gbase) + (voff)[_i]), (LAS unsigned*)(lds + (bufoff) + ldsw + _i * 8192), 16, 0, 0); } while (0)
; #define PG8_LDA(dst, b, h) do { _Pragma("unroll") for (int m = 0; m < 4; ++m) _Pragma("unroll") for (int k = 0; k < 2; ++k) dst[m][k] = *(const LAS bf16x8*)(lds + PG8_SA(b, h) + aoff + m * 2048 + k * 1024); } while (0)
; #define PG8_MMA(ai, bj, At, Bt) do { __builtin_amdgcn_s_setprio(1); _Pragma("unroll") for (int m = 0; m < 4; ++m) _Pragma("unroll") for (int n = 0; n < 2; ++n) _Pragma("unroll") for (int k = 0; k < 2; ++k) \
;         acc[ai][bj][m][n] = __builtin_amdgcn_mfma_f32_16x16x32_bf16(Bt[n][k], At[m][k], acc[ai][bj][m][n], 0, 0, 0); __builtin_amdgcn_s_setprio(0); } while (0)
; #define PG8_WAIT_V(n) asm volatile("s_waitcnt vmcnt(" #n ")" ::: "memory")
; #define PG8_WAIT_L(n) asm volatile("s_waitcnt lgkmcnt(" #n ")" ::: "memory")
; #define PG8_BAR __builtin_amdgcn_s_barrier()
; #define PG8_SCHED __builtin_amdgcn_sched_barrier(0)
; template <class Epi, class Sched>
; __device__ __forceinline__ void gemm_phase(LAS unsigned char* lds, const Gemm g, const Sched& S, const Epi& E, const int tid) {
;     ...
;             PG8_WAIT_V(8); PG8_WAIT_L(0); PG8_BAR; PG8_MMA(0, 0, At, B0); PG8_MMA(0, 1, At, B1); PG8_BAR; PG8_SCHED;
;             PG8_LDA(At, 0, 1); PG8_STAGE(PG8_SB(0, 0), b2, voffB); PG8_STAGE(PG8_SB(0, 1), b2 + hstep, voffB); PG8_STAGE(PG8_SA(0, 0), a2, voffA);
;             PG8_WAIT_V(8); PG8_WAIT_L(0); PG8_BAR; PG8_MMA(1, 0, At, B0); PG8_MMA(1, 1, At, B1); PG8_BAR; PG8_SCHED;
	s_waitcnt lgkmcnt(0)
	v_mfma_f32_16x16x32_bf16 v[160:163], v[58:61], v[164:167], v[160:163]
	v_mfma_f32_16x16x32_bf16 v[156:159], v[66:69], v[164:167], v[156:159]
	v_mfma_f32_16x16x32_bf16 v[136:139], v[66:69], v[172:175], v[136:139]
	v_mfma_f32_16x16x32_bf16 v[140:143], v[58:61], v[172:175], v[140:143]
	v_mfma_f32_16x16x32_bf16 v[124:127], v[58:61], v[180:183], v[124:127]
	v_mfma_f32_16x16x32_bf16 v[120:123], v[66:69], v[180:183], v[120:123]
	v_mfma_f32_16x16x32_bf16 v[104:107], v[66:69], v[188:191], v[104:107]
	v_mfma_f32_16x16x32_bf16 v[108:111], v[58:61], v[188:191], v[108:111]
	v_mfma_f32_16x16x32_bf16 v[160:163], v[62:65], v[168:171], v[160:163]
	v_mfma_f32_16x16x32_bf16 v[156:159], v[80:83], v[168:171], v[156:159]
	v_mfma_f32_16x16x32_bf16 v[136:139], v[80:83], v[176:179], v[136:139]
	v_mfma_f32_16x16x32_bf16 v[140:143], v[62:65], v[176:179], v[140:143]
	v_mfma_f32_16x16x32_bf16 v[124:127], v[62:65], v[184:187], v[124:127]
	v_mfma_f32_16x16x32_bf16 v[120:123], v[80:83], v[184:187], v[120:123]
	v_mfma_f32_16x16x32_bf16 v[104:107], v[80:83], v[208:211], v[104:107]
	v_mfma_f32_16x16x32_bf16 v[108:111], v[62:65], v[208:211], v[108:111]
	v_mfma_f32_16x16x32_bf16 v[148:151], v[84:87], v[164:167], v[148:151]
	v_mfma_f32_16x16x32_bf16 v[144:147], v[92:95], v[164:167], v[144:147]
	v_mfma_f32_16x16x32_bf16 v[128:131], v[92:95], v[172:175], v[128:131]
	v_mfma_f32_16x16x32_bf16 v[132:135], v[84:87], v[172:175], v[132:135]
	v_mfma_f32_16x16x32_bf16 v[116:119], v[84:87], v[180:183], v[116:119]
	v_mfma_f32_16x16x32_bf16 v[112:115], v[92:95], v[180:183], v[112:115]
	v_mfma_f32_16x16x32_bf16 v[96:99], v[92:95], v[188:191], v[96:99]
	v_mfma_f32_16x16x32_bf16 v[100:103], v[84:87], v[188:191], v[100:103]
	v_mfma_f32_16x16x32_bf16 v[148:151], v[88:91], v[168:171], v[148:151]
	v_mfma_f32_16x16x32_bf16 v[144:147], v[152:155], v[168:171], v[144:147]
	v_mfma_f32_16x16x32_bf16 v[128:131], v[152:155], v[176:179], v[128:131]
	v_mfma_f32_16x16x32_bf16 v[132:135], v[88:91], v[176:179], v[132:135]
	v_mfma_f32_16x16x32_bf16 v[116:119], v[88:91], v[184:187], v[116:119]
	v_mfma_f32_16x16x32_bf16 v[112:115], v[152:155], v[184:187], v[112:115]
	v_mfma_f32_16x16x32_bf16 v[96:99], v[152:155], v[208:211], v[96:99]
	v_mfma_f32_16x16x32_bf16 v[100:103], v[88:91], v[208:211], v[100:103]
	s_barrier
	s_setprio 1
	s_add_i32 s3, s3, s94
	v_lshl_add_u64 v[212:213], s[82:83], 0, v[192:193]
	s_mov_b32 m0, s3
	ds_read_b128 v[164:167], v240 offset:16384
	ds_read_b128 v[168:171], v240 offset:17408
	ds_read_b128 v[172:175], v240 offset:18432
	ds_read_b128 v[176:179], v240 offset:19456
	ds_read_b128 v[180:183], v240 offset:20480
	ds_read_b128 v[184:187], v240 offset:21504
	ds_read_b128 v[188:191], v240 offset:22528
	ds_read_b128 v[208:211], v240 offset:23552
	global_load_lds_dwordx4 v[212:213], off
	s_add_i32 m0, s3, 0x2000
	v_lshl_add_u64 v[214:215], s[82:83], 0, v[198:199]
	s_add_u32 s82, s82, s12
	s_addc_u32 s83, s83, 0
	s_add_i32 s3, s81, s94
	global_load_lds_dwordx4 v[214:215], off
	v_lshl_add_u64 v[216:217], s[82:83], 0, v[192:193]
	s_mov_b32 m0, s3
	v_lshl_add_u64 v[218:219], s[82:83], 0, v[198:199]
	global_load_lds_dwordx4 v[216:217], off
	s_add_i32 m0, s3, 0x2000
	v_lshl_add_u64 v[220:221], s[74:75], 0, v[202:203]
	global_load_lds_dwordx4 v[218:219], off
	s_mov_b32 m0, s97
	v_lshl_add_u64 v[224:225], s[74:75], 0, v[200:201]
	global_load_lds_dwordx4 v[220:221], off
	s_mov_b32 m0, s98
	s_nop 0
	global_load_lds_dwordx4 v[224:225], off
	s_waitcnt vmcnt(8)
	s_waitcnt lgkmcnt(0)
	s_setprio 0
	s_barrier
	s_waitcnt lgkmcnt(0)
	v_mfma_f32_16x16x32_bf16 v[76:79], v[58:61], v[164:167], v[76:79]
	v_mfma_f32_16x16x32_bf16 v[70:73], v[66:69], v[164:167], v[72:75]
	v_mfma_f32_16x16x32_bf16 v[40:43], v[66:69], v[172:175], v[40:43]
	v_mfma_f32_16x16x32_bf16 v[44:47], v[58:61], v[172:175], v[44:47]
	v_mfma_f32_16x16x32_bf16 v[28:31], v[58:61], v[180:183], v[28:31]
	v_mfma_f32_16x16x32_bf16 v[24:27], v[66:69], v[180:183], v[24:27]
	v_mfma_f32_16x16x32_bf16 v[8:11], v[66:69], v[188:191], v[8:11]
	v_mfma_f32_16x16x32_bf16 v[12:15], v[58:61], v[188:191], v[12:15]
	v_mfma_f32_16x16x32_bf16 v[76:79], v[62:65], v[168:171], v[76:79]
	v_mfma_f32_16x16x32_bf16 v[70:73], v[80:83], v[168:171], v[70:73]
	v_mfma_f32_16x16x32_bf16 v[40:43], v[80:83], v[176:179], v[40:43]
	v_mfma_f32_16x16x32_bf16 v[44:47], v[62:65], v[176:179], v[44:47]
	v_mfma_f32_16x16x32_bf16 v[28:31], v[62:65], v[184:187], v[28:31]
	v_mfma_f32_16x16x32_bf16 v[24:27], v[80:83], v[184:187], v[24:27]
	v_mfma_f32_16x16x32_bf16 v[8:11], v[80:83], v[208:211], v[8:11]
	v_mfma_f32_16x16x32_bf16 v[12:15], v[62:65], v[208:211], v[12:15]
	v_mfma_f32_16x16x32_bf16 v[52:55], v[84:87], v[164:167], v[52:55]
	v_mfma_f32_16x16x32_bf16 v[48:51], v[92:95], v[164:167], v[48:51]
	v_mfma_f32_16x16x32_bf16 v[32:35], v[92:95], v[172:175], v[32:35]
	v_mfma_f32_16x16x32_bf16 v[36:39], v[84:87], v[172:175], v[36:39]
	v_mfma_f32_16x16x32_bf16 v[20:23], v[84:87], v[180:183], v[20:23]
	v_mfma_f32_16x16x32_bf16 v[16:19], v[92:95], v[180:183], v[16:19]
	v_mfma_f32_16x16x32_bf16 v[0:3], v[92:95], v[188:191], v[0:3]
	v_mfma_f32_16x16x32_bf16 v[4:7], v[84:87], v[188:191], v[4:7]
	v_mfma_f32_16x16x32_bf16 v[52:55], v[88:91], v[168:171], v[52:55]
	v_mfma_f32_16x16x32_bf16 v[48:51], v[152:155], v[168:171], v[48:51]
	v_mfma_f32_16x16x32_bf16 v[32:35], v[152:155], v[176:179], v[32:35]
	v_mfma_f32_16x16x32_bf16 v[36:39], v[88:91], v[176:179], v[36:39]
	v_mfma_f32_16x16x32_bf16 v[20:23], v[88:91], v[184:187], v[20:23]
	v_mfma_f32_16x16x32_bf16 v[16:19], v[152:155], v[184:187], v[16:19]
	v_mfma_f32_16x16x32_bf16 v[0:3], v[152:155], v[208:211], v[0:3]
	v_mfma_f32_16x16x32_bf16 v[4:7], v[88:91], v[208:211], v[4:7]
	s_barrier
; #define PG8_STAGE(bufoff, gbase, voff) do { _Pragma("unroll") for (int _i = 0; _i < 2; ++_i) \
;         __builtin_amdgcn_global_load_lds((const unsigned*)((const char*)(gbase) + (voff)[_i]), (LAS unsigned*)(lds + (bufoff) + ldsw + _i * 8192), 16, 0, 0); } while (0)
; #define PG8_LDA(dst, b, h) do { _Pragma("unroll") for (int m = 0; m < 4; ++m) _Pragma("unroll") for (int k = 0; k < 2; ++k) dst[m][k] = *(const LAS bf16x8*)(lds + PG8_SA(b, h) + aoff + m * 2048 + k * 1024); } while (0)
; #define PG8_LDB(dst, b, h) do { _Pragma("unroll") for (int n = 0; n < 2; ++n) _Pragma("unroll") for (int k = 0; k < 2; ++k) dst[n][k] = *(const LAS bf16x8*)(lds + PG8_SB(b, h) + boff + n * 2048 + k * 1024); } while (0)
; #define PG8_WAIT_V(n) asm volatile("s_waitcnt vmcnt(" #n ")" ::: "memory")
; template <class Epi, class Sched>
; __device__ __forceinline__ void gemm_phase(LAS unsigned char* lds, const Gemm g, const Sched& S, const Epi& E, const int tid) {
;     ...
;         for (int t = 0; t < nt; t += 2) {
;             const bool last = (t == nt - 2);
;             const char* a1 = cA + (size_t)(t + 1) * kstep;
;             const char* a2 = last ? nA : cA + (size_t)(t + 2) * kstep; const char* b2 = last ? nB : cB + (size_t)(t + 2) * kstep;
;             const char* a3 = a2 + kstep; const char* b3 = b2 + kstep;
;             PG8_LDB(B0, 0, 0); PG8_LDB(B1, 0, 1); PG8_SCHED; PG8_LDA(At, 0, 0); PG8_STAGE(PG8_SA(1, 1), a1 + hstep, voffA);
;             PG8_WAIT_V(8); PG8_WAIT_L(0); PG8_BAR; PG8_MMA(0, 0, At, B0); PG8_MMA(0, 1, At, B1); PG8_BAR; PG8_SCHED;
;             PG8_LDA(At, 0, 1); PG8_STAGE(PG8_SB(0, 0), b2, voffB); PG8_STAGE(PG8_SB(0, 1), b2 + hstep, voffB); PG8_STAGE(PG8_SA(0, 0), a2, voffA);
;             PG8_WAIT_V(8); PG8_WAIT_L(0); PG8_BAR; PG8_MMA(1, 0, At, B0); PG8_MMA(1, 1, At, B1); PG8_BAR; PG8_SCHED;
;             PG8_LDB(B0, 1, 0); PG8_LDB(B1, 1, 1); PG8_SCHED; PG8_LDA(At, 1, 0); PG8_STAGE(PG8_SA(0, 1), a2 + hstep, voffA);
;             PG8_WAIT_V(8); PG8_WAIT_L(0); PG8_BAR; PG8_MMA(0, 0, At, B0); PG8_MMA(0, 1, At, B1); PG8_BAR; PG8_SCHED;
;             PG8_LDA(At, 1, 1); PG8_STAGE(PG8_SB(1, 0), b3, voffB); PG8_STAGE(PG8_SB(1, 1), b3 + hstep, voffB); PG8_STAGE(PG8_SA(1, 0), a3, voffA);
;             PG8_WAIT_V(8); PG8_WAIT_L(0); PG8_BAR; PG8_MMA(1, 0, At, B0); PG8_MMA(1, 1, At, B1); PG8_BAR; PG8_SCHED;
;         }
;         if (wr == 0) PG8_BAR;
	s_setprio 1
	s_add_i32 s3, 0, 0x18000
	v_add_u32_e32 v74, s3, v232
	s_add_i32 s81, 0, 0x1c000
	ds_read_b128 v[58:61], v74
	ds_read_b128 v[62:65], v74 offset:1024
	ds_read_b128 v[66:69], v74 offset:2048
	ds_read_b128 v[80:83], v74 offset:3072
	v_add_u32_e32 v74, s81, v232
	ds_read_b128 v[84:87], v74
	ds_read_b128 v[88:91], v74 offset:1024
	ds_read_b128 v[92:95], v74 offset:2048
	ds_read_b128 v[152:155], v74 offset:3072
	s_add_u32 s74, s74, s12
	s_addc_u32 s75, s75, 0
	s_mov_b32 m0, s99
	v_lshl_add_u64 v[74:75], s[74:75], 0, v[202:203]
	ds_read_b128 v[164:167], v240 offset:32768
	ds_read_b128 v[168:171], v240 offset:33792
	ds_read_b128 v[172:175], v240 offset:34816
	ds_read_b128 v[176:179], v240 offset:35840
	ds_read_b128 v[180:183], v240 offset:36864
	ds_read_b128 v[184:187], v240 offset:37888
	ds_read_b128 v[188:191], v240 offset:38912
	ds_read_b128 v[208:211], v240 offset:39936
	global_load_lds_dwordx4 v[74:75], off
	v_lshl_add_u64 v[74:75], s[74:75], 0, v[200:201]
	s_mov_b32 m0, s78
	s_nop 0
	global_load_lds_dwordx4 v[74:75], off
	s_waitcnt vmcnt(8)
	s_waitcnt lgkmcnt(0)
	s_setprio 0
	s_barrier
	s_waitcnt lgkmcnt(0)
	v_mfma_f32_16x16x32_bf16 v[160:163], v[58:61], v[164:167], v[160:163]
	v_mfma_f32_16x16x32_bf16 v[156:159], v[66:69], v[164:167], v[156:159]
	v_mfma_f32_16x16x32_bf16 v[136:139], v[66:69], v[172:175], v[136:139]
	v_mfma_f32_16x16x32_bf16 v[140:143], v[58:61], v[172:175], v[140:143]
	v_mfma_f32_16x16x32_bf16 v[124:127], v[58:61], v[180:183], v[124:127]
	v_mfma_f32_16x16x32_bf16 v[120:123], v[66:69], v[180:183], v[120:123]
	v_mfma_f32_16x16x32_bf16 v[104:107], v[66:69], v[188:191], v[104:107]
	v_mfma_f32_16x16x32_bf16 v[108:111], v[58:61], v[188:191], v[108:111]
	v_mfma_f32_16x16x32_bf16 v[160:163], v[62:65], v[168:171], v[160:163]
	v_mfma_f32_16x16x32_bf16 v[156:159], v[80:83], v[168:171], v[156:159]
	v_mfma_f32_16x16x32_bf16 v[136:139], v[80:83], v[176:179], v[136:139]
	v_mfma_f32_16x16x32_bf16 v[140:143], v[62:65], v[176:179], v[140:143]
	v_mfma_f32_16x16x32_bf16 v[124:127], v[62:65], v[184:187], v[124:127]
	v_mfma_f32_16x16x32_bf16 v[120:123], v[80:83], v[184:187], v[120:123]
	v_mfma_f32_16x16x32_bf16 v[104:107], v[80:83], v[208:211], v[104:107]
	v_mfma_f32_16x16x32_bf16 v[108:111], v[62:65], v[208:211], v[108:111]
	v_mfma_f32_16x16x32_bf16 v[148:151], v[84:87], v[164:167], v[148:151]
	v_mfma_f32_16x16x32_bf16 v[144:147], v[92:95], v[164:167], v[144:147]
	v_mfma_f32_16x16x32_bf16 v[128:131], v[92:95], v[172:175], v[128:131]
	v_mfma_f32_16x16x32_bf16 v[132:135], v[84:87], v[172:175], v[132:135]
	v_mfma_f32_16x16x32_bf16 v[116:119], v[84:87], v[180:183], v[116:119]
	v_mfma_f32_16x16x32_bf16 v[112:115], v[92:95], v[180:183], v[112:115]
	v_mfma_f32_16x16x32_bf16 v[96:99], v[92:95], v[188:191], v[96:99]
	v_mfma_f32_16x16x32_bf16 v[100:103], v[84:87], v[188:191], v[100:103]
	v_mfma_f32_16x16x32_bf16 v[148:151], v[88:91], v[168:171], v[148:151]
	v_mfma_f32_16x16x32_bf16 v[144:147], v[152:155], v[168:171], v[144:147]
	v_mfma_f32_16x16x32_bf16 v[128:131], v[152:155], v[176:179], v[128:131]
	v_mfma_f32_16x16x32_bf16 v[132:135], v[88:91], v[176:179], v[132:135]
	v_mfma_f32_16x16x32_bf16 v[116:119], v[88:91], v[184:187], v[116:119]
	v_mfma_f32_16x16x32_bf16 v[112:115], v[152:155], v[184:187], v[112:115]
	v_mfma_f32_16x16x32_bf16 v[96:99], v[152:155], v[208:211], v[96:99]
	v_mfma_f32_16x16x32_bf16 v[100:103], v[88:91], v[208:211], v[100:103]
	s_barrier
	s_setprio 1
	s_add_i32 s3, s3, s94
	v_lshl_add_u64 v[74:75], v[212:213], 0, s[68:69]
	s_mov_b32 m0, s3
	ds_read_b128 v[164:167], v240 offset:49152
	ds_read_b128 v[168:171], v240 offset:50176
	ds_read_b128 v[172:175], v240 offset:51200
	ds_read_b128 v[176:179], v240 offset:52224
	ds_read_b128 v[180:183], v240 offset:53248
	ds_read_b128 v[184:187], v240 offset:54272
	ds_read_b128 v[188:191], v240 offset:55296
	ds_read_b128 v[208:211], v240 offset:56320
	global_load_lds_dwordx4 v[74:75], off
	v_lshl_add_u64 v[74:75], v[214:215], 0, s[68:69]
	s_add_i32 m0, s3, 0x2000
	s_add_i32 s3, s81, s94
	global_load_lds_dwordx4 v[74:75], off
	v_lshl_add_u64 v[74:75], v[216:217], 0, s[68:69]
	s_mov_b32 m0, s3
	s_nop 0
	global_load_lds_dwordx4 v[74:75], off
	v_lshl_add_u64 v[74:75], v[218:219], 0, s[68:69]
	s_add_i32 m0, s3, 0x2000
	s_nop 0
	global_load_lds_dwordx4 v[74:75], off
	v_lshl_add_u64 v[74:75], v[220:221], 0, s[68:69]
	s_mov_b32 m0, s53
	s_nop 0
	global_load_lds_dwordx4 v[74:75], off
	v_lshl_add_u64 v[74:75], v[224:225], 0, s[68:69]
	s_mov_b32 m0, s56
	s_nop 0
	global_load_lds_dwordx4 v[74:75], off
	s_waitcnt vmcnt(8)
	s_waitcnt lgkmcnt(0)
	s_setprio 0
	s_barrier
	s_waitcnt lgkmcnt(0)
	v_mfma_f32_16x16x32_bf16 v[74:77], v[58:61], v[164:167], v[76:79]
	v_mfma_f32_16x16x32_bf16 v[70:73], v[66:69], v[164:167], v[70:73]
	v_mfma_f32_16x16x32_bf16 v[40:43], v[66:69], v[172:175], v[40:43]
	v_mfma_f32_16x16x32_bf16 v[44:47], v[58:61], v[172:175], v[44:47]
	v_mfma_f32_16x16x32_bf16 v[28:31], v[58:61], v[180:183], v[28:31]
	v_mfma_f32_16x16x32_bf16 v[24:27], v[66:69], v[180:183], v[24:27]
	v_mfma_f32_16x16x32_bf16 v[8:11], v[66:69], v[188:191], v[8:11]
	v_mfma_f32_16x16x32_bf16 v[12:15], v[58:61], v[188:191], v[12:15]
	v_mfma_f32_16x16x32_bf16 v[76:79], v[62:65], v[168:171], v[74:77]
	v_mfma_f32_16x16x32_bf16 v[72:75], v[80:83], v[168:171], v[70:73]
	v_mfma_f32_16x16x32_bf16 v[40:43], v[80:83], v[176:179], v[40:43]
	v_mfma_f32_16x16x32_bf16 v[44:47], v[62:65], v[176:179], v[44:47]
	v_mfma_f32_16x16x32_bf16 v[28:31], v[62:65], v[184:187], v[28:31]
	v_mfma_f32_16x16x32_bf16 v[24:27], v[80:83], v[184:187], v[24:27]
	v_mfma_f32_16x16x32_bf16 v[8:11], v[80:83], v[208:211], v[8:11]
	v_mfma_f32_16x16x32_bf16 v[12:15], v[62:65], v[208:211], v[12:15]
	v_mfma_f32_16x16x32_bf16 v[52:55], v[84:87], v[164:167], v[52:55]
	v_mfma_f32_16x16x32_bf16 v[48:51], v[92:95], v[164:167], v[48:51]
	v_mfma_f32_16x16x32_bf16 v[32:35], v[92:95], v[172:175], v[32:35]
	v_mfma_f32_16x16x32_bf16 v[36:39], v[84:87], v[172:175], v[36:39]
	v_mfma_f32_16x16x32_bf16 v[20:23], v[84:87], v[180:183], v[20:23]
	v_mfma_f32_16x16x32_bf16 v[16:19], v[92:95], v[180:183], v[16:19]
	v_mfma_f32_16x16x32_bf16 v[0:3], v[92:95], v[188:191], v[0:3]
	v_mfma_f32_16x16x32_bf16 v[4:7], v[84:87], v[188:191], v[4:7]
	v_mfma_f32_16x16x32_bf16 v[52:55], v[88:91], v[168:171], v[52:55]
	v_mfma_f32_16x16x32_bf16 v[48:51], v[152:155], v[168:171], v[48:51]
	v_mfma_f32_16x16x32_bf16 v[32:35], v[152:155], v[176:179], v[32:35]
	v_mfma_f32_16x16x32_bf16 v[36:39], v[88:91], v[176:179], v[36:39]
	v_mfma_f32_16x16x32_bf16 v[20:23], v[88:91], v[184:187], v[20:23]
	v_mfma_f32_16x16x32_bf16 v[16:19], v[152:155], v[184:187], v[16:19]
	v_mfma_f32_16x16x32_bf16 v[0:3], v[152:155], v[208:211], v[0:3]
	v_mfma_f32_16x16x32_bf16 v[4:7], v[88:91], v[208:211], v[4:7]
	s_barrier
	s_setprio 1
	s_add_u32 vcc_lo, vcc_lo, 0x100
	s_addc_u32 vcc_hi, vcc_hi, 0
	s_add_u32 s61, s61, 0x100
	s_addc_u32 s67, s67, 0
	s_cmp_ge_u32 s80, s52
	s_mov_b32 s74, s80
	s_cbranch_scc0 .LBB0_567
	s_and_b64 vcc, exec, s[64:65]
	s_cbranch_vccz .LBB0_570
	s_barrier
